# conv tile pair body rewritten by hand in P2 and P2b: taps and input rows stream in under the FMAs, 4-token LayerNorm/swish staged
# speedup vs baseline: 1.0058x; 1.0058x over previous
; template <int TT>
; __device__ __forceinline__ void conv_pair(const Params& p, unsigned char* lds, bool sample, int tile) {
;     int tid = threadIdx.x; asm volatile("" : "+v"(tid));
;     const int half = tid >> 8, cp = tid & 255, lane = tid & 63, wq = (tid >> 6) & 3;
;     unsigned char* ws = p.ws; const bf16_t* U = (const bf16_t*)(ws + WS_U); bf16_t* CAT = (bf16_t*)(ws + WS_CAT);
;     const int sq = sample ? tile : tile >> 7, t0 = sample ? 0 : (tile & 127) * 16;
;     const int row0 = sample ? MP + sq * DS : sq * SEQ + t0;
;     float* zb = (float*)lds + (size_t)half * (TT * MIXB);
;     const f32x4 g0 = *(const f32x4*)(p.in[I_CLG] + 8 * lane), g1 = *(const f32x4*)(p.in[I_CLG] + 8 * lane + 4), b0 = *(const f32x4*)(p.in[I_CLB] + 8 * lane), b1 = *(const f32x4*)(p.in[I_CLB] + 8 * lane + 4);
;     if (tile >= 0) {
;         f32x2v w[CW];
; #pragma unroll
;         for (int j = 0; j < CW; ++j) w[j] = *(const f32x2v*)(p.in[I_CDW] + j * MIXB + 2 * cp);
;         const f32x2v bias = *(const f32x2v*)(p.in[I_CDB] + 2 * cp);
;         f32x2v acc[TT];
; #pragma unroll
;         for (int t = 0; t < TT; ++t) acc[t] = bias;
; #pragma unroll
;         for (int r = 0; r < TT + CW - 1; ++r) {
;             f32x2v val;
;             if (sample && r < CW - 1) val = __builtin_nontemporal_load((const f32x2v*)(p.in[I_SC] + ((size_t)sq * (CW - 1) + r) * MIXB + 2 * cp));
;             else { const int i = t0 + r - (CW - 1); unsigned raw = 0u; if (sample || i >= 0) raw = *(const unsigned*)(U + (size_t)(sample ? row0 + r - (CW - 1) : sq * SEQ + i) * MIXB + 2 * cp);
;                 val[0] = __uint_as_float(raw << 16); val[1] = __uint_as_float(raw & 0xffff0000u); }
.LBB0_336:
	s_mov_b64 s[6:7], exec
	s_waitcnt vmcnt(4)
	v_readfirstlane_b32 s4, v89
	v_and_b32_e32 v151, 0xff, v176
	v_lshrrev_b32_e32 v152, 8, v176
	v_readlane_b32 s50, v247, 36
	v_readlane_b32 s51, v247, 37
	v_lshlrev_b32_e32 v150, 3, v151
	v_lshlrev_b32_e32 v151, 2, v151
	v_lshl_add_u32 v152, v152, 15, v150
	s_lshr_b32 s47, s4, 7
	s_and_b32 s46, s4, 0x7f
	s_lshl_b32 s60, s46, 4
	s_lshl_b32 s47, s47, 11
	s_add_u32 s47, s47, s60
	s_lshl_b32 s60, s47, 10
	s_add_u32 s50, s50, s60
	s_addc_u32 s51, s51, 0
	s_sub_u32 s50, s50, 0x7800
	s_subb_u32 s51, s51, 0
	s_cmp_ge_u32 s46, 2
	s_cselect_b32 s32, -1, 0
	s_cselect_b32 s60, 0, 0x7800
	s_cmp_ge_u32 s46, 1
	s_cselect_b32 s99, -1, 0
	s_cselect_b32 s61, 0, 0x4000
	s_mov_b64 s[54:55], s[72:73]
	s_add_u32 s50, s50, s60
	s_addc_u32 s51, s51, 0
	global_load_dwordx2 v[82:83], v150, s[74:75]
	global_load_dwordx2 v[0:1], v150, s[54:55]
	global_load_dwordx2 v[2:3], v150, s[54:55] offset:2048
	s_add_u32 s54, s54, 0x1000
	s_addc_u32 s55, s55, 0
	global_load_dwordx2 v[4:5], v150, s[54:55]
	global_load_dwordx2 v[6:7], v150, s[54:55] offset:2048
	s_add_u32 s54, s54, 0x1000
	s_addc_u32 s55, s55, 0
	global_load_dwordx2 v[8:9], v150, s[54:55]
	global_load_dwordx2 v[10:11], v150, s[54:55] offset:2048
	s_add_u32 s54, s54, 0x1000
	s_addc_u32 s55, s55, 0
	global_load_dwordx2 v[12:13], v150, s[54:55]
	global_load_dwordx2 v[14:15], v150, s[54:55] offset:2048
	s_add_u32 s54, s54, 0x1000
	s_addc_u32 s55, s55, 0
	global_load_dwordx2 v[18:19], v150, s[54:55]
	global_load_dwordx2 v[20:21], v150, s[54:55] offset:2048
	s_add_u32 s54, s54, 0x1000
	s_addc_u32 s55, s55, 0
	global_load_dwordx2 v[22:23], v150, s[54:55]
	global_load_dwordx2 v[24:25], v150, s[54:55] offset:2048
	s_add_u32 s54, s54, 0x1000
	s_addc_u32 s55, s55, 0
	global_load_dwordx2 v[26:27], v150, s[54:55]
	global_load_dwordx2 v[28:29], v150, s[54:55] offset:2048
	s_add_u32 s54, s54, 0x1000
	s_addc_u32 s55, s55, 0
	global_load_dwordx2 v[30:31], v150, s[54:55]
	global_load_dwordx2 v[32:33], v150, s[54:55] offset:2048
	s_add_u32 s54, s54, 0x1000
	s_addc_u32 s55, s55, 0
	global_load_dwordx2 v[34:35], v150, s[54:55]
	global_load_dwordx2 v[50:51], v150, s[54:55] offset:2048
	s_add_u32 s54, s54, 0x1000
	s_addc_u32 s55, s55, 0
	global_load_dwordx2 v[56:57], v150, s[54:55]
	global_load_dwordx2 v[58:59], v150, s[54:55] offset:2048
	s_add_u32 s54, s54, 0x1000
	s_addc_u32 s55, s55, 0
	global_load_dwordx2 v[60:61], v150, s[54:55]
	global_load_dwordx2 v[62:63], v150, s[54:55] offset:2048
	s_add_u32 s54, s54, 0x1000
	s_addc_u32 s55, s55, 0
	global_load_dwordx2 v[64:65], v150, s[54:55]
	global_load_dwordx2 v[66:67], v150, s[54:55] offset:2048
	s_add_u32 s54, s54, 0x1000
	s_addc_u32 s55, s55, 0
	global_load_dwordx2 v[68:69], v150, s[54:55]
	global_load_dwordx2 v[70:71], v150, s[54:55] offset:2048
	s_add_u32 s54, s54, 0x1000
	s_addc_u32 s55, s55, 0
	global_load_dwordx2 v[72:73], v150, s[54:55]
	global_load_dwordx2 v[74:75], v150, s[54:55] offset:2048
	s_add_u32 s54, s54, 0x1000
	s_addc_u32 s55, s55, 0
	global_load_dwordx2 v[76:77], v150, s[54:55]
	global_load_dwordx2 v[78:79], v150, s[54:55] offset:2048
	s_add_u32 s54, s54, 0x1000
	s_addc_u32 s55, s55, 0
	global_load_dwordx2 v[80:81], v150, s[54:55]
	global_load_dword v16, v151, s[50:51]
	global_load_dword v97, v151, s[50:51] offset:1024
	global_load_dword v126, v151, s[50:51] offset:2048
	global_load_dword v127, v151, s[50:51] offset:3072
	s_add_u32 s50, s50, 0x1000
	s_addc_u32 s51, s51, 0
	global_load_dword v128, v151, s[50:51]
	global_load_dword v129, v151, s[50:51] offset:1024
	global_load_dword v130, v151, s[50:51] offset:2048
	global_load_dword v131, v151, s[50:51] offset:3072
	s_add_u32 s50, s50, 0x1000
	s_addc_u32 s51, s51, 0
	global_load_dword v132, v151, s[50:51]
	global_load_dword v133, v151, s[50:51] offset:1024
	global_load_dword v134, v151, s[50:51] offset:2048
	global_load_dword v135, v151, s[50:51] offset:3072
	s_add_u32 s50, s50, 0x1000
	s_addc_u32 s51, s51, 0
	global_load_dword v136, v151, s[50:51]
	global_load_dword v137, v151, s[50:51] offset:1024
	s_sub_u32 s50, s50, s60
	s_subb_u32 s51, s51, 0
	s_add_u32 s50, s50, s61
	s_addc_u32 s51, s51, 0
	global_load_dword v138, v151, s[50:51] offset:2048
	global_load_dword v139, v151, s[50:51] offset:3072
	s_add_u32 s50, s50, 0x1000
	s_addc_u32 s51, s51, 0
	global_load_dword v140, v151, s[50:51]
	global_load_dword v141, v151, s[50:51] offset:1024
	global_load_dword v142, v151, s[50:51] offset:2048
	global_load_dword v143, v151, s[50:51] offset:3072
	s_add_u32 s50, s50, 0x1000
	s_addc_u32 s51, s51, 0
	global_load_dword v144, v151, s[50:51]
	global_load_dword v145, v151, s[50:51] offset:1024
	global_load_dword v146, v151, s[50:51] offset:2048
	global_load_dword v147, v151, s[50:51] offset:3072
	s_add_u32 s50, s50, 0x1000
	s_addc_u32 s51, s51, 0
	global_load_dword v148, v151, s[50:51]
	global_load_dword v149, v151, s[50:51] offset:1024
	s_waitcnt vmcnt(25)
	v_and_b32_e32 v16, s32, v16
	v_lshlrev_b32_e32 v122, 16, v16
	v_and_b32_e32 v123, 0xffff0000, v16
	v_pk_fma_f32 v[84:85], v[0:1], v[122:123], v[82:83]
	global_load_dword v16, v151, s[50:51] offset:2048
	s_waitcnt vmcnt(25)
	v_and_b32_e32 v97, s32, v97
	v_lshlrev_b32_e32 v124, 16, v97
	v_and_b32_e32 v125, 0xffff0000, v97
	v_pk_fma_f32 v[84:85], v[2:3], v[124:125], v[84:85]
	v_pk_fma_f32 v[86:87], v[0:1], v[124:125], v[82:83]
	global_load_dword v97, v151, s[50:51] offset:3072
	s_waitcnt vmcnt(25)
	v_and_b32_e32 v126, s32, v126
	v_lshlrev_b32_e32 v122, 16, v126
	v_and_b32_e32 v123, 0xffff0000, v126
	v_pk_fma_f32 v[84:85], v[4:5], v[122:123], v[84:85]
	v_pk_fma_f32 v[86:87], v[2:3], v[122:123], v[86:87]
	v_pk_fma_f32 v[92:93], v[0:1], v[122:123], v[82:83]
	s_add_u32 s50, s50, 0x1000
	s_addc_u32 s51, s51, 0
	global_load_dword v126, v151, s[50:51]
	s_waitcnt vmcnt(25)
; template <int TT>
; __device__ __forceinline__ void conv_pair(const Params& p, unsigned char* lds, bool sample, int tile) {
;     ...
;         for (int r = 0; r < TT + CW - 1; ++r) {
;             f32x2v val;
;             if (sample && r < CW - 1) val = __builtin_nontemporal_load((const f32x2v*)(p.in[I_SC] + ((size_t)sq * (CW - 1) + r) * MIXB + 2 * cp));
;             else { const int i = t0 + r - (CW - 1); unsigned raw = 0u; if (sample || i >= 0) raw = *(const unsigned*)(U + (size_t)(sample ? row0 + r - (CW - 1) : sq * SEQ + i) * MIXB + 2 * cp);
;                 val[0] = __uint_as_float(raw << 16); val[1] = __uint_as_float(raw & 0xffff0000u); }
; #pragma unroll
;             for (int t = 0; t < TT; ++t) { const int j = r - t; if (j >= 0 && j < CW) acc[t] += w[j] * val; }
	v_and_b32_e32 v127, s32, v127
	v_lshlrev_b32_e32 v124, 16, v127
	v_and_b32_e32 v125, 0xffff0000, v127
	v_pk_fma_f32 v[84:85], v[6:7], v[124:125], v[84:85]
	v_pk_fma_f32 v[86:87], v[4:5], v[124:125], v[86:87]
	v_pk_fma_f32 v[92:93], v[2:3], v[124:125], v[92:93]
	v_pk_fma_f32 v[94:95], v[0:1], v[124:125], v[82:83]
	global_load_dword v127, v151, s[50:51] offset:1024
	s_waitcnt vmcnt(25)
	v_and_b32_e32 v128, s32, v128
	v_lshlrev_b32_e32 v122, 16, v128
	v_and_b32_e32 v123, 0xffff0000, v128
	v_pk_fma_f32 v[84:85], v[8:9], v[122:123], v[84:85]
	v_pk_fma_f32 v[86:87], v[6:7], v[122:123], v[86:87]
	v_pk_fma_f32 v[92:93], v[4:5], v[122:123], v[92:93]
	v_pk_fma_f32 v[94:95], v[2:3], v[122:123], v[94:95]
	v_pk_fma_f32 v[98:99], v[0:1], v[122:123], v[82:83]
	s_sub_u32 s50, s50, s61
	s_subb_u32 s51, s51, 0
	global_load_dword v128, v151, s[50:51] offset:2048
	s_waitcnt vmcnt(25)
	v_and_b32_e32 v129, s32, v129
	v_lshlrev_b32_e32 v124, 16, v129
	v_and_b32_e32 v125, 0xffff0000, v129
	v_pk_fma_f32 v[84:85], v[10:11], v[124:125], v[84:85]
	v_pk_fma_f32 v[86:87], v[8:9], v[124:125], v[86:87]
	v_pk_fma_f32 v[92:93], v[6:7], v[124:125], v[92:93]
	v_pk_fma_f32 v[94:95], v[4:5], v[124:125], v[94:95]
	v_pk_fma_f32 v[98:99], v[2:3], v[124:125], v[98:99]
	v_pk_fma_f32 v[100:101], v[0:1], v[124:125], v[82:83]
	global_load_dword v129, v151, s[50:51] offset:3072
	s_waitcnt vmcnt(25)
	v_and_b32_e32 v130, s32, v130
	v_lshlrev_b32_e32 v122, 16, v130
	v_and_b32_e32 v123, 0xffff0000, v130
	v_pk_fma_f32 v[84:85], v[12:13], v[122:123], v[84:85]
	v_pk_fma_f32 v[86:87], v[10:11], v[122:123], v[86:87]
	v_pk_fma_f32 v[92:93], v[8:9], v[122:123], v[92:93]
	v_pk_fma_f32 v[94:95], v[6:7], v[122:123], v[94:95]
	v_pk_fma_f32 v[98:99], v[4:5], v[122:123], v[98:99]
	v_pk_fma_f32 v[100:101], v[2:3], v[122:123], v[100:101]
	v_pk_fma_f32 v[102:103], v[0:1], v[122:123], v[82:83]
	s_add_u32 s50, s50, 0x1000
	s_addc_u32 s51, s51, 0
	global_load_dword v130, v151, s[50:51]
	s_waitcnt vmcnt(25)
	v_and_b32_e32 v131, s32, v131
	v_lshlrev_b32_e32 v124, 16, v131
	v_and_b32_e32 v125, 0xffff0000, v131
	v_pk_fma_f32 v[84:85], v[14:15], v[124:125], v[84:85]
	v_pk_fma_f32 v[86:87], v[12:13], v[124:125], v[86:87]
	v_pk_fma_f32 v[92:93], v[10:11], v[124:125], v[92:93]
	v_pk_fma_f32 v[94:95], v[8:9], v[124:125], v[94:95]
	v_pk_fma_f32 v[98:99], v[6:7], v[124:125], v[98:99]
	v_pk_fma_f32 v[100:101], v[4:5], v[124:125], v[100:101]
	v_pk_fma_f32 v[102:103], v[2:3], v[124:125], v[102:103]
	v_pk_fma_f32 v[104:105], v[0:1], v[124:125], v[82:83]
	global_load_dword v131, v151, s[50:51] offset:1024
	s_waitcnt vmcnt(25)
	v_and_b32_e32 v132, s32, v132
	v_lshlrev_b32_e32 v122, 16, v132
	v_and_b32_e32 v123, 0xffff0000, v132
	v_pk_fma_f32 v[84:85], v[18:19], v[122:123], v[84:85]
	v_pk_fma_f32 v[86:87], v[14:15], v[122:123], v[86:87]
	v_pk_fma_f32 v[92:93], v[12:13], v[122:123], v[92:93]
	v_pk_fma_f32 v[94:95], v[10:11], v[122:123], v[94:95]
	v_pk_fma_f32 v[98:99], v[8:9], v[122:123], v[98:99]
	v_pk_fma_f32 v[100:101], v[6:7], v[122:123], v[100:101]
	v_pk_fma_f32 v[102:103], v[4:5], v[122:123], v[102:103]
	v_pk_fma_f32 v[104:105], v[2:3], v[122:123], v[104:105]
	v_pk_fma_f32 v[106:107], v[0:1], v[122:123], v[82:83]
	global_load_dword v132, v151, s[50:51] offset:2048
	s_waitcnt vmcnt(25)
	v_and_b32_e32 v133, s32, v133
	v_lshlrev_b32_e32 v124, 16, v133
	v_and_b32_e32 v125, 0xffff0000, v133
	v_pk_fma_f32 v[84:85], v[20:21], v[124:125], v[84:85]
	v_pk_fma_f32 v[86:87], v[18:19], v[124:125], v[86:87]
	v_pk_fma_f32 v[92:93], v[14:15], v[124:125], v[92:93]
	v_pk_fma_f32 v[94:95], v[12:13], v[124:125], v[94:95]
	v_pk_fma_f32 v[98:99], v[10:11], v[124:125], v[98:99]
	v_pk_fma_f32 v[100:101], v[8:9], v[124:125], v[100:101]
	v_pk_fma_f32 v[102:103], v[6:7], v[124:125], v[102:103]
	v_pk_fma_f32 v[104:105], v[4:5], v[124:125], v[104:105]
	v_pk_fma_f32 v[106:107], v[2:3], v[124:125], v[106:107]
	v_pk_fma_f32 v[108:109], v[0:1], v[124:125], v[82:83]
	global_load_dword v133, v151, s[50:51] offset:3072
	s_waitcnt vmcnt(25)
	v_and_b32_e32 v134, s32, v134
	v_lshlrev_b32_e32 v122, 16, v134
	v_and_b32_e32 v123, 0xffff0000, v134
	v_pk_fma_f32 v[84:85], v[22:23], v[122:123], v[84:85]
	v_pk_fma_f32 v[86:87], v[20:21], v[122:123], v[86:87]
	v_pk_fma_f32 v[92:93], v[18:19], v[122:123], v[92:93]
	v_pk_fma_f32 v[94:95], v[14:15], v[122:123], v[94:95]
	v_pk_fma_f32 v[98:99], v[12:13], v[122:123], v[98:99]
	v_pk_fma_f32 v[100:101], v[10:11], v[122:123], v[100:101]
	v_pk_fma_f32 v[102:103], v[8:9], v[122:123], v[102:103]
	v_pk_fma_f32 v[104:105], v[6:7], v[122:123], v[104:105]
	v_pk_fma_f32 v[106:107], v[4:5], v[122:123], v[106:107]
	v_pk_fma_f32 v[108:109], v[2:3], v[122:123], v[108:109]
	v_pk_fma_f32 v[110:111], v[0:1], v[122:123], v[82:83]
	s_add_u32 s50, s50, 0x1000
	s_addc_u32 s51, s51, 0
	global_load_dword v134, v151, s[50:51]
	s_waitcnt vmcnt(25)
	v_and_b32_e32 v135, s32, v135
	v_lshlrev_b32_e32 v124, 16, v135
	v_and_b32_e32 v125, 0xffff0000, v135
	v_pk_fma_f32 v[84:85], v[24:25], v[124:125], v[84:85]
	v_pk_fma_f32 v[86:87], v[22:23], v[124:125], v[86:87]
	v_pk_fma_f32 v[92:93], v[20:21], v[124:125], v[92:93]
	v_pk_fma_f32 v[94:95], v[18:19], v[124:125], v[94:95]
	v_pk_fma_f32 v[98:99], v[14:15], v[124:125], v[98:99]
	v_pk_fma_f32 v[100:101], v[12:13], v[124:125], v[100:101]
	v_pk_fma_f32 v[102:103], v[10:11], v[124:125], v[102:103]
	v_pk_fma_f32 v[104:105], v[8:9], v[124:125], v[104:105]
	v_pk_fma_f32 v[106:107], v[6:7], v[124:125], v[106:107]
	v_pk_fma_f32 v[108:109], v[4:5], v[124:125], v[108:109]
	v_pk_fma_f32 v[110:111], v[2:3], v[124:125], v[110:111]
	v_pk_fma_f32 v[112:113], v[0:1], v[124:125], v[82:83]
	global_load_dword v135, v151, s[50:51] offset:1024
	s_waitcnt vmcnt(25)
; template <int TT>
; __device__ __forceinline__ void conv_pair(const Params& p, unsigned char* lds, bool sample, int tile) {
;     ...
;         for (int r = 0; r < TT + CW - 1; ++r) {
;             f32x2v val;
;             if (sample && r < CW - 1) val = __builtin_nontemporal_load((const f32x2v*)(p.in[I_SC] + ((size_t)sq * (CW - 1) + r) * MIXB + 2 * cp));
;             else { const int i = t0 + r - (CW - 1); unsigned raw = 0u; if (sample || i >= 0) raw = *(const unsigned*)(U + (size_t)(sample ? row0 + r - (CW - 1) : sq * SEQ + i) * MIXB + 2 * cp);
;                 val[0] = __uint_as_float(raw << 16); val[1] = __uint_as_float(raw & 0xffff0000u); }
; #pragma unroll
;             for (int t = 0; t < TT; ++t) { const int j = r - t; if (j >= 0 && j < CW) acc[t] += w[j] * val; }
	v_and_b32_e32 v136, s32, v136
	v_lshlrev_b32_e32 v122, 16, v136
	v_and_b32_e32 v123, 0xffff0000, v136
	v_pk_fma_f32 v[84:85], v[26:27], v[122:123], v[84:85]
	v_pk_fma_f32 v[86:87], v[24:25], v[122:123], v[86:87]
	v_pk_fma_f32 v[92:93], v[22:23], v[122:123], v[92:93]
	v_pk_fma_f32 v[94:95], v[20:21], v[122:123], v[94:95]
	v_pk_fma_f32 v[98:99], v[18:19], v[122:123], v[98:99]
	v_pk_fma_f32 v[100:101], v[14:15], v[122:123], v[100:101]
	v_pk_fma_f32 v[102:103], v[12:13], v[122:123], v[102:103]
	v_pk_fma_f32 v[104:105], v[10:11], v[122:123], v[104:105]
	v_pk_fma_f32 v[106:107], v[8:9], v[122:123], v[106:107]
	v_pk_fma_f32 v[108:109], v[6:7], v[122:123], v[108:109]
	v_pk_fma_f32 v[110:111], v[4:5], v[122:123], v[110:111]
	v_pk_fma_f32 v[112:113], v[2:3], v[122:123], v[112:113]
	v_pk_fma_f32 v[114:115], v[0:1], v[122:123], v[82:83]
	global_load_dword v136, v151, s[50:51] offset:2048
	s_waitcnt vmcnt(25)
	v_and_b32_e32 v137, s32, v137
	v_lshlrev_b32_e32 v124, 16, v137
	v_and_b32_e32 v125, 0xffff0000, v137
	v_pk_fma_f32 v[84:85], v[28:29], v[124:125], v[84:85]
	v_pk_fma_f32 v[86:87], v[26:27], v[124:125], v[86:87]
	v_pk_fma_f32 v[92:93], v[24:25], v[124:125], v[92:93]
	v_pk_fma_f32 v[94:95], v[22:23], v[124:125], v[94:95]
	v_pk_fma_f32 v[98:99], v[20:21], v[124:125], v[98:99]
	v_pk_fma_f32 v[100:101], v[18:19], v[124:125], v[100:101]
	v_pk_fma_f32 v[102:103], v[14:15], v[124:125], v[102:103]
	v_pk_fma_f32 v[104:105], v[12:13], v[124:125], v[104:105]
	v_pk_fma_f32 v[106:107], v[10:11], v[124:125], v[106:107]
	v_pk_fma_f32 v[108:109], v[8:9], v[124:125], v[108:109]
	v_pk_fma_f32 v[110:111], v[6:7], v[124:125], v[110:111]
	v_pk_fma_f32 v[112:113], v[4:5], v[124:125], v[112:113]
	v_pk_fma_f32 v[114:115], v[2:3], v[124:125], v[114:115]
	v_pk_fma_f32 v[116:117], v[0:1], v[124:125], v[82:83]
	global_load_dword v137, v151, s[50:51] offset:3072
	s_waitcnt vmcnt(25)
	v_and_b32_e32 v138, s99, v138
	v_lshlrev_b32_e32 v122, 16, v138
	v_and_b32_e32 v123, 0xffff0000, v138
	v_pk_fma_f32 v[84:85], v[30:31], v[122:123], v[84:85]
	v_pk_fma_f32 v[86:87], v[28:29], v[122:123], v[86:87]
	v_pk_fma_f32 v[92:93], v[26:27], v[122:123], v[92:93]
	v_pk_fma_f32 v[94:95], v[24:25], v[122:123], v[94:95]
	v_pk_fma_f32 v[98:99], v[22:23], v[122:123], v[98:99]
	v_pk_fma_f32 v[100:101], v[20:21], v[122:123], v[100:101]
	v_pk_fma_f32 v[102:103], v[18:19], v[122:123], v[102:103]
	v_pk_fma_f32 v[104:105], v[14:15], v[122:123], v[104:105]
	v_pk_fma_f32 v[106:107], v[12:13], v[122:123], v[106:107]
	v_pk_fma_f32 v[108:109], v[10:11], v[122:123], v[108:109]
	v_pk_fma_f32 v[110:111], v[8:9], v[122:123], v[110:111]
	v_pk_fma_f32 v[112:113], v[6:7], v[122:123], v[112:113]
	v_pk_fma_f32 v[114:115], v[4:5], v[122:123], v[114:115]
	v_pk_fma_f32 v[116:117], v[2:3], v[122:123], v[116:117]
	v_pk_fma_f32 v[118:119], v[0:1], v[122:123], v[82:83]
	s_add_u32 s50, s50, 0x1000
	s_addc_u32 s51, s51, 0
	global_load_dword v138, v151, s[50:51]
	s_waitcnt vmcnt(25)
	v_and_b32_e32 v139, s99, v139
	v_lshlrev_b32_e32 v124, 16, v139
	v_and_b32_e32 v125, 0xffff0000, v139
	v_pk_fma_f32 v[84:85], v[32:33], v[124:125], v[84:85]
	v_pk_fma_f32 v[86:87], v[30:31], v[124:125], v[86:87]
	v_pk_fma_f32 v[92:93], v[28:29], v[124:125], v[92:93]
	v_pk_fma_f32 v[94:95], v[26:27], v[124:125], v[94:95]
	v_pk_fma_f32 v[98:99], v[24:25], v[124:125], v[98:99]
	v_pk_fma_f32 v[100:101], v[22:23], v[124:125], v[100:101]
	v_pk_fma_f32 v[102:103], v[20:21], v[124:125], v[102:103]
	v_pk_fma_f32 v[104:105], v[18:19], v[124:125], v[104:105]
	v_pk_fma_f32 v[106:107], v[14:15], v[124:125], v[106:107]
	v_pk_fma_f32 v[108:109], v[12:13], v[124:125], v[108:109]
	v_pk_fma_f32 v[110:111], v[10:11], v[124:125], v[110:111]
	v_pk_fma_f32 v[112:113], v[8:9], v[124:125], v[112:113]
	v_pk_fma_f32 v[114:115], v[6:7], v[124:125], v[114:115]
	v_pk_fma_f32 v[116:117], v[4:5], v[124:125], v[116:117]
	v_pk_fma_f32 v[118:119], v[2:3], v[124:125], v[118:119]
	v_pk_fma_f32 v[120:121], v[0:1], v[124:125], v[82:83]
	global_load_dword v139, v151, s[50:51] offset:1024
	s_waitcnt vmcnt(25)
	v_and_b32_e32 v140, s99, v140
	v_lshlrev_b32_e32 v122, 16, v140
	v_and_b32_e32 v123, 0xffff0000, v140
	v_pk_fma_f32 v[84:85], v[34:35], v[122:123], v[84:85]
	v_pk_fma_f32 v[86:87], v[32:33], v[122:123], v[86:87]
	v_pk_fma_f32 v[92:93], v[30:31], v[122:123], v[92:93]
	v_pk_fma_f32 v[94:95], v[28:29], v[122:123], v[94:95]
	v_pk_fma_f32 v[98:99], v[26:27], v[122:123], v[98:99]
	v_pk_fma_f32 v[100:101], v[24:25], v[122:123], v[100:101]
	v_pk_fma_f32 v[102:103], v[22:23], v[122:123], v[102:103]
	v_pk_fma_f32 v[104:105], v[20:21], v[122:123], v[104:105]
	v_pk_fma_f32 v[106:107], v[18:19], v[122:123], v[106:107]
	v_pk_fma_f32 v[108:109], v[14:15], v[122:123], v[108:109]
	v_pk_fma_f32 v[110:111], v[12:13], v[122:123], v[110:111]
	v_pk_fma_f32 v[112:113], v[10:11], v[122:123], v[112:113]
	v_pk_fma_f32 v[114:115], v[8:9], v[122:123], v[114:115]
	v_pk_fma_f32 v[116:117], v[6:7], v[122:123], v[116:117]
	v_pk_fma_f32 v[118:119], v[4:5], v[122:123], v[118:119]
	v_pk_fma_f32 v[120:121], v[2:3], v[122:123], v[120:121]
	global_load_dword v140, v151, s[50:51] offset:2048
	s_waitcnt vmcnt(25)
; template <int TT>
; __device__ __forceinline__ void conv_pair(const Params& p, unsigned char* lds, bool sample, int tile) {
;     ...
;         for (int r = 0; r < TT + CW - 1; ++r) {
;             f32x2v val;
;             if (sample && r < CW - 1) val = __builtin_nontemporal_load((const f32x2v*)(p.in[I_SC] + ((size_t)sq * (CW - 1) + r) * MIXB + 2 * cp));
;             else { const int i = t0 + r - (CW - 1); unsigned raw = 0u; if (sample || i >= 0) raw = *(const unsigned*)(U + (size_t)(sample ? row0 + r - (CW - 1) : sq * SEQ + i) * MIXB + 2 * cp);
;                 val[0] = __uint_as_float(raw << 16); val[1] = __uint_as_float(raw & 0xffff0000u); }
; #pragma unroll
;             for (int t = 0; t < TT; ++t) { const int j = r - t; if (j >= 0 && j < CW) acc[t] += w[j] * val; }
	v_and_b32_e32 v141, s99, v141
	v_lshlrev_b32_e32 v124, 16, v141
	v_and_b32_e32 v125, 0xffff0000, v141
	v_pk_fma_f32 v[84:85], v[50:51], v[124:125], v[84:85]
	v_pk_fma_f32 v[86:87], v[34:35], v[124:125], v[86:87]
	v_pk_fma_f32 v[92:93], v[32:33], v[124:125], v[92:93]
	v_pk_fma_f32 v[94:95], v[30:31], v[124:125], v[94:95]
	v_pk_fma_f32 v[98:99], v[28:29], v[124:125], v[98:99]
	v_pk_fma_f32 v[100:101], v[26:27], v[124:125], v[100:101]
	v_pk_fma_f32 v[102:103], v[24:25], v[124:125], v[102:103]
	v_pk_fma_f32 v[104:105], v[22:23], v[124:125], v[104:105]
	v_pk_fma_f32 v[106:107], v[20:21], v[124:125], v[106:107]
	v_pk_fma_f32 v[108:109], v[18:19], v[124:125], v[108:109]
	v_pk_fma_f32 v[110:111], v[14:15], v[124:125], v[110:111]
	v_pk_fma_f32 v[112:113], v[12:13], v[124:125], v[112:113]
	v_pk_fma_f32 v[114:115], v[10:11], v[124:125], v[114:115]
	v_pk_fma_f32 v[116:117], v[8:9], v[124:125], v[116:117]
	v_pk_fma_f32 v[118:119], v[6:7], v[124:125], v[118:119]
	v_pk_fma_f32 v[120:121], v[4:5], v[124:125], v[120:121]
	global_load_dword v141, v151, s[50:51] offset:3072
	s_waitcnt vmcnt(25)
	v_and_b32_e32 v142, s99, v142
	v_lshlrev_b32_e32 v122, 16, v142
	v_and_b32_e32 v123, 0xffff0000, v142
	v_pk_fma_f32 v[84:85], v[56:57], v[122:123], v[84:85]
	v_pk_fma_f32 v[86:87], v[50:51], v[122:123], v[86:87]
	v_pk_fma_f32 v[92:93], v[34:35], v[122:123], v[92:93]
	v_pk_fma_f32 v[94:95], v[32:33], v[122:123], v[94:95]
	v_pk_fma_f32 v[98:99], v[30:31], v[122:123], v[98:99]
	v_pk_fma_f32 v[100:101], v[28:29], v[122:123], v[100:101]
	v_pk_fma_f32 v[102:103], v[26:27], v[122:123], v[102:103]
	v_pk_fma_f32 v[104:105], v[24:25], v[122:123], v[104:105]
	v_pk_fma_f32 v[106:107], v[22:23], v[122:123], v[106:107]
	v_pk_fma_f32 v[108:109], v[20:21], v[122:123], v[108:109]
	v_pk_fma_f32 v[110:111], v[18:19], v[122:123], v[110:111]
	v_pk_fma_f32 v[112:113], v[14:15], v[122:123], v[112:113]
	v_pk_fma_f32 v[114:115], v[12:13], v[122:123], v[114:115]
	v_pk_fma_f32 v[116:117], v[10:11], v[122:123], v[116:117]
	v_pk_fma_f32 v[118:119], v[8:9], v[122:123], v[118:119]
	v_pk_fma_f32 v[120:121], v[6:7], v[122:123], v[120:121]
	s_add_u32 s50, s50, 0x1000
	s_addc_u32 s51, s51, 0
	global_load_dword v142, v151, s[50:51]
	s_waitcnt vmcnt(25)
	v_and_b32_e32 v143, s99, v143
	v_lshlrev_b32_e32 v124, 16, v143
	v_and_b32_e32 v125, 0xffff0000, v143
	v_pk_fma_f32 v[84:85], v[58:59], v[124:125], v[84:85]
	v_pk_fma_f32 v[86:87], v[56:57], v[124:125], v[86:87]
	v_pk_fma_f32 v[92:93], v[50:51], v[124:125], v[92:93]
	v_pk_fma_f32 v[94:95], v[34:35], v[124:125], v[94:95]
	v_pk_fma_f32 v[98:99], v[32:33], v[124:125], v[98:99]
	v_pk_fma_f32 v[100:101], v[30:31], v[124:125], v[100:101]
	v_pk_fma_f32 v[102:103], v[28:29], v[124:125], v[102:103]
	v_pk_fma_f32 v[104:105], v[26:27], v[124:125], v[104:105]
	v_pk_fma_f32 v[106:107], v[24:25], v[124:125], v[106:107]
	v_pk_fma_f32 v[108:109], v[22:23], v[124:125], v[108:109]
	v_pk_fma_f32 v[110:111], v[20:21], v[124:125], v[110:111]
	v_pk_fma_f32 v[112:113], v[18:19], v[124:125], v[112:113]
	v_pk_fma_f32 v[114:115], v[14:15], v[124:125], v[114:115]
	v_pk_fma_f32 v[116:117], v[12:13], v[124:125], v[116:117]
	v_pk_fma_f32 v[118:119], v[10:11], v[124:125], v[118:119]
	v_pk_fma_f32 v[120:121], v[8:9], v[124:125], v[120:121]
	global_load_dword v143, v151, s[50:51] offset:1024
	s_waitcnt vmcnt(25)
	v_and_b32_e32 v144, s99, v144
	v_lshlrev_b32_e32 v122, 16, v144
	v_and_b32_e32 v123, 0xffff0000, v144
	v_pk_fma_f32 v[84:85], v[60:61], v[122:123], v[84:85]
	v_pk_fma_f32 v[86:87], v[58:59], v[122:123], v[86:87]
	v_pk_fma_f32 v[92:93], v[56:57], v[122:123], v[92:93]
	v_pk_fma_f32 v[94:95], v[50:51], v[122:123], v[94:95]
	v_pk_fma_f32 v[98:99], v[34:35], v[122:123], v[98:99]
	v_pk_fma_f32 v[100:101], v[32:33], v[122:123], v[100:101]
	v_pk_fma_f32 v[102:103], v[30:31], v[122:123], v[102:103]
	v_pk_fma_f32 v[104:105], v[28:29], v[122:123], v[104:105]
	v_pk_fma_f32 v[106:107], v[26:27], v[122:123], v[106:107]
	v_pk_fma_f32 v[108:109], v[24:25], v[122:123], v[108:109]
	v_pk_fma_f32 v[110:111], v[22:23], v[122:123], v[110:111]
	v_pk_fma_f32 v[112:113], v[20:21], v[122:123], v[112:113]
	v_pk_fma_f32 v[114:115], v[18:19], v[122:123], v[114:115]
	v_pk_fma_f32 v[116:117], v[14:15], v[122:123], v[116:117]
	v_pk_fma_f32 v[118:119], v[12:13], v[122:123], v[118:119]
	v_pk_fma_f32 v[120:121], v[10:11], v[122:123], v[120:121]
	s_waitcnt vmcnt(24)
	v_and_b32_e32 v145, s99, v145
	v_lshlrev_b32_e32 v124, 16, v145
	v_and_b32_e32 v125, 0xffff0000, v145
	v_pk_fma_f32 v[84:85], v[62:63], v[124:125], v[84:85]
	v_pk_fma_f32 v[86:87], v[60:61], v[124:125], v[86:87]
	v_pk_fma_f32 v[92:93], v[58:59], v[124:125], v[92:93]
	v_pk_fma_f32 v[94:95], v[56:57], v[124:125], v[94:95]
	v_pk_fma_f32 v[98:99], v[50:51], v[124:125], v[98:99]
	v_pk_fma_f32 v[100:101], v[34:35], v[124:125], v[100:101]
	v_pk_fma_f32 v[102:103], v[32:33], v[124:125], v[102:103]
	v_pk_fma_f32 v[104:105], v[30:31], v[124:125], v[104:105]
	v_pk_fma_f32 v[106:107], v[28:29], v[124:125], v[106:107]
	v_pk_fma_f32 v[108:109], v[26:27], v[124:125], v[108:109]
	v_pk_fma_f32 v[110:111], v[24:25], v[124:125], v[110:111]
	v_pk_fma_f32 v[112:113], v[22:23], v[124:125], v[112:113]
	v_pk_fma_f32 v[114:115], v[20:21], v[124:125], v[114:115]
	v_pk_fma_f32 v[116:117], v[18:19], v[124:125], v[116:117]
	v_pk_fma_f32 v[118:119], v[14:15], v[124:125], v[118:119]
	v_pk_fma_f32 v[120:121], v[12:13], v[124:125], v[120:121]
	s_waitcnt vmcnt(23)
; template <int TT>
; __device__ __forceinline__ void conv_pair(const Params& p, unsigned char* lds, bool sample, int tile) {
;     ...
;         for (int r = 0; r < TT + CW - 1; ++r) {
;             f32x2v val;
;             if (sample && r < CW - 1) val = __builtin_nontemporal_load((const f32x2v*)(p.in[I_SC] + ((size_t)sq * (CW - 1) + r) * MIXB + 2 * cp));
;             else { const int i = t0 + r - (CW - 1); unsigned raw = 0u; if (sample || i >= 0) raw = *(const unsigned*)(U + (size_t)(sample ? row0 + r - (CW - 1) : sq * SEQ + i) * MIXB + 2 * cp);
;                 val[0] = __uint_as_float(raw << 16); val[1] = __uint_as_float(raw & 0xffff0000u); }
; #pragma unroll
;             for (int t = 0; t < TT; ++t) { const int j = r - t; if (j >= 0 && j < CW) acc[t] += w[j] * val; }
	v_and_b32_e32 v146, s99, v146
	v_lshlrev_b32_e32 v122, 16, v146
	v_and_b32_e32 v123, 0xffff0000, v146
	v_pk_fma_f32 v[84:85], v[64:65], v[122:123], v[84:85]
	v_pk_fma_f32 v[86:87], v[62:63], v[122:123], v[86:87]
	v_pk_fma_f32 v[92:93], v[60:61], v[122:123], v[92:93]
	v_pk_fma_f32 v[94:95], v[58:59], v[122:123], v[94:95]
	v_pk_fma_f32 v[98:99], v[56:57], v[122:123], v[98:99]
	v_pk_fma_f32 v[100:101], v[50:51], v[122:123], v[100:101]
	v_pk_fma_f32 v[102:103], v[34:35], v[122:123], v[102:103]
	v_pk_fma_f32 v[104:105], v[32:33], v[122:123], v[104:105]
	v_pk_fma_f32 v[106:107], v[30:31], v[122:123], v[106:107]
	v_pk_fma_f32 v[108:109], v[28:29], v[122:123], v[108:109]
	v_pk_fma_f32 v[110:111], v[26:27], v[122:123], v[110:111]
	v_pk_fma_f32 v[112:113], v[24:25], v[122:123], v[112:113]
	v_pk_fma_f32 v[114:115], v[22:23], v[122:123], v[114:115]
	v_pk_fma_f32 v[116:117], v[20:21], v[122:123], v[116:117]
	v_pk_fma_f32 v[118:119], v[18:19], v[122:123], v[118:119]
	v_pk_fma_f32 v[120:121], v[14:15], v[122:123], v[120:121]
	s_waitcnt vmcnt(22)
	v_and_b32_e32 v147, s99, v147
	v_lshlrev_b32_e32 v124, 16, v147
	v_and_b32_e32 v125, 0xffff0000, v147
	v_pk_fma_f32 v[84:85], v[66:67], v[124:125], v[84:85]
	v_pk_fma_f32 v[86:87], v[64:65], v[124:125], v[86:87]
	v_pk_fma_f32 v[92:93], v[62:63], v[124:125], v[92:93]
	v_pk_fma_f32 v[94:95], v[60:61], v[124:125], v[94:95]
	v_pk_fma_f32 v[98:99], v[58:59], v[124:125], v[98:99]
	v_pk_fma_f32 v[100:101], v[56:57], v[124:125], v[100:101]
	v_pk_fma_f32 v[102:103], v[50:51], v[124:125], v[102:103]
	v_pk_fma_f32 v[104:105], v[34:35], v[124:125], v[104:105]
	v_pk_fma_f32 v[106:107], v[32:33], v[124:125], v[106:107]
	v_pk_fma_f32 v[108:109], v[30:31], v[124:125], v[108:109]
	v_pk_fma_f32 v[110:111], v[28:29], v[124:125], v[110:111]
	v_pk_fma_f32 v[112:113], v[26:27], v[124:125], v[112:113]
	v_pk_fma_f32 v[114:115], v[24:25], v[124:125], v[114:115]
	v_pk_fma_f32 v[116:117], v[22:23], v[124:125], v[116:117]
	v_pk_fma_f32 v[118:119], v[20:21], v[124:125], v[118:119]
	v_pk_fma_f32 v[120:121], v[18:19], v[124:125], v[120:121]
	s_waitcnt vmcnt(21)
	v_and_b32_e32 v148, s99, v148
	v_lshlrev_b32_e32 v122, 16, v148
	v_and_b32_e32 v123, 0xffff0000, v148
	v_pk_fma_f32 v[84:85], v[68:69], v[122:123], v[84:85]
	v_pk_fma_f32 v[86:87], v[66:67], v[122:123], v[86:87]
	v_pk_fma_f32 v[92:93], v[64:65], v[122:123], v[92:93]
	v_pk_fma_f32 v[94:95], v[62:63], v[122:123], v[94:95]
	v_pk_fma_f32 v[98:99], v[60:61], v[122:123], v[98:99]
	v_pk_fma_f32 v[100:101], v[58:59], v[122:123], v[100:101]
	v_pk_fma_f32 v[102:103], v[56:57], v[122:123], v[102:103]
	v_pk_fma_f32 v[104:105], v[50:51], v[122:123], v[104:105]
	v_pk_fma_f32 v[106:107], v[34:35], v[122:123], v[106:107]
	v_pk_fma_f32 v[108:109], v[32:33], v[122:123], v[108:109]
	v_pk_fma_f32 v[110:111], v[30:31], v[122:123], v[110:111]
	v_pk_fma_f32 v[112:113], v[28:29], v[122:123], v[112:113]
	v_pk_fma_f32 v[114:115], v[26:27], v[122:123], v[114:115]
	v_pk_fma_f32 v[116:117], v[24:25], v[122:123], v[116:117]
	v_pk_fma_f32 v[118:119], v[22:23], v[122:123], v[118:119]
	v_pk_fma_f32 v[120:121], v[20:21], v[122:123], v[120:121]
	s_waitcnt vmcnt(20)
	v_and_b32_e32 v149, s99, v149
	v_lshlrev_b32_e32 v124, 16, v149
	v_and_b32_e32 v125, 0xffff0000, v149
	v_pk_fma_f32 v[84:85], v[70:71], v[124:125], v[84:85]
	v_pk_fma_f32 v[86:87], v[68:69], v[124:125], v[86:87]
	v_pk_fma_f32 v[92:93], v[66:67], v[124:125], v[92:93]
	v_pk_fma_f32 v[94:95], v[64:65], v[124:125], v[94:95]
	v_pk_fma_f32 v[98:99], v[62:63], v[124:125], v[98:99]
	v_pk_fma_f32 v[100:101], v[60:61], v[124:125], v[100:101]
	v_pk_fma_f32 v[102:103], v[58:59], v[124:125], v[102:103]
	v_pk_fma_f32 v[104:105], v[56:57], v[124:125], v[104:105]
	v_pk_fma_f32 v[106:107], v[50:51], v[124:125], v[106:107]
	v_pk_fma_f32 v[108:109], v[34:35], v[124:125], v[108:109]
	v_pk_fma_f32 v[110:111], v[32:33], v[124:125], v[110:111]
	v_pk_fma_f32 v[112:113], v[30:31], v[124:125], v[112:113]
	v_pk_fma_f32 v[114:115], v[28:29], v[124:125], v[114:115]
	v_pk_fma_f32 v[116:117], v[26:27], v[124:125], v[116:117]
	v_pk_fma_f32 v[118:119], v[24:25], v[124:125], v[118:119]
	v_pk_fma_f32 v[120:121], v[22:23], v[124:125], v[120:121]
	s_waitcnt vmcnt(19)
	v_and_b32_e32 v16, s99, v16
	v_lshlrev_b32_e32 v122, 16, v16
	v_and_b32_e32 v123, 0xffff0000, v16
	v_pk_fma_f32 v[84:85], v[72:73], v[122:123], v[84:85]
	v_pk_fma_f32 v[86:87], v[70:71], v[122:123], v[86:87]
	v_pk_fma_f32 v[92:93], v[68:69], v[122:123], v[92:93]
	v_pk_fma_f32 v[94:95], v[66:67], v[122:123], v[94:95]
	v_pk_fma_f32 v[98:99], v[64:65], v[122:123], v[98:99]
	v_pk_fma_f32 v[100:101], v[62:63], v[122:123], v[100:101]
	v_pk_fma_f32 v[102:103], v[60:61], v[122:123], v[102:103]
	v_pk_fma_f32 v[104:105], v[58:59], v[122:123], v[104:105]
	v_pk_fma_f32 v[106:107], v[56:57], v[122:123], v[106:107]
	v_pk_fma_f32 v[108:109], v[50:51], v[122:123], v[108:109]
	v_pk_fma_f32 v[110:111], v[34:35], v[122:123], v[110:111]
	v_pk_fma_f32 v[112:113], v[32:33], v[122:123], v[112:113]
	v_pk_fma_f32 v[114:115], v[30:31], v[122:123], v[114:115]
	v_pk_fma_f32 v[116:117], v[28:29], v[122:123], v[116:117]
	v_pk_fma_f32 v[118:119], v[26:27], v[122:123], v[118:119]
	v_pk_fma_f32 v[120:121], v[24:25], v[122:123], v[120:121]
	s_waitcnt vmcnt(18)
; template <int TT>
; __device__ __forceinline__ void conv_pair(const Params& p, unsigned char* lds, bool sample, int tile) {
;     ...
;         for (int r = 0; r < TT + CW - 1; ++r) {
;             f32x2v val;
;             if (sample && r < CW - 1) val = __builtin_nontemporal_load((const f32x2v*)(p.in[I_SC] + ((size_t)sq * (CW - 1) + r) * MIXB + 2 * cp));
;             else { const int i = t0 + r - (CW - 1); unsigned raw = 0u; if (sample || i >= 0) raw = *(const unsigned*)(U + (size_t)(sample ? row0 + r - (CW - 1) : sq * SEQ + i) * MIXB + 2 * cp);
;                 val[0] = __uint_as_float(raw << 16); val[1] = __uint_as_float(raw & 0xffff0000u); }
; #pragma unroll
;             for (int t = 0; t < TT; ++t) { const int j = r - t; if (j >= 0 && j < CW) acc[t] += w[j] * val; }
	v_and_b32_e32 v97, s99, v97
	v_lshlrev_b32_e32 v124, 16, v97
	v_and_b32_e32 v125, 0xffff0000, v97
	v_pk_fma_f32 v[84:85], v[74:75], v[124:125], v[84:85]
	v_pk_fma_f32 v[86:87], v[72:73], v[124:125], v[86:87]
	v_pk_fma_f32 v[92:93], v[70:71], v[124:125], v[92:93]
	v_pk_fma_f32 v[94:95], v[68:69], v[124:125], v[94:95]
	v_pk_fma_f32 v[98:99], v[66:67], v[124:125], v[98:99]
	v_pk_fma_f32 v[100:101], v[64:65], v[124:125], v[100:101]
	v_pk_fma_f32 v[102:103], v[62:63], v[124:125], v[102:103]
	v_pk_fma_f32 v[104:105], v[60:61], v[124:125], v[104:105]
	v_pk_fma_f32 v[106:107], v[58:59], v[124:125], v[106:107]
	v_pk_fma_f32 v[108:109], v[56:57], v[124:125], v[108:109]
	v_pk_fma_f32 v[110:111], v[50:51], v[124:125], v[110:111]
	v_pk_fma_f32 v[112:113], v[34:35], v[124:125], v[112:113]
	v_pk_fma_f32 v[114:115], v[32:33], v[124:125], v[114:115]
	v_pk_fma_f32 v[116:117], v[30:31], v[124:125], v[116:117]
	v_pk_fma_f32 v[118:119], v[28:29], v[124:125], v[118:119]
	v_pk_fma_f32 v[120:121], v[26:27], v[124:125], v[120:121]
	s_waitcnt vmcnt(17)
	v_and_b32_e32 v126, s99, v126
	v_lshlrev_b32_e32 v122, 16, v126
	v_and_b32_e32 v123, 0xffff0000, v126
	v_pk_fma_f32 v[84:85], v[76:77], v[122:123], v[84:85]
	v_pk_fma_f32 v[86:87], v[74:75], v[122:123], v[86:87]
	v_pk_fma_f32 v[92:93], v[72:73], v[122:123], v[92:93]
	v_pk_fma_f32 v[94:95], v[70:71], v[122:123], v[94:95]
	v_pk_fma_f32 v[98:99], v[68:69], v[122:123], v[98:99]
	v_pk_fma_f32 v[100:101], v[66:67], v[122:123], v[100:101]
	v_pk_fma_f32 v[102:103], v[64:65], v[122:123], v[102:103]
	v_pk_fma_f32 v[104:105], v[62:63], v[122:123], v[104:105]
	v_pk_fma_f32 v[106:107], v[60:61], v[122:123], v[106:107]
	v_pk_fma_f32 v[108:109], v[58:59], v[122:123], v[108:109]
	v_pk_fma_f32 v[110:111], v[56:57], v[122:123], v[110:111]
	v_pk_fma_f32 v[112:113], v[50:51], v[122:123], v[112:113]
	v_pk_fma_f32 v[114:115], v[34:35], v[122:123], v[114:115]
	v_pk_fma_f32 v[116:117], v[32:33], v[122:123], v[116:117]
	v_pk_fma_f32 v[118:119], v[30:31], v[122:123], v[118:119]
	v_pk_fma_f32 v[120:121], v[28:29], v[122:123], v[120:121]
	s_waitcnt vmcnt(16)
	v_and_b32_e32 v127, s99, v127
	v_lshlrev_b32_e32 v124, 16, v127
	v_and_b32_e32 v125, 0xffff0000, v127
	v_pk_fma_f32 v[84:85], v[78:79], v[124:125], v[84:85]
	v_pk_fma_f32 v[86:87], v[76:77], v[124:125], v[86:87]
	v_pk_fma_f32 v[92:93], v[74:75], v[124:125], v[92:93]
	v_pk_fma_f32 v[94:95], v[72:73], v[124:125], v[94:95]
	v_pk_fma_f32 v[98:99], v[70:71], v[124:125], v[98:99]
	v_pk_fma_f32 v[100:101], v[68:69], v[124:125], v[100:101]
	v_pk_fma_f32 v[102:103], v[66:67], v[124:125], v[102:103]
	v_pk_fma_f32 v[104:105], v[64:65], v[124:125], v[104:105]
	v_pk_fma_f32 v[106:107], v[62:63], v[124:125], v[106:107]
	v_pk_fma_f32 v[108:109], v[60:61], v[124:125], v[108:109]
	v_pk_fma_f32 v[110:111], v[58:59], v[124:125], v[110:111]
	v_pk_fma_f32 v[112:113], v[56:57], v[124:125], v[112:113]
	v_pk_fma_f32 v[114:115], v[50:51], v[124:125], v[114:115]
	v_pk_fma_f32 v[116:117], v[34:35], v[124:125], v[116:117]
	v_pk_fma_f32 v[118:119], v[32:33], v[124:125], v[118:119]
	v_pk_fma_f32 v[120:121], v[30:31], v[124:125], v[120:121]
	s_waitcnt vmcnt(15)
	v_lshlrev_b32_e32 v122, 16, v128
	v_and_b32_e32 v123, 0xffff0000, v128
	v_pk_fma_f32 v[84:85], v[80:81], v[122:123], v[84:85]
	v_pk_fma_f32 v[86:87], v[78:79], v[122:123], v[86:87]
	v_pk_fma_f32 v[92:93], v[76:77], v[122:123], v[92:93]
	v_pk_fma_f32 v[94:95], v[74:75], v[122:123], v[94:95]
	v_pk_fma_f32 v[98:99], v[72:73], v[122:123], v[98:99]
	v_pk_fma_f32 v[100:101], v[70:71], v[122:123], v[100:101]
	v_pk_fma_f32 v[102:103], v[68:69], v[122:123], v[102:103]
	v_pk_fma_f32 v[104:105], v[66:67], v[122:123], v[104:105]
	v_pk_fma_f32 v[106:107], v[64:65], v[122:123], v[106:107]
	v_pk_fma_f32 v[108:109], v[62:63], v[122:123], v[108:109]
	v_pk_fma_f32 v[110:111], v[60:61], v[122:123], v[110:111]
	v_pk_fma_f32 v[112:113], v[58:59], v[122:123], v[112:113]
	v_pk_fma_f32 v[114:115], v[56:57], v[122:123], v[114:115]
	v_pk_fma_f32 v[116:117], v[50:51], v[122:123], v[116:117]
	v_pk_fma_f32 v[118:119], v[34:35], v[122:123], v[118:119]
	v_pk_fma_f32 v[120:121], v[32:33], v[122:123], v[120:121]
	s_waitcnt vmcnt(14)
	v_lshlrev_b32_e32 v124, 16, v129
	v_and_b32_e32 v125, 0xffff0000, v129
	v_pk_fma_f32 v[86:87], v[80:81], v[124:125], v[86:87]
	v_pk_fma_f32 v[92:93], v[78:79], v[124:125], v[92:93]
	v_pk_fma_f32 v[94:95], v[76:77], v[124:125], v[94:95]
	v_pk_fma_f32 v[98:99], v[74:75], v[124:125], v[98:99]
	v_pk_fma_f32 v[100:101], v[72:73], v[124:125], v[100:101]
	v_pk_fma_f32 v[102:103], v[70:71], v[124:125], v[102:103]
	v_pk_fma_f32 v[104:105], v[68:69], v[124:125], v[104:105]
	v_pk_fma_f32 v[106:107], v[66:67], v[124:125], v[106:107]
	v_pk_fma_f32 v[108:109], v[64:65], v[124:125], v[108:109]
	v_pk_fma_f32 v[110:111], v[62:63], v[124:125], v[110:111]
	v_pk_fma_f32 v[112:113], v[60:61], v[124:125], v[112:113]
	v_pk_fma_f32 v[114:115], v[58:59], v[124:125], v[114:115]
	v_pk_fma_f32 v[116:117], v[56:57], v[124:125], v[116:117]
	v_pk_fma_f32 v[118:119], v[50:51], v[124:125], v[118:119]
	v_pk_fma_f32 v[120:121], v[34:35], v[124:125], v[120:121]
	s_waitcnt vmcnt(13)
	v_lshlrev_b32_e32 v122, 16, v130
	v_and_b32_e32 v123, 0xffff0000, v130
	v_pk_fma_f32 v[92:93], v[80:81], v[122:123], v[92:93]
	v_pk_fma_f32 v[94:95], v[78:79], v[122:123], v[94:95]
	v_pk_fma_f32 v[98:99], v[76:77], v[122:123], v[98:99]
	v_pk_fma_f32 v[100:101], v[74:75], v[122:123], v[100:101]
	v_pk_fma_f32 v[102:103], v[72:73], v[122:123], v[102:103]
	v_pk_fma_f32 v[104:105], v[70:71], v[122:123], v[104:105]
	v_pk_fma_f32 v[106:107], v[68:69], v[122:123], v[106:107]
	v_pk_fma_f32 v[108:109], v[66:67], v[122:123], v[108:109]
	v_pk_fma_f32 v[110:111], v[64:65], v[122:123], v[110:111]
	v_pk_fma_f32 v[112:113], v[62:63], v[122:123], v[112:113]
	v_pk_fma_f32 v[114:115], v[60:61], v[122:123], v[114:115]
	v_pk_fma_f32 v[116:117], v[58:59], v[122:123], v[116:117]
	v_pk_fma_f32 v[118:119], v[56:57], v[122:123], v[118:119]
	v_pk_fma_f32 v[120:121], v[50:51], v[122:123], v[120:121]
	s_waitcnt vmcnt(12)
; template <int TT>
; __device__ __forceinline__ void conv_pair(const Params& p, unsigned char* lds, bool sample, int tile) {
;     ...
;         for (int r = 0; r < TT + CW - 1; ++r) {
;             f32x2v val;
;             if (sample && r < CW - 1) val = __builtin_nontemporal_load((const f32x2v*)(p.in[I_SC] + ((size_t)sq * (CW - 1) + r) * MIXB + 2 * cp));
;             else { const int i = t0 + r - (CW - 1); unsigned raw = 0u; if (sample || i >= 0) raw = *(const unsigned*)(U + (size_t)(sample ? row0 + r - (CW - 1) : sq * SEQ + i) * MIXB + 2 * cp);
;                 val[0] = __uint_as_float(raw << 16); val[1] = __uint_as_float(raw & 0xffff0000u); }
; #pragma unroll
;             for (int t = 0; t < TT; ++t) { const int j = r - t; if (j >= 0 && j < CW) acc[t] += w[j] * val; }
	v_lshlrev_b32_e32 v124, 16, v131
	v_and_b32_e32 v125, 0xffff0000, v131
	v_pk_fma_f32 v[94:95], v[80:81], v[124:125], v[94:95]
	v_pk_fma_f32 v[98:99], v[78:79], v[124:125], v[98:99]
	v_pk_fma_f32 v[100:101], v[76:77], v[124:125], v[100:101]
	v_pk_fma_f32 v[102:103], v[74:75], v[124:125], v[102:103]
	v_pk_fma_f32 v[104:105], v[72:73], v[124:125], v[104:105]
	v_pk_fma_f32 v[106:107], v[70:71], v[124:125], v[106:107]
	v_pk_fma_f32 v[108:109], v[68:69], v[124:125], v[108:109]
	v_pk_fma_f32 v[110:111], v[66:67], v[124:125], v[110:111]
	v_pk_fma_f32 v[112:113], v[64:65], v[124:125], v[112:113]
	v_pk_fma_f32 v[114:115], v[62:63], v[124:125], v[114:115]
	v_pk_fma_f32 v[116:117], v[60:61], v[124:125], v[116:117]
	v_pk_fma_f32 v[118:119], v[58:59], v[124:125], v[118:119]
	v_pk_fma_f32 v[120:121], v[56:57], v[124:125], v[120:121]
	s_waitcnt vmcnt(11)
	v_lshlrev_b32_e32 v122, 16, v132
	v_and_b32_e32 v123, 0xffff0000, v132
	v_pk_fma_f32 v[98:99], v[80:81], v[122:123], v[98:99]
	v_pk_fma_f32 v[100:101], v[78:79], v[122:123], v[100:101]
	v_pk_fma_f32 v[102:103], v[76:77], v[122:123], v[102:103]
	v_pk_fma_f32 v[104:105], v[74:75], v[122:123], v[104:105]
	v_pk_fma_f32 v[106:107], v[72:73], v[122:123], v[106:107]
	v_pk_fma_f32 v[108:109], v[70:71], v[122:123], v[108:109]
	v_pk_fma_f32 v[110:111], v[68:69], v[122:123], v[110:111]
	v_pk_fma_f32 v[112:113], v[66:67], v[122:123], v[112:113]
	v_pk_fma_f32 v[114:115], v[64:65], v[122:123], v[114:115]
	v_pk_fma_f32 v[116:117], v[62:63], v[122:123], v[116:117]
	v_pk_fma_f32 v[118:119], v[60:61], v[122:123], v[118:119]
	v_pk_fma_f32 v[120:121], v[58:59], v[122:123], v[120:121]
	s_waitcnt vmcnt(10)
	v_lshlrev_b32_e32 v124, 16, v133
	v_and_b32_e32 v125, 0xffff0000, v133
	v_pk_fma_f32 v[100:101], v[80:81], v[124:125], v[100:101]
	v_pk_fma_f32 v[102:103], v[78:79], v[124:125], v[102:103]
	v_pk_fma_f32 v[104:105], v[76:77], v[124:125], v[104:105]
	v_pk_fma_f32 v[106:107], v[74:75], v[124:125], v[106:107]
	v_pk_fma_f32 v[108:109], v[72:73], v[124:125], v[108:109]
	v_pk_fma_f32 v[110:111], v[70:71], v[124:125], v[110:111]
	v_pk_fma_f32 v[112:113], v[68:69], v[124:125], v[112:113]
	v_pk_fma_f32 v[114:115], v[66:67], v[124:125], v[114:115]
	v_pk_fma_f32 v[116:117], v[64:65], v[124:125], v[116:117]
	v_pk_fma_f32 v[118:119], v[62:63], v[124:125], v[118:119]
	v_pk_fma_f32 v[120:121], v[60:61], v[124:125], v[120:121]
	s_waitcnt vmcnt(9)
	v_lshlrev_b32_e32 v122, 16, v134
	v_and_b32_e32 v123, 0xffff0000, v134
	v_pk_fma_f32 v[102:103], v[80:81], v[122:123], v[102:103]
	v_pk_fma_f32 v[104:105], v[78:79], v[122:123], v[104:105]
	v_pk_fma_f32 v[106:107], v[76:77], v[122:123], v[106:107]
	v_pk_fma_f32 v[108:109], v[74:75], v[122:123], v[108:109]
	v_pk_fma_f32 v[110:111], v[72:73], v[122:123], v[110:111]
	v_pk_fma_f32 v[112:113], v[70:71], v[122:123], v[112:113]
	v_pk_fma_f32 v[114:115], v[68:69], v[122:123], v[114:115]
	v_pk_fma_f32 v[116:117], v[66:67], v[122:123], v[116:117]
	v_pk_fma_f32 v[118:119], v[64:65], v[122:123], v[118:119]
	v_pk_fma_f32 v[120:121], v[62:63], v[122:123], v[120:121]
	s_waitcnt vmcnt(8)
	v_lshlrev_b32_e32 v124, 16, v135
	v_and_b32_e32 v125, 0xffff0000, v135
	v_pk_fma_f32 v[104:105], v[80:81], v[124:125], v[104:105]
	v_pk_fma_f32 v[106:107], v[78:79], v[124:125], v[106:107]
	v_pk_fma_f32 v[108:109], v[76:77], v[124:125], v[108:109]
	v_pk_fma_f32 v[110:111], v[74:75], v[124:125], v[110:111]
	v_pk_fma_f32 v[112:113], v[72:73], v[124:125], v[112:113]
	v_pk_fma_f32 v[114:115], v[70:71], v[124:125], v[114:115]
	v_pk_fma_f32 v[116:117], v[68:69], v[124:125], v[116:117]
	v_pk_fma_f32 v[118:119], v[66:67], v[124:125], v[118:119]
	v_pk_fma_f32 v[120:121], v[64:65], v[124:125], v[120:121]
	s_waitcnt vmcnt(7)
	v_lshlrev_b32_e32 v122, 16, v136
	v_and_b32_e32 v123, 0xffff0000, v136
	v_pk_fma_f32 v[106:107], v[80:81], v[122:123], v[106:107]
	v_pk_fma_f32 v[108:109], v[78:79], v[122:123], v[108:109]
	v_pk_fma_f32 v[110:111], v[76:77], v[122:123], v[110:111]
	v_pk_fma_f32 v[112:113], v[74:75], v[122:123], v[112:113]
	v_pk_fma_f32 v[114:115], v[72:73], v[122:123], v[114:115]
	v_pk_fma_f32 v[116:117], v[70:71], v[122:123], v[116:117]
	v_pk_fma_f32 v[118:119], v[68:69], v[122:123], v[118:119]
	v_pk_fma_f32 v[120:121], v[66:67], v[122:123], v[120:121]
	s_waitcnt vmcnt(6)
	v_lshlrev_b32_e32 v124, 16, v137
	v_and_b32_e32 v125, 0xffff0000, v137
	v_pk_fma_f32 v[108:109], v[80:81], v[124:125], v[108:109]
	v_pk_fma_f32 v[110:111], v[78:79], v[124:125], v[110:111]
	v_pk_fma_f32 v[112:113], v[76:77], v[124:125], v[112:113]
	v_pk_fma_f32 v[114:115], v[74:75], v[124:125], v[114:115]
	v_pk_fma_f32 v[116:117], v[72:73], v[124:125], v[116:117]
	v_pk_fma_f32 v[118:119], v[70:71], v[124:125], v[118:119]
	v_pk_fma_f32 v[120:121], v[68:69], v[124:125], v[120:121]
	s_waitcnt vmcnt(5)
	v_lshlrev_b32_e32 v122, 16, v138
	v_and_b32_e32 v123, 0xffff0000, v138
	v_pk_fma_f32 v[110:111], v[80:81], v[122:123], v[110:111]
	v_pk_fma_f32 v[112:113], v[78:79], v[122:123], v[112:113]
	v_pk_fma_f32 v[114:115], v[76:77], v[122:123], v[114:115]
	v_pk_fma_f32 v[116:117], v[74:75], v[122:123], v[116:117]
	v_pk_fma_f32 v[118:119], v[72:73], v[122:123], v[118:119]
	v_pk_fma_f32 v[120:121], v[70:71], v[122:123], v[120:121]
	s_waitcnt vmcnt(4)
	v_lshlrev_b32_e32 v124, 16, v139
	v_and_b32_e32 v125, 0xffff0000, v139
	v_pk_fma_f32 v[112:113], v[80:81], v[124:125], v[112:113]
	v_pk_fma_f32 v[114:115], v[78:79], v[124:125], v[114:115]
	v_pk_fma_f32 v[116:117], v[76:77], v[124:125], v[116:117]
	v_pk_fma_f32 v[118:119], v[74:75], v[124:125], v[118:119]
	v_pk_fma_f32 v[120:121], v[72:73], v[124:125], v[120:121]
	s_waitcnt vmcnt(3)
; #define LDS_BARRIER() do { asm volatile("s_waitcnt lgkmcnt(0)" ::: "memory"); __builtin_amdgcn_s_barrier(); asm volatile("" ::: "memory"); } while (0)
; template <int TT>
; __device__ __forceinline__ void conv_pair(const Params& p, unsigned char* lds, bool sample, int tile) {
;     ...
;     const f32x4 g0 = *(const f32x4*)(p.in[I_CLG] + 8 * lane), g1 = *(const f32x4*)(p.in[I_CLG] + 8 * lane + 4), b0 = *(const f32x4*)(p.in[I_CLB] + 8 * lane), b1 = *(const f32x4*)(p.in[I_CLB] + 8 * lane + 4);
;     if (tile >= 0) {
;         f32x2v w[CW];
; #pragma unroll
;         for (int j = 0; j < CW; ++j) w[j] = *(const f32x2v*)(p.in[I_CDW] + j * MIXB + 2 * cp);
;         const f32x2v bias = *(const f32x2v*)(p.in[I_CDB] + 2 * cp);
;         f32x2v acc[TT];
; #pragma unroll
;         for (int t = 0; t < TT; ++t) acc[t] = bias;
; #pragma unroll
;         for (int r = 0; r < TT + CW - 1; ++r) {
;             f32x2v val;
;             if (sample && r < CW - 1) val = __builtin_nontemporal_load((const f32x2v*)(p.in[I_SC] + ((size_t)sq * (CW - 1) + r) * MIXB + 2 * cp));
;             else { const int i = t0 + r - (CW - 1); unsigned raw = 0u; if (sample || i >= 0) raw = *(const unsigned*)(U + (size_t)(sample ? row0 + r - (CW - 1) : sq * SEQ + i) * MIXB + 2 * cp);
;                 val[0] = __uint_as_float(raw << 16); val[1] = __uint_as_float(raw & 0xffff0000u); }
; #pragma unroll
;             for (int t = 0; t < TT; ++t) { const int j = r - t; if (j >= 0 && j < CW) acc[t] += w[j] * val; }
;         }
; #pragma unroll
;         for (int t = 0; t < TT; ++t) *(f32x2v*)(zb + t * MIXB + 2 * cp) = acc[t];
;     }
;     LDS_BARRIER();
;     if (tile >= 0) {
; #pragma unroll
;         for (int tt = 0; tt < TT / 4; ++tt) { const int t = wq * (TT / 4) + tt;
;             const f32x4 z0 = *(const f32x4*)(zb + t * MIXB + 8 * lane), z1 = *(const f32x4*)(zb + t * MIXB + 8 * lane + 4);
;             const float s1 = wave_sum((z0[0] + z0[1]) + (z0[2] + z0[3]) + (z1[0] + z1[1]) + (z1[2] + z1[3]));
;             const float mu = s1 * (1.0f / MIXB); const f32x4 d0 = z0 - mu, d1 = z1 - mu;
;             const float s2 = wave_sum((d0[0] * d0[0] + d0[1] * d0[1]) + (d0[2] * d0[2] + d0[3] * d0[3]) + (d1[0] * d1[0] + d1[1] * d1[1]) + (d1[2] * d1[2] + d1[3] * d1[3]));
;             const float rstd = rsqrtf(s2 * (1.0f / MIXB) + EPS);
	v_lshlrev_b32_e32 v122, 16, v140
	v_and_b32_e32 v123, 0xffff0000, v140
	v_pk_fma_f32 v[114:115], v[80:81], v[122:123], v[114:115]
	v_pk_fma_f32 v[116:117], v[78:79], v[122:123], v[116:117]
	v_pk_fma_f32 v[118:119], v[76:77], v[122:123], v[118:119]
	v_pk_fma_f32 v[120:121], v[74:75], v[122:123], v[120:121]
	s_waitcnt vmcnt(2)
	v_lshlrev_b32_e32 v124, 16, v141
	v_and_b32_e32 v125, 0xffff0000, v141
	v_pk_fma_f32 v[116:117], v[80:81], v[124:125], v[116:117]
	v_pk_fma_f32 v[118:119], v[78:79], v[124:125], v[118:119]
	v_pk_fma_f32 v[120:121], v[76:77], v[124:125], v[120:121]
	s_waitcnt vmcnt(1)
	v_lshlrev_b32_e32 v122, 16, v142
	v_and_b32_e32 v123, 0xffff0000, v142
	v_pk_fma_f32 v[118:119], v[80:81], v[122:123], v[118:119]
	v_pk_fma_f32 v[120:121], v[78:79], v[122:123], v[120:121]
	s_waitcnt vmcnt(0)
	v_lshlrev_b32_e32 v124, 16, v143
	v_and_b32_e32 v125, 0xffff0000, v143
	v_pk_fma_f32 v[120:121], v[80:81], v[124:125], v[120:121]
	v_lshlrev_b32_e32 v153, 5, v206
	global_load_dwordx4 v[36:39], v153, s[76:77]
	global_load_dwordx4 v[40:43], v153, s[76:77] offset:16
	global_load_dwordx4 v[44:47], v153, s[78:79]
	global_load_dwordx4 v[52:55], v153, s[78:79] offset:16
	ds_write_b64 v152, v[84:85]
	ds_write_b64 v152, v[86:87] offset:2048
	ds_write_b64 v152, v[92:93] offset:4096
	ds_write_b64 v152, v[94:95] offset:6144
	ds_write_b64 v152, v[98:99] offset:8192
	ds_write_b64 v152, v[100:101] offset:10240
	ds_write_b64 v152, v[102:103] offset:12288
	ds_write_b64 v152, v[104:105] offset:14336
	ds_write_b64 v152, v[106:107] offset:16384
	ds_write_b64 v152, v[108:109] offset:18432
	ds_write_b64 v152, v[110:111] offset:20480
	ds_write_b64 v152, v[112:113] offset:22528
	ds_write_b64 v152, v[114:115] offset:24576
	ds_write_b64 v152, v[116:117] offset:26624
	ds_write_b64 v152, v[118:119] offset:28672
	ds_write_b64 v152, v[120:121] offset:30720
	s_waitcnt lgkmcnt(0)
	s_barrier
	v_lshrrev_b32_e32 v83, 6, v176
	v_readfirstlane_b32 s46, v176
	v_lshlrev_b32_e32 v83, 13, v83
	v_lshl_add_u32 v83, v206, 5, v83
	v_readlane_b32 s56, v247, 38
	v_readlane_b32 s57, v247, 39
	ds_read_b128 v[0:3], v83
	ds_read_b128 v[4:7], v83 offset:16
	ds_read_b128 v[8:11], v83 offset:2048
	ds_read_b128 v[12:15], v83 offset:2064
	ds_read_b128 v[20:23], v83 offset:4096
	ds_read_b128 v[24:27], v83 offset:4112
	ds_read_b128 v[28:31], v83 offset:6144
	ds_read_b128 v[32:35], v83 offset:6160
	s_lshr_b32 s46, s46, 6
	s_and_b32 s46, s46, 3
	s_lshl_b32 s46, s46, 2
	s_add_u32 s46, s46, s47
	s_lshl_b32 s46, s46, 11
	s_add_u32 s56, s56, s46
	s_addc_u32 s57, s57, 0
	s_add_u32 s56, s56, 0x96f6200
	s_addc_u32 s57, s57, 0
	v_mov_b32_e32 v84, 0x358637bd
	v_lshlrev_b32_e32 v85, 4, v206
	s_waitcnt lgkmcnt(6)
	v_add_f32_e32 v16, v0, v1
	v_add_f32_e32 v75, v2, v3
	v_add_f32_e32 v76, v4, v5
	v_add_f32_e32 v16, v16, v75
	v_add_f32_e32 v75, v6, v7
	v_add_f32_e32 v16, v16, v76
	v_add_f32_e32 v16, v16, v75
	s_waitcnt lgkmcnt(4)
	v_add_f32_e32 v72, v8, v9
	v_add_f32_e32 v77, v10, v11
	v_add_f32_e32 v78, v12, v13
	v_add_f32_e32 v72, v72, v77
	v_add_f32_e32 v77, v14, v15
	v_add_f32_e32 v72, v72, v78
	v_add_f32_e32 v72, v72, v77
	s_waitcnt lgkmcnt(2)
	v_add_f32_e32 v73, v20, v21
	v_add_f32_e32 v79, v22, v23
	v_add_f32_e32 v80, v24, v25
	v_add_f32_e32 v73, v73, v79
	v_add_f32_e32 v79, v26, v27
	v_add_f32_e32 v73, v73, v80
	v_add_f32_e32 v73, v73, v79
	s_waitcnt lgkmcnt(0)
	v_add_f32_e32 v74, v28, v29
	v_add_f32_e32 v81, v30, v31
	v_add_f32_e32 v82, v32, v33
	v_add_f32_e32 v74, v74, v81
	v_add_f32_e32 v81, v34, v35
	v_add_f32_e32 v74, v74, v82
	v_add_f32_e32 v74, v74, v81
	v_add_f32_dpp v16, v16, v16 quad_perm:[1,0,3,2] row_mask:0xf bank_mask:0xf bound_ctrl:1
	v_add_f32_dpp v72, v72, v72 quad_perm:[1,0,3,2] row_mask:0xf bank_mask:0xf bound_ctrl:1
	v_add_f32_dpp v73, v73, v73 quad_perm:[1,0,3,2] row_mask:0xf bank_mask:0xf bound_ctrl:1
	v_add_f32_dpp v74, v74, v74 quad_perm:[1,0,3,2] row_mask:0xf bank_mask:0xf bound_ctrl:1
	v_add_f32_dpp v16, v16, v16 quad_perm:[2,3,0,1] row_mask:0xf bank_mask:0xf bound_ctrl:1
	v_add_f32_dpp v72, v72, v72 quad_perm:[2,3,0,1] row_mask:0xf bank_mask:0xf bound_ctrl:1
	v_add_f32_dpp v73, v73, v73 quad_perm:[2,3,0,1] row_mask:0xf bank_mask:0xf bound_ctrl:1
	v_add_f32_dpp v74, v74, v74 quad_perm:[2,3,0,1] row_mask:0xf bank_mask:0xf bound_ctrl:1
	v_add_f32_dpp v16, v16, v16 row_half_mirror row_mask:0xf bank_mask:0xf bound_ctrl:1
	v_add_f32_dpp v72, v72, v72 row_half_mirror row_mask:0xf bank_mask:0xf bound_ctrl:1
	v_add_f32_dpp v73, v73, v73 row_half_mirror row_mask:0xf bank_mask:0xf bound_ctrl:1
	v_add_f32_dpp v74, v74, v74 row_half_mirror row_mask:0xf bank_mask:0xf bound_ctrl:1
	v_add_f32_dpp v16, v16, v16 row_mirror row_mask:0xf bank_mask:0xf bound_ctrl:1
	v_add_f32_dpp v72, v72, v72 row_mirror row_mask:0xf bank_mask:0xf bound_ctrl:1
	v_add_f32_dpp v73, v73, v73 row_mirror row_mask:0xf bank_mask:0xf bound_ctrl:1
	v_add_f32_dpp v74, v74, v74 row_mirror row_mask:0xf bank_mask:0xf bound_ctrl:1
	s_nop 0
	v_readlane_b32 s46, v16, 0
	v_readlane_b32 s50, v16, 16
	v_readlane_b32 s51, v16, 32
	v_readlane_b32 s54, v16, 48
	v_readlane_b32 s55, v72, 0
	v_readlane_b32 s60, v72, 16
	v_readlane_b32 s61, v72, 32
	v_readlane_b32 s32, v72, 48
	v_mov_b32_e32 v75, s50
	v_mov_b32_e32 v76, s54
	v_add_f32_e32 v75, s46, v75
	v_add_f32_e32 v76, s51, v76
	v_add_f32_e32 v16, v75, v76
	v_mov_b32_e32 v77, s60
	v_mov_b32_e32 v78, s32
	v_add_f32_e32 v77, s55, v77
	v_add_f32_e32 v78, s61, v78
	v_add_f32_e32 v72, v77, v78
	s_nop 0
	v_readlane_b32 s46, v73, 0
	v_readlane_b32 s50, v73, 16
	v_readlane_b32 s51, v73, 32
	v_readlane_b32 s54, v73, 48
	v_readlane_b32 s55, v74, 0
	v_readlane_b32 s60, v74, 16
	v_readlane_b32 s61, v74, 32
; template <int CTRL> __device__ __forceinline__ float dpp_step(float t) { return t + __builtin_bit_cast(float, __builtin_amdgcn_update_dpp(0, __builtin_bit_cast(int, t), CTRL, 0xF, 0xF, true)); }
; __device__ __forceinline__ float wave_sum(float v) {
;     float t = dpp_step<0xB1>(v);
;     t = dpp_step<0x4E>(t);
;     t = dpp_step<0x141>(t);
;     t = dpp_step<0x140>(t);
;     const int ti = __builtin_bit_cast(int, t);
;     return (__builtin_bit_cast(float, __builtin_amdgcn_readlane(ti, 0)) + __builtin_bit_cast(float, __builtin_amdgcn_readlane(ti, 16)))
;          + (__builtin_bit_cast(float, __builtin_amdgcn_readlane(ti, 32)) + __builtin_bit_cast(float, __builtin_amdgcn_readlane(ti, 48)));
; template <int TT>
; __device__ __forceinline__ void conv_pair(const Params& p, unsigned char* lds, bool sample, int tile) {
;     ...
;             const float s1 = wave_sum((z0[0] + z0[1]) + (z0[2] + z0[3]) + (z1[0] + z1[1]) + (z1[2] + z1[3]));
;             const float mu = s1 * (1.0f / MIXB); const f32x4 d0 = z0 - mu, d1 = z1 - mu;
;             const float s2 = wave_sum((d0[0] * d0[0] + d0[1] * d0[1]) + (d0[2] * d0[2] + d0[3] * d0[3]) + (d1[0] * d1[0] + d1[1] * d1[1]) + (d1[2] * d1[2] + d1[3] * d1[3]));
;             const float rstd = rsqrtf(s2 * (1.0f / MIXB) + EPS);
	v_readlane_b32 s32, v74, 48
	v_mov_b32_e32 v79, s50
	v_mov_b32_e32 v80, s54
	v_add_f32_e32 v79, s46, v79
	v_add_f32_e32 v80, s51, v80
	v_add_f32_e32 v73, v79, v80
	v_mov_b32_e32 v81, s60
	v_mov_b32_e32 v82, s32
	v_add_f32_e32 v81, s55, v81
	v_add_f32_e32 v82, s61, v82
	v_add_f32_e32 v74, v81, v82
	v_fmamk_f32 v0, v16, 0xbb000000, v0
	v_fmamk_f32 v1, v16, 0xbb000000, v1
	v_fmamk_f32 v2, v16, 0xbb000000, v2
	v_fmamk_f32 v3, v16, 0xbb000000, v3
	v_fmamk_f32 v4, v16, 0xbb000000, v4
	v_fmamk_f32 v5, v16, 0xbb000000, v5
	v_fmamk_f32 v6, v16, 0xbb000000, v6
	v_fmamk_f32 v7, v16, 0xbb000000, v7
	v_fmamk_f32 v8, v72, 0xbb000000, v8
	v_fmamk_f32 v9, v72, 0xbb000000, v9
	v_fmamk_f32 v10, v72, 0xbb000000, v10
	v_fmamk_f32 v11, v72, 0xbb000000, v11
	v_fmamk_f32 v12, v72, 0xbb000000, v12
	v_fmamk_f32 v13, v72, 0xbb000000, v13
	v_fmamk_f32 v14, v72, 0xbb000000, v14
	v_fmamk_f32 v15, v72, 0xbb000000, v15
	v_fmamk_f32 v20, v73, 0xbb000000, v20
	v_fmamk_f32 v21, v73, 0xbb000000, v21
	v_fmamk_f32 v22, v73, 0xbb000000, v22
	v_fmamk_f32 v23, v73, 0xbb000000, v23
	v_fmamk_f32 v24, v73, 0xbb000000, v24
	v_fmamk_f32 v25, v73, 0xbb000000, v25
	v_fmamk_f32 v26, v73, 0xbb000000, v26
	v_fmamk_f32 v27, v73, 0xbb000000, v27
	v_fmamk_f32 v28, v74, 0xbb000000, v28
	v_fmamk_f32 v29, v74, 0xbb000000, v29
	v_fmamk_f32 v30, v74, 0xbb000000, v30
	v_fmamk_f32 v31, v74, 0xbb000000, v31
	v_fmamk_f32 v32, v74, 0xbb000000, v32
	v_fmamk_f32 v33, v74, 0xbb000000, v33
	v_fmamk_f32 v34, v74, 0xbb000000, v34
	v_fmamk_f32 v35, v74, 0xbb000000, v35
	v_pk_mul_f32 v[56:57], v[0:1], v[0:1]
	v_pk_mul_f32 v[58:59], v[2:3], v[2:3]
	v_pk_mul_f32 v[18:19], v[4:5], v[4:5]
	v_pk_mul_f32 v[50:51], v[6:7], v[6:7]
	v_add_f32_e32 v16, v56, v57
	v_add_f32_e32 v75, v58, v59
	v_add_f32_e32 v76, v18, v19
	v_add_f32_e32 v16, v16, v75
	v_add_f32_e32 v75, v50, v51
	v_add_f32_e32 v16, v16, v76
	v_add_f32_e32 v16, v16, v75
	v_pk_mul_f32 v[60:61], v[8:9], v[8:9]
	v_pk_mul_f32 v[62:63], v[10:11], v[10:11]
	v_pk_mul_f32 v[18:19], v[12:13], v[12:13]
	v_pk_mul_f32 v[50:51], v[14:15], v[14:15]
	v_add_f32_e32 v72, v60, v61
	v_add_f32_e32 v77, v62, v63
	v_add_f32_e32 v78, v18, v19
	v_add_f32_e32 v72, v72, v77
	v_add_f32_e32 v77, v50, v51
	v_add_f32_e32 v72, v72, v78
	v_add_f32_e32 v72, v72, v77
	v_pk_mul_f32 v[64:65], v[20:21], v[20:21]
	v_pk_mul_f32 v[66:67], v[22:23], v[22:23]
	v_pk_mul_f32 v[18:19], v[24:25], v[24:25]
	v_pk_mul_f32 v[50:51], v[26:27], v[26:27]
	v_add_f32_e32 v73, v64, v65
	v_add_f32_e32 v79, v66, v67
	v_add_f32_e32 v80, v18, v19
	v_add_f32_e32 v73, v73, v79
	v_add_f32_e32 v79, v50, v51
	v_add_f32_e32 v73, v73, v80
	v_add_f32_e32 v73, v73, v79
	v_pk_mul_f32 v[68:69], v[28:29], v[28:29]
	v_pk_mul_f32 v[70:71], v[30:31], v[30:31]
	v_pk_mul_f32 v[18:19], v[32:33], v[32:33]
	v_pk_mul_f32 v[50:51], v[34:35], v[34:35]
	v_add_f32_e32 v74, v68, v69
	v_add_f32_e32 v81, v70, v71
	v_add_f32_e32 v82, v18, v19
	v_add_f32_e32 v74, v74, v81
	v_add_f32_e32 v81, v50, v51
	v_add_f32_e32 v74, v74, v82
	v_add_f32_e32 v74, v74, v81
	v_add_f32_dpp v16, v16, v16 quad_perm:[1,0,3,2] row_mask:0xf bank_mask:0xf bound_ctrl:1
	v_add_f32_dpp v72, v72, v72 quad_perm:[1,0,3,2] row_mask:0xf bank_mask:0xf bound_ctrl:1
	v_add_f32_dpp v73, v73, v73 quad_perm:[1,0,3,2] row_mask:0xf bank_mask:0xf bound_ctrl:1
	v_add_f32_dpp v74, v74, v74 quad_perm:[1,0,3,2] row_mask:0xf bank_mask:0xf bound_ctrl:1
	v_add_f32_dpp v16, v16, v16 quad_perm:[2,3,0,1] row_mask:0xf bank_mask:0xf bound_ctrl:1
	v_add_f32_dpp v72, v72, v72 quad_perm:[2,3,0,1] row_mask:0xf bank_mask:0xf bound_ctrl:1
	v_add_f32_dpp v73, v73, v73 quad_perm:[2,3,0,1] row_mask:0xf bank_mask:0xf bound_ctrl:1
	v_add_f32_dpp v74, v74, v74 quad_perm:[2,3,0,1] row_mask:0xf bank_mask:0xf bound_ctrl:1
	v_add_f32_dpp v16, v16, v16 row_half_mirror row_mask:0xf bank_mask:0xf bound_ctrl:1
	v_add_f32_dpp v72, v72, v72 row_half_mirror row_mask:0xf bank_mask:0xf bound_ctrl:1
	v_add_f32_dpp v73, v73, v73 row_half_mirror row_mask:0xf bank_mask:0xf bound_ctrl:1
	v_add_f32_dpp v74, v74, v74 row_half_mirror row_mask:0xf bank_mask:0xf bound_ctrl:1
	v_add_f32_dpp v16, v16, v16 row_mirror row_mask:0xf bank_mask:0xf bound_ctrl:1
	v_add_f32_dpp v72, v72, v72 row_mirror row_mask:0xf bank_mask:0xf bound_ctrl:1
	v_add_f32_dpp v73, v73, v73 row_mirror row_mask:0xf bank_mask:0xf bound_ctrl:1
	v_add_f32_dpp v74, v74, v74 row_mirror row_mask:0xf bank_mask:0xf bound_ctrl:1
	s_nop 0
	v_readlane_b32 s46, v16, 0
	v_readlane_b32 s50, v16, 16
	v_readlane_b32 s51, v16, 32
	v_readlane_b32 s54, v16, 48
	v_readlane_b32 s55, v72, 0
	v_readlane_b32 s60, v72, 16
	v_readlane_b32 s61, v72, 32
	v_readlane_b32 s32, v72, 48
	v_mov_b32_e32 v75, s50
	v_mov_b32_e32 v76, s54
	v_add_f32_e32 v75, s46, v75
	v_add_f32_e32 v76, s51, v76
	v_add_f32_e32 v16, v75, v76
	v_mov_b32_e32 v77, s60
	v_mov_b32_e32 v78, s32
	v_add_f32_e32 v77, s55, v77
	v_add_f32_e32 v78, s61, v78
	v_add_f32_e32 v72, v77, v78
	s_nop 0
	v_readlane_b32 s46, v73, 0
	v_readlane_b32 s50, v73, 16
	v_readlane_b32 s51, v73, 32
	v_readlane_b32 s54, v73, 48
	v_readlane_b32 s55, v74, 0
	v_readlane_b32 s60, v74, 16
	v_readlane_b32 s61, v74, 32
	v_readlane_b32 s32, v74, 48
	v_mov_b32_e32 v79, s50
	v_mov_b32_e32 v80, s54
	v_add_f32_e32 v79, s46, v79
	v_add_f32_e32 v80, s51, v80
	v_add_f32_e32 v73, v79, v80
	v_mov_b32_e32 v81, s60
	v_mov_b32_e32 v82, s32
	v_add_f32_e32 v81, s55, v81
	v_add_f32_e32 v82, s61, v82
	v_add_f32_e32 v74, v81, v82
	v_fmamk_f32 v16, v16, 0x3b000000, v84
	v_fmamk_f32 v72, v72, 0x3b000000, v84
	v_fmamk_f32 v73, v73, 0x3b000000, v84
	v_fmamk_f32 v74, v74, 0x3b000000, v84
	v_rsq_f32_e32 v16, v16
	v_rsq_f32_e32 v72, v72
	v_rsq_f32_e32 v73, v73
	v_rsq_f32_e32 v74, v74
	s_waitcnt vmcnt(0)
; __device__ __forceinline__ unsigned cvt_pk_bf16(float lo, float hi) { unsigned r; asm volatile("v_cvt_pk_bf16_f32 %0, %1, %2" : "=v"(r) : "v"(lo), "v"(hi)); return r; }
; __device__ __forceinline__ float siluf_(float x) { return x * frcp(1.0f + __expf(-x)); }
; template <int TT>
; __device__ __forceinline__ void conv_pair(const Params& p, unsigned char* lds, bool sample, int tile) {
;     ...
;             f32x4 y0 = d0 * rstd * g0 + b0, y1 = d1 * rstd * g1 + b1;
; #pragma unroll
;             for (int j = 0; j < 4; ++j) { y0[j] = siluf_(y0[j]); y1[j] = siluf_(y1[j]); }
;             u32x4 o; o.x = cvt_pk_bf16(y0[0], y0[1]); o.y = cvt_pk_bf16(y0[2], y0[3]); o.z = cvt_pk_bf16(y1[0], y1[1]); o.w = cvt_pk_bf16(y1[2], y1[3]);
;             *(u32x4*)(CAT + (size_t)(row0 + t) * DM + MIXA + 8 * lane) = o; }
	v_mul_f32_e32 v0, v0, v16
	v_mul_f32_e32 v1, v1, v16
	v_mul_f32_e32 v2, v2, v16
	v_mul_f32_e32 v3, v3, v16
	v_mul_f32_e32 v4, v4, v16
	v_mul_f32_e32 v5, v5, v16
	v_mul_f32_e32 v6, v6, v16
	v_mul_f32_e32 v7, v7, v16
	v_mul_f32_e32 v8, v8, v72
	v_mul_f32_e32 v9, v9, v72
	v_mul_f32_e32 v10, v10, v72
	v_mul_f32_e32 v11, v11, v72
	v_mul_f32_e32 v12, v12, v72
	v_mul_f32_e32 v13, v13, v72
	v_mul_f32_e32 v14, v14, v72
	v_mul_f32_e32 v15, v15, v72
	v_mul_f32_e32 v20, v20, v73
	v_mul_f32_e32 v21, v21, v73
	v_mul_f32_e32 v22, v22, v73
	v_mul_f32_e32 v23, v23, v73
	v_mul_f32_e32 v24, v24, v73
	v_mul_f32_e32 v25, v25, v73
	v_mul_f32_e32 v26, v26, v73
	v_mul_f32_e32 v27, v27, v73
	v_mul_f32_e32 v28, v28, v74
	v_mul_f32_e32 v29, v29, v74
	v_mul_f32_e32 v30, v30, v74
	v_mul_f32_e32 v31, v31, v74
	v_mul_f32_e32 v32, v32, v74
	v_mul_f32_e32 v33, v33, v74
	v_mul_f32_e32 v34, v34, v74
	v_mul_f32_e32 v35, v35, v74
	v_pk_fma_f32 v[0:1], v[36:37], v[0:1], v[44:45]
	v_pk_fma_f32 v[2:3], v[38:39], v[2:3], v[46:47]
	v_pk_fma_f32 v[4:5], v[40:41], v[4:5], v[52:53]
	v_pk_fma_f32 v[6:7], v[42:43], v[6:7], v[54:55]
	v_pk_fma_f32 v[8:9], v[36:37], v[8:9], v[44:45]
	v_pk_fma_f32 v[10:11], v[38:39], v[10:11], v[46:47]
	v_pk_fma_f32 v[12:13], v[40:41], v[12:13], v[52:53]
	v_pk_fma_f32 v[14:15], v[42:43], v[14:15], v[54:55]
	v_pk_fma_f32 v[20:21], v[36:37], v[20:21], v[44:45]
	v_pk_fma_f32 v[22:23], v[38:39], v[22:23], v[46:47]
	v_pk_fma_f32 v[24:25], v[40:41], v[24:25], v[52:53]
	v_pk_fma_f32 v[26:27], v[42:43], v[26:27], v[54:55]
	v_pk_fma_f32 v[28:29], v[36:37], v[28:29], v[44:45]
	v_pk_fma_f32 v[30:31], v[38:39], v[30:31], v[46:47]
	v_pk_fma_f32 v[32:33], v[40:41], v[32:33], v[52:53]
	v_pk_fma_f32 v[34:35], v[42:43], v[34:35], v[54:55]
	v_mul_f32_e32 v56, 0xbfb8aa3b, v0
	v_mul_f32_e32 v57, 0xbfb8aa3b, v1
	v_mul_f32_e32 v58, 0xbfb8aa3b, v2
	v_mul_f32_e32 v59, 0xbfb8aa3b, v3
	v_mul_f32_e32 v18, 0xbfb8aa3b, v4
	v_mul_f32_e32 v19, 0xbfb8aa3b, v5
	v_mul_f32_e32 v50, 0xbfb8aa3b, v6
	v_mul_f32_e32 v51, 0xbfb8aa3b, v7
	v_exp_f32_e32 v56, v56
	v_exp_f32_e32 v57, v57
	v_exp_f32_e32 v58, v58
	v_exp_f32_e32 v59, v59
	v_exp_f32_e32 v18, v18
	v_exp_f32_e32 v19, v19
	v_exp_f32_e32 v50, v50
	v_exp_f32_e32 v51, v51
	v_add_f32_e32 v56, 1.0, v56
	v_add_f32_e32 v57, 1.0, v57
	v_add_f32_e32 v58, 1.0, v58
	v_add_f32_e32 v59, 1.0, v59
	v_add_f32_e32 v18, 1.0, v18
	v_add_f32_e32 v19, 1.0, v19
	v_add_f32_e32 v50, 1.0, v50
	v_add_f32_e32 v51, 1.0, v51
	v_rcp_f32_e32 v56, v56
	v_rcp_f32_e32 v57, v57
	v_rcp_f32_e32 v58, v58
	v_rcp_f32_e32 v59, v59
	v_rcp_f32_e32 v18, v18
	v_rcp_f32_e32 v19, v19
	v_rcp_f32_e32 v50, v50
	v_rcp_f32_e32 v51, v51
	v_mul_f32_e32 v0, v0, v56
	v_mul_f32_e32 v1, v1, v57
	v_mul_f32_e32 v2, v2, v58
	v_mul_f32_e32 v3, v3, v59
	v_mul_f32_e32 v4, v4, v18
	v_mul_f32_e32 v5, v5, v19
	v_mul_f32_e32 v6, v6, v50
	v_mul_f32_e32 v7, v7, v51
	v_cvt_pk_bf16_f32 v56, v0, v1
	v_cvt_pk_bf16_f32 v57, v2, v3
	v_cvt_pk_bf16_f32 v58, v4, v5
	v_cvt_pk_bf16_f32 v59, v6, v7
	global_store_dwordx4 v85, v[56:59], s[56:57]
	v_mul_f32_e32 v60, 0xbfb8aa3b, v8
	v_mul_f32_e32 v61, 0xbfb8aa3b, v9
	v_mul_f32_e32 v62, 0xbfb8aa3b, v10
	v_mul_f32_e32 v63, 0xbfb8aa3b, v11
	v_mul_f32_e32 v18, 0xbfb8aa3b, v12
	v_mul_f32_e32 v19, 0xbfb8aa3b, v13
	v_mul_f32_e32 v50, 0xbfb8aa3b, v14
	v_mul_f32_e32 v51, 0xbfb8aa3b, v15
	v_exp_f32_e32 v60, v60
	v_exp_f32_e32 v61, v61
	v_exp_f32_e32 v62, v62
	v_exp_f32_e32 v63, v63
	v_exp_f32_e32 v18, v18
	v_exp_f32_e32 v19, v19
	v_exp_f32_e32 v50, v50
	v_exp_f32_e32 v51, v51
	v_add_f32_e32 v60, 1.0, v60
	v_add_f32_e32 v61, 1.0, v61
	v_add_f32_e32 v62, 1.0, v62
	v_add_f32_e32 v63, 1.0, v63
	v_add_f32_e32 v18, 1.0, v18
	v_add_f32_e32 v19, 1.0, v19
	v_add_f32_e32 v50, 1.0, v50
	v_add_f32_e32 v51, 1.0, v51
	v_rcp_f32_e32 v60, v60
	v_rcp_f32_e32 v61, v61
	v_rcp_f32_e32 v62, v62
	v_rcp_f32_e32 v63, v63
	v_rcp_f32_e32 v18, v18
	v_rcp_f32_e32 v19, v19
	v_rcp_f32_e32 v50, v50
	v_rcp_f32_e32 v51, v51
	v_mul_f32_e32 v8, v8, v60
	v_mul_f32_e32 v9, v9, v61
	v_mul_f32_e32 v10, v10, v62
	v_mul_f32_e32 v11, v11, v63
	v_mul_f32_e32 v12, v12, v18
	v_mul_f32_e32 v13, v13, v19
	v_mul_f32_e32 v14, v14, v50
	v_mul_f32_e32 v15, v15, v51
	v_cvt_pk_bf16_f32 v60, v8, v9
	v_cvt_pk_bf16_f32 v61, v10, v11
	v_cvt_pk_bf16_f32 v62, v12, v13
	v_cvt_pk_bf16_f32 v63, v14, v15
	global_store_dwordx4 v85, v[60:63], s[56:57] offset:2048
	v_mul_f32_e32 v64, 0xbfb8aa3b, v20
	v_mul_f32_e32 v65, 0xbfb8aa3b, v21
	v_mul_f32_e32 v66, 0xbfb8aa3b, v22
	v_mul_f32_e32 v67, 0xbfb8aa3b, v23
	v_mul_f32_e32 v18, 0xbfb8aa3b, v24
	v_mul_f32_e32 v19, 0xbfb8aa3b, v25
	v_mul_f32_e32 v50, 0xbfb8aa3b, v26
	v_mul_f32_e32 v51, 0xbfb8aa3b, v27
	v_exp_f32_e32 v64, v64
	v_exp_f32_e32 v65, v65
	v_exp_f32_e32 v66, v66
	v_exp_f32_e32 v67, v67
	v_exp_f32_e32 v18, v18
	v_exp_f32_e32 v19, v19
	v_exp_f32_e32 v50, v50
	v_exp_f32_e32 v51, v51
	v_add_f32_e32 v64, 1.0, v64
	v_add_f32_e32 v65, 1.0, v65
	v_add_f32_e32 v66, 1.0, v66
	v_add_f32_e32 v67, 1.0, v67
	v_add_f32_e32 v18, 1.0, v18
	v_add_f32_e32 v19, 1.0, v19
	v_add_f32_e32 v50, 1.0, v50
	v_add_f32_e32 v51, 1.0, v51
	v_rcp_f32_e32 v64, v64
	v_rcp_f32_e32 v65, v65
	v_rcp_f32_e32 v66, v66
	v_rcp_f32_e32 v67, v67
	v_rcp_f32_e32 v18, v18
	v_rcp_f32_e32 v19, v19
	v_rcp_f32_e32 v50, v50
	v_rcp_f32_e32 v51, v51
	v_mul_f32_e32 v20, v20, v64
	v_mul_f32_e32 v21, v21, v65
	v_mul_f32_e32 v22, v22, v66
	v_mul_f32_e32 v23, v23, v67
	v_mul_f32_e32 v24, v24, v18
	v_mul_f32_e32 v25, v25, v19
	v_mul_f32_e32 v26, v26, v50
	v_mul_f32_e32 v27, v27, v51
	v_cvt_pk_bf16_f32 v64, v20, v21
	v_cvt_pk_bf16_f32 v65, v22, v23
	v_cvt_pk_bf16_f32 v66, v24, v25
	v_cvt_pk_bf16_f32 v67, v26, v27
	s_add_u32 s56, s56, 0x1000
	s_addc_u32 s57, s57, 0
	global_store_dwordx4 v85, v[64:67], s[56:57]
	v_mul_f32_e32 v68, 0xbfb8aa3b, v28
	v_mul_f32_e32 v69, 0xbfb8aa3b, v29
	v_mul_f32_e32 v70, 0xbfb8aa3b, v30
	v_mul_f32_e32 v71, 0xbfb8aa3b, v31
	v_mul_f32_e32 v18, 0xbfb8aa3b, v32
	v_mul_f32_e32 v19, 0xbfb8aa3b, v33
	v_mul_f32_e32 v50, 0xbfb8aa3b, v34
	v_mul_f32_e32 v51, 0xbfb8aa3b, v35
	v_exp_f32_e32 v68, v68
	v_exp_f32_e32 v69, v69
	v_exp_f32_e32 v70, v70
	v_exp_f32_e32 v71, v71
	v_exp_f32_e32 v18, v18
	v_exp_f32_e32 v19, v19
	v_exp_f32_e32 v50, v50
	v_exp_f32_e32 v51, v51
	v_add_f32_e32 v68, 1.0, v68
	v_add_f32_e32 v69, 1.0, v69
	v_add_f32_e32 v70, 1.0, v70
	v_add_f32_e32 v71, 1.0, v71
	v_add_f32_e32 v18, 1.0, v18
	v_add_f32_e32 v19, 1.0, v19
	v_add_f32_e32 v50, 1.0, v50
	v_add_f32_e32 v51, 1.0, v51
	v_rcp_f32_e32 v68, v68
	v_rcp_f32_e32 v69, v69
	v_rcp_f32_e32 v70, v70
	v_rcp_f32_e32 v71, v71
	v_rcp_f32_e32 v18, v18
	v_rcp_f32_e32 v19, v19
	v_rcp_f32_e32 v50, v50
	v_rcp_f32_e32 v51, v51
	v_mul_f32_e32 v28, v28, v68
	v_mul_f32_e32 v29, v29, v69
	v_mul_f32_e32 v30, v30, v70
	v_mul_f32_e32 v31, v31, v71
	v_mul_f32_e32 v32, v32, v18
	v_mul_f32_e32 v33, v33, v19
	v_mul_f32_e32 v34, v34, v50
	v_mul_f32_e32 v35, v35, v51
	v_cvt_pk_bf16_f32 v68, v28, v29
	v_cvt_pk_bf16_f32 v69, v30, v31
	v_cvt_pk_bf16_f32 v70, v32, v33
	v_cvt_pk_bf16_f32 v71, v34, v35
	global_store_dwordx4 v85, v[68:71], s[56:57] offset:2048
	s_branch .LBB0_335

; template <int TT>
; __device__ __forceinline__ void conv_pair(const Params& p, unsigned char* lds, bool sample, int tile) {
;     ...
;     if (tile >= 0) {
;         f32x2v w[CW];
; #pragma unroll
;         for (int j = 0; j < CW; ++j) w[j] = *(const f32x2v*)(p.in[I_CDW] + j * MIXB + 2 * cp);
;         const f32x2v bias = *(const f32x2v*)(p.in[I_CDB] + 2 * cp);
;         f32x2v acc[TT];
; #pragma unroll
;         for (int t = 0; t < TT; ++t) acc[t] = bias;
; #pragma unroll
;         for (int r = 0; r < TT + CW - 1; ++r) {
;             f32x2v val;
;             if (sample && r < CW - 1) val = __builtin_nontemporal_load((const f32x2v*)(p.in[I_SC] + ((size_t)sq * (CW - 1) + r) * MIXB + 2 * cp));
;             else { const int i = t0 + r - (CW - 1); unsigned raw = 0u; if (sample || i >= 0) raw = *(const unsigned*)(U + (size_t)(sample ? row0 + r - (CW - 1) : sq * SEQ + i) * MIXB + 2 * cp);
;                 val[0] = __uint_as_float(raw << 16); val[1] = __uint_as_float(raw & 0xffff0000u); }
; #pragma unroll
;             for (int t = 0; t < TT; ++t) { const int j = r - t; if (j >= 0 && j < CW) acc[t] += w[j] * val; }
.LBB0_485:
	s_mov_b64 s[62:63], exec
	s_waitcnt vmcnt(4)
	v_readfirstlane_b32 s4, v136
	v_and_b32_e32 v200, 0xff, v176
	v_lshrrev_b32_e32 v201, 8, v176
	v_readlane_b32 s50, v247, 36
	v_readlane_b32 s51, v247, 37
	v_lshlrev_b32_e32 v199, 3, v200
	v_lshlrev_b32_e32 v200, 2, v200
	v_lshl_add_u32 v201, v201, 15, v199
	s_lshr_b32 s47, s4, 7
	s_and_b32 s46, s4, 0x7f
	s_lshl_b32 s60, s46, 4
	s_lshl_b32 s47, s47, 11
	s_add_u32 s47, s47, s60
	s_lshl_b32 s60, s47, 10
	s_add_u32 s50, s50, s60
	s_addc_u32 s51, s51, 0
	s_sub_u32 s50, s50, 0x7800
	s_subb_u32 s51, s51, 0
	s_cmp_ge_u32 s46, 2
	s_cselect_b32 s32, -1, 0
	s_cselect_b32 s60, 0, 0x7800
	s_cmp_ge_u32 s46, 1
	s_cselect_b32 s99, -1, 0
	s_cselect_b32 s61, 0, 0x4000
	s_mov_b64 s[54:55], s[72:73]
	s_add_u32 s50, s50, s60
	s_addc_u32 s51, s51, 0
	global_load_dwordx2 v[90:91], v199, s[74:75]
	global_load_dwordx2 v[0:1], v199, s[54:55]
	global_load_dwordx2 v[2:3], v199, s[54:55] offset:2048
	s_add_u32 s54, s54, 0x1000
	s_addc_u32 s55, s55, 0
	global_load_dwordx2 v[4:5], v199, s[54:55]
	global_load_dwordx2 v[6:7], v199, s[54:55] offset:2048
	s_add_u32 s54, s54, 0x1000
	s_addc_u32 s55, s55, 0
	global_load_dwordx2 v[8:9], v199, s[54:55]
	global_load_dwordx2 v[10:11], v199, s[54:55] offset:2048
	s_add_u32 s54, s54, 0x1000
	s_addc_u32 s55, s55, 0
	global_load_dwordx2 v[12:13], v199, s[54:55]
	global_load_dwordx2 v[14:15], v199, s[54:55] offset:2048
	s_add_u32 s54, s54, 0x1000
	s_addc_u32 s55, s55, 0
	global_load_dwordx2 v[16:17], v199, s[54:55]
	global_load_dwordx2 v[18:19], v199, s[54:55] offset:2048
	s_add_u32 s54, s54, 0x1000
	s_addc_u32 s55, s55, 0
	global_load_dwordx2 v[20:21], v199, s[54:55]
	global_load_dwordx2 v[22:23], v199, s[54:55] offset:2048
	s_add_u32 s54, s54, 0x1000
	s_addc_u32 s55, s55, 0
	global_load_dwordx2 v[24:25], v199, s[54:55]
	global_load_dwordx2 v[26:27], v199, s[54:55] offset:2048
	s_add_u32 s54, s54, 0x1000
	s_addc_u32 s55, s55, 0
	global_load_dwordx2 v[28:29], v199, s[54:55]
	global_load_dwordx2 v[30:31], v199, s[54:55] offset:2048
	s_add_u32 s54, s54, 0x1000
	s_addc_u32 s55, s55, 0
	global_load_dwordx2 v[60:61], v199, s[54:55]
	global_load_dwordx2 v[62:63], v199, s[54:55] offset:2048
	s_add_u32 s54, s54, 0x1000
	s_addc_u32 s55, s55, 0
	global_load_dwordx2 v[64:65], v199, s[54:55]
	global_load_dwordx2 v[66:67], v199, s[54:55] offset:2048
	s_add_u32 s54, s54, 0x1000
	s_addc_u32 s55, s55, 0
	global_load_dwordx2 v[68:69], v199, s[54:55]
	global_load_dwordx2 v[70:71], v199, s[54:55] offset:2048
	s_add_u32 s54, s54, 0x1000
	s_addc_u32 s55, s55, 0
	global_load_dwordx2 v[72:73], v199, s[54:55]
	global_load_dwordx2 v[74:75], v199, s[54:55] offset:2048
	s_add_u32 s54, s54, 0x1000
	s_addc_u32 s55, s55, 0
	global_load_dwordx2 v[76:77], v199, s[54:55]
	global_load_dwordx2 v[78:79], v199, s[54:55] offset:2048
	s_add_u32 s54, s54, 0x1000
	s_addc_u32 s55, s55, 0
	global_load_dwordx2 v[80:81], v199, s[54:55]
	global_load_dwordx2 v[82:83], v199, s[54:55] offset:2048
	s_add_u32 s54, s54, 0x1000
	s_addc_u32 s55, s55, 0
	global_load_dwordx2 v[84:85], v199, s[54:55]
	global_load_dwordx2 v[86:87], v199, s[54:55] offset:2048
	s_add_u32 s54, s54, 0x1000
	s_addc_u32 s55, s55, 0
	global_load_dwordx2 v[88:89], v199, s[54:55]
	global_load_dword v50, v200, s[50:51]
	global_load_dword v170, v200, s[50:51] offset:1024
	global_load_dword v171, v200, s[50:51] offset:2048
	global_load_dword v172, v200, s[50:51] offset:3072
	s_add_u32 s50, s50, 0x1000
	s_addc_u32 s51, s51, 0
	global_load_dword v173, v200, s[50:51]
	global_load_dword v174, v200, s[50:51] offset:1024
	global_load_dword v175, v200, s[50:51] offset:2048
	global_load_dword v180, v200, s[50:51] offset:3072
	s_add_u32 s50, s50, 0x1000
	s_addc_u32 s51, s51, 0
	global_load_dword v181, v200, s[50:51]
	global_load_dword v182, v200, s[50:51] offset:1024
	global_load_dword v183, v200, s[50:51] offset:2048
	global_load_dword v184, v200, s[50:51] offset:3072
	s_add_u32 s50, s50, 0x1000
	s_addc_u32 s51, s51, 0
	global_load_dword v185, v200, s[50:51]
	global_load_dword v186, v200, s[50:51] offset:1024
	s_sub_u32 s50, s50, s60
	s_subb_u32 s51, s51, 0
	s_add_u32 s50, s50, s61
	s_addc_u32 s51, s51, 0
	global_load_dword v187, v200, s[50:51] offset:2048
	global_load_dword v188, v200, s[50:51] offset:3072
	s_add_u32 s50, s50, 0x1000
	s_addc_u32 s51, s51, 0
	global_load_dword v189, v200, s[50:51]
	global_load_dword v190, v200, s[50:51] offset:1024
	global_load_dword v191, v200, s[50:51] offset:2048
	global_load_dword v192, v200, s[50:51] offset:3072
	s_add_u32 s50, s50, 0x1000
	s_addc_u32 s51, s51, 0
	global_load_dword v193, v200, s[50:51]
	global_load_dword v194, v200, s[50:51] offset:1024
	global_load_dword v195, v200, s[50:51] offset:2048
	global_load_dword v196, v200, s[50:51] offset:3072
	s_add_u32 s50, s50, 0x1000
	s_addc_u32 s51, s51, 0
	global_load_dword v197, v200, s[50:51]
	global_load_dword v198, v200, s[50:51] offset:1024
	s_waitcnt vmcnt(25)
	v_and_b32_e32 v50, s32, v50
	v_lshlrev_b32_e32 v166, 16, v50
	v_and_b32_e32 v167, 0xffff0000, v50
	v_pk_fma_f32 v[92:93], v[0:1], v[166:167], v[90:91]
	global_load_dword v50, v200, s[50:51] offset:2048
	s_waitcnt vmcnt(25)
	v_and_b32_e32 v170, s32, v170
	v_lshlrev_b32_e32 v168, 16, v170
	v_and_b32_e32 v169, 0xffff0000, v170
	v_pk_fma_f32 v[92:93], v[2:3], v[168:169], v[92:93]
	v_pk_fma_f32 v[94:95], v[0:1], v[168:169], v[90:91]
	global_load_dword v170, v200, s[50:51] offset:3072
	s_waitcnt vmcnt(25)
	v_and_b32_e32 v171, s32, v171
	v_lshlrev_b32_e32 v166, 16, v171
	v_and_b32_e32 v167, 0xffff0000, v171
	v_pk_fma_f32 v[92:93], v[4:5], v[166:167], v[92:93]
	v_pk_fma_f32 v[94:95], v[2:3], v[166:167], v[94:95]
	v_pk_fma_f32 v[138:139], v[0:1], v[166:167], v[90:91]
	s_add_u32 s50, s50, 0x1000
	s_addc_u32 s51, s51, 0
	global_load_dword v171, v200, s[50:51]
	s_waitcnt vmcnt(25)
; template <int TT>
; __device__ __forceinline__ void conv_pair(const Params& p, unsigned char* lds, bool sample, int tile) {
;     ...
;             else { const int i = t0 + r - (CW - 1); unsigned raw = 0u; if (sample || i >= 0) raw = *(const unsigned*)(U + (size_t)(sample ? row0 + r - (CW - 1) : sq * SEQ + i) * MIXB + 2 * cp);
;                 val[0] = __uint_as_float(raw << 16); val[1] = __uint_as_float(raw & 0xffff0000u); }
; #pragma unroll
;             for (int t = 0; t < TT; ++t) { const int j = r - t; if (j >= 0 && j < CW) acc[t] += w[j] * val; }
	v_and_b32_e32 v172, s32, v172
	v_lshlrev_b32_e32 v168, 16, v172
	v_and_b32_e32 v169, 0xffff0000, v172
	v_pk_fma_f32 v[92:93], v[6:7], v[168:169], v[92:93]
	v_pk_fma_f32 v[94:95], v[4:5], v[168:169], v[94:95]
	v_pk_fma_f32 v[138:139], v[2:3], v[168:169], v[138:139]
	v_pk_fma_f32 v[140:141], v[0:1], v[168:169], v[90:91]
	global_load_dword v172, v200, s[50:51] offset:1024
	s_waitcnt vmcnt(25)
	v_and_b32_e32 v173, s32, v173
	v_lshlrev_b32_e32 v166, 16, v173
	v_and_b32_e32 v167, 0xffff0000, v173
	v_pk_fma_f32 v[92:93], v[8:9], v[166:167], v[92:93]
	v_pk_fma_f32 v[94:95], v[6:7], v[166:167], v[94:95]
	v_pk_fma_f32 v[138:139], v[4:5], v[166:167], v[138:139]
	v_pk_fma_f32 v[140:141], v[2:3], v[166:167], v[140:141]
	v_pk_fma_f32 v[142:143], v[0:1], v[166:167], v[90:91]
	s_sub_u32 s50, s50, s61
	s_subb_u32 s51, s51, 0
	global_load_dword v173, v200, s[50:51] offset:2048
	s_waitcnt vmcnt(25)
	v_and_b32_e32 v174, s32, v174
	v_lshlrev_b32_e32 v168, 16, v174
	v_and_b32_e32 v169, 0xffff0000, v174
	v_pk_fma_f32 v[92:93], v[10:11], v[168:169], v[92:93]
	v_pk_fma_f32 v[94:95], v[8:9], v[168:169], v[94:95]
	v_pk_fma_f32 v[138:139], v[6:7], v[168:169], v[138:139]
	v_pk_fma_f32 v[140:141], v[4:5], v[168:169], v[140:141]
	v_pk_fma_f32 v[142:143], v[2:3], v[168:169], v[142:143]
	v_pk_fma_f32 v[144:145], v[0:1], v[168:169], v[90:91]
	global_load_dword v174, v200, s[50:51] offset:3072
	s_waitcnt vmcnt(25)
	v_and_b32_e32 v175, s32, v175
	v_lshlrev_b32_e32 v166, 16, v175
	v_and_b32_e32 v167, 0xffff0000, v175
	v_pk_fma_f32 v[92:93], v[12:13], v[166:167], v[92:93]
	v_pk_fma_f32 v[94:95], v[10:11], v[166:167], v[94:95]
	v_pk_fma_f32 v[138:139], v[8:9], v[166:167], v[138:139]
	v_pk_fma_f32 v[140:141], v[6:7], v[166:167], v[140:141]
	v_pk_fma_f32 v[142:143], v[4:5], v[166:167], v[142:143]
	v_pk_fma_f32 v[144:145], v[2:3], v[166:167], v[144:145]
	v_pk_fma_f32 v[146:147], v[0:1], v[166:167], v[90:91]
	s_add_u32 s50, s50, 0x1000
	s_addc_u32 s51, s51, 0
	global_load_dword v175, v200, s[50:51]
	s_waitcnt vmcnt(25)
	v_and_b32_e32 v180, s32, v180
	v_lshlrev_b32_e32 v168, 16, v180
	v_and_b32_e32 v169, 0xffff0000, v180
	v_pk_fma_f32 v[92:93], v[14:15], v[168:169], v[92:93]
	v_pk_fma_f32 v[94:95], v[12:13], v[168:169], v[94:95]
	v_pk_fma_f32 v[138:139], v[10:11], v[168:169], v[138:139]
	v_pk_fma_f32 v[140:141], v[8:9], v[168:169], v[140:141]
	v_pk_fma_f32 v[142:143], v[6:7], v[168:169], v[142:143]
	v_pk_fma_f32 v[144:145], v[4:5], v[168:169], v[144:145]
	v_pk_fma_f32 v[146:147], v[2:3], v[168:169], v[146:147]
	v_pk_fma_f32 v[148:149], v[0:1], v[168:169], v[90:91]
	global_load_dword v180, v200, s[50:51] offset:1024
	s_waitcnt vmcnt(25)
	v_and_b32_e32 v181, s32, v181
	v_lshlrev_b32_e32 v166, 16, v181
	v_and_b32_e32 v167, 0xffff0000, v181
	v_pk_fma_f32 v[92:93], v[16:17], v[166:167], v[92:93]
	v_pk_fma_f32 v[94:95], v[14:15], v[166:167], v[94:95]
	v_pk_fma_f32 v[138:139], v[12:13], v[166:167], v[138:139]
	v_pk_fma_f32 v[140:141], v[10:11], v[166:167], v[140:141]
	v_pk_fma_f32 v[142:143], v[8:9], v[166:167], v[142:143]
	v_pk_fma_f32 v[144:145], v[6:7], v[166:167], v[144:145]
	v_pk_fma_f32 v[146:147], v[4:5], v[166:167], v[146:147]
	v_pk_fma_f32 v[148:149], v[2:3], v[166:167], v[148:149]
	v_pk_fma_f32 v[150:151], v[0:1], v[166:167], v[90:91]
	global_load_dword v181, v200, s[50:51] offset:2048
	s_waitcnt vmcnt(25)
	v_and_b32_e32 v182, s32, v182
	v_lshlrev_b32_e32 v168, 16, v182
	v_and_b32_e32 v169, 0xffff0000, v182
	v_pk_fma_f32 v[92:93], v[18:19], v[168:169], v[92:93]
	v_pk_fma_f32 v[94:95], v[16:17], v[168:169], v[94:95]
	v_pk_fma_f32 v[138:139], v[14:15], v[168:169], v[138:139]
	v_pk_fma_f32 v[140:141], v[12:13], v[168:169], v[140:141]
	v_pk_fma_f32 v[142:143], v[10:11], v[168:169], v[142:143]
	v_pk_fma_f32 v[144:145], v[8:9], v[168:169], v[144:145]
	v_pk_fma_f32 v[146:147], v[6:7], v[168:169], v[146:147]
	v_pk_fma_f32 v[148:149], v[4:5], v[168:169], v[148:149]
	v_pk_fma_f32 v[150:151], v[2:3], v[168:169], v[150:151]
	v_pk_fma_f32 v[152:153], v[0:1], v[168:169], v[90:91]
	global_load_dword v182, v200, s[50:51] offset:3072
	s_waitcnt vmcnt(25)
	v_and_b32_e32 v183, s32, v183
	v_lshlrev_b32_e32 v166, 16, v183
	v_and_b32_e32 v167, 0xffff0000, v183
	v_pk_fma_f32 v[92:93], v[20:21], v[166:167], v[92:93]
	v_pk_fma_f32 v[94:95], v[18:19], v[166:167], v[94:95]
	v_pk_fma_f32 v[138:139], v[16:17], v[166:167], v[138:139]
	v_pk_fma_f32 v[140:141], v[14:15], v[166:167], v[140:141]
	v_pk_fma_f32 v[142:143], v[12:13], v[166:167], v[142:143]
	v_pk_fma_f32 v[144:145], v[10:11], v[166:167], v[144:145]
	v_pk_fma_f32 v[146:147], v[8:9], v[166:167], v[146:147]
	v_pk_fma_f32 v[148:149], v[6:7], v[166:167], v[148:149]
	v_pk_fma_f32 v[150:151], v[4:5], v[166:167], v[150:151]
	v_pk_fma_f32 v[152:153], v[2:3], v[166:167], v[152:153]
	v_pk_fma_f32 v[154:155], v[0:1], v[166:167], v[90:91]
	s_add_u32 s50, s50, 0x1000
	s_addc_u32 s51, s51, 0
	global_load_dword v183, v200, s[50:51]
	s_waitcnt vmcnt(25)
	v_and_b32_e32 v184, s32, v184
	v_lshlrev_b32_e32 v168, 16, v184
	v_and_b32_e32 v169, 0xffff0000, v184
	v_pk_fma_f32 v[92:93], v[22:23], v[168:169], v[92:93]
	v_pk_fma_f32 v[94:95], v[20:21], v[168:169], v[94:95]
	v_pk_fma_f32 v[138:139], v[18:19], v[168:169], v[138:139]
	v_pk_fma_f32 v[140:141], v[16:17], v[168:169], v[140:141]
	v_pk_fma_f32 v[142:143], v[14:15], v[168:169], v[142:143]
	v_pk_fma_f32 v[144:145], v[12:13], v[168:169], v[144:145]
	v_pk_fma_f32 v[146:147], v[10:11], v[168:169], v[146:147]
	v_pk_fma_f32 v[148:149], v[8:9], v[168:169], v[148:149]
	v_pk_fma_f32 v[150:151], v[6:7], v[168:169], v[150:151]
	v_pk_fma_f32 v[152:153], v[4:5], v[168:169], v[152:153]
	v_pk_fma_f32 v[154:155], v[2:3], v[168:169], v[154:155]
	v_pk_fma_f32 v[156:157], v[0:1], v[168:169], v[90:91]
	global_load_dword v184, v200, s[50:51] offset:1024
	s_waitcnt vmcnt(25)
; template <int TT>
; __device__ __forceinline__ void conv_pair(const Params& p, unsigned char* lds, bool sample, int tile) {
;     ...
;             else { const int i = t0 + r - (CW - 1); unsigned raw = 0u; if (sample || i >= 0) raw = *(const unsigned*)(U + (size_t)(sample ? row0 + r - (CW - 1) : sq * SEQ + i) * MIXB + 2 * cp);
;                 val[0] = __uint_as_float(raw << 16); val[1] = __uint_as_float(raw & 0xffff0000u); }
; #pragma unroll
;             for (int t = 0; t < TT; ++t) { const int j = r - t; if (j >= 0 && j < CW) acc[t] += w[j] * val; }
	v_and_b32_e32 v185, s32, v185
	v_lshlrev_b32_e32 v166, 16, v185
	v_and_b32_e32 v167, 0xffff0000, v185
	v_pk_fma_f32 v[92:93], v[24:25], v[166:167], v[92:93]
	v_pk_fma_f32 v[94:95], v[22:23], v[166:167], v[94:95]
	v_pk_fma_f32 v[138:139], v[20:21], v[166:167], v[138:139]
	v_pk_fma_f32 v[140:141], v[18:19], v[166:167], v[140:141]
	v_pk_fma_f32 v[142:143], v[16:17], v[166:167], v[142:143]
	v_pk_fma_f32 v[144:145], v[14:15], v[166:167], v[144:145]
	v_pk_fma_f32 v[146:147], v[12:13], v[166:167], v[146:147]
	v_pk_fma_f32 v[148:149], v[10:11], v[166:167], v[148:149]
	v_pk_fma_f32 v[150:151], v[8:9], v[166:167], v[150:151]
	v_pk_fma_f32 v[152:153], v[6:7], v[166:167], v[152:153]
	v_pk_fma_f32 v[154:155], v[4:5], v[166:167], v[154:155]
	v_pk_fma_f32 v[156:157], v[2:3], v[166:167], v[156:157]
	v_pk_fma_f32 v[158:159], v[0:1], v[166:167], v[90:91]
	global_load_dword v185, v200, s[50:51] offset:2048
	s_waitcnt vmcnt(25)
	v_and_b32_e32 v186, s32, v186
	v_lshlrev_b32_e32 v168, 16, v186
	v_and_b32_e32 v169, 0xffff0000, v186
	v_pk_fma_f32 v[92:93], v[26:27], v[168:169], v[92:93]
	v_pk_fma_f32 v[94:95], v[24:25], v[168:169], v[94:95]
	v_pk_fma_f32 v[138:139], v[22:23], v[168:169], v[138:139]
	v_pk_fma_f32 v[140:141], v[20:21], v[168:169], v[140:141]
	v_pk_fma_f32 v[142:143], v[18:19], v[168:169], v[142:143]
	v_pk_fma_f32 v[144:145], v[16:17], v[168:169], v[144:145]
	v_pk_fma_f32 v[146:147], v[14:15], v[168:169], v[146:147]
	v_pk_fma_f32 v[148:149], v[12:13], v[168:169], v[148:149]
	v_pk_fma_f32 v[150:151], v[10:11], v[168:169], v[150:151]
	v_pk_fma_f32 v[152:153], v[8:9], v[168:169], v[152:153]
	v_pk_fma_f32 v[154:155], v[6:7], v[168:169], v[154:155]
	v_pk_fma_f32 v[156:157], v[4:5], v[168:169], v[156:157]
	v_pk_fma_f32 v[158:159], v[2:3], v[168:169], v[158:159]
	v_pk_fma_f32 v[160:161], v[0:1], v[168:169], v[90:91]
	global_load_dword v186, v200, s[50:51] offset:3072
	s_waitcnt vmcnt(25)
	v_and_b32_e32 v187, s99, v187
	v_lshlrev_b32_e32 v166, 16, v187
	v_and_b32_e32 v167, 0xffff0000, v187
	v_pk_fma_f32 v[92:93], v[28:29], v[166:167], v[92:93]
	v_pk_fma_f32 v[94:95], v[26:27], v[166:167], v[94:95]
	v_pk_fma_f32 v[138:139], v[24:25], v[166:167], v[138:139]
	v_pk_fma_f32 v[140:141], v[22:23], v[166:167], v[140:141]
	v_pk_fma_f32 v[142:143], v[20:21], v[166:167], v[142:143]
	v_pk_fma_f32 v[144:145], v[18:19], v[166:167], v[144:145]
	v_pk_fma_f32 v[146:147], v[16:17], v[166:167], v[146:147]
	v_pk_fma_f32 v[148:149], v[14:15], v[166:167], v[148:149]
	v_pk_fma_f32 v[150:151], v[12:13], v[166:167], v[150:151]
	v_pk_fma_f32 v[152:153], v[10:11], v[166:167], v[152:153]
	v_pk_fma_f32 v[154:155], v[8:9], v[166:167], v[154:155]
	v_pk_fma_f32 v[156:157], v[6:7], v[166:167], v[156:157]
	v_pk_fma_f32 v[158:159], v[4:5], v[166:167], v[158:159]
	v_pk_fma_f32 v[160:161], v[2:3], v[166:167], v[160:161]
	v_pk_fma_f32 v[162:163], v[0:1], v[166:167], v[90:91]
	s_add_u32 s50, s50, 0x1000
	s_addc_u32 s51, s51, 0
	global_load_dword v187, v200, s[50:51]
	s_waitcnt vmcnt(25)
	v_and_b32_e32 v188, s99, v188
	v_lshlrev_b32_e32 v168, 16, v188
	v_and_b32_e32 v169, 0xffff0000, v188
	v_pk_fma_f32 v[92:93], v[30:31], v[168:169], v[92:93]
	v_pk_fma_f32 v[94:95], v[28:29], v[168:169], v[94:95]
	v_pk_fma_f32 v[138:139], v[26:27], v[168:169], v[138:139]
	v_pk_fma_f32 v[140:141], v[24:25], v[168:169], v[140:141]
	v_pk_fma_f32 v[142:143], v[22:23], v[168:169], v[142:143]
	v_pk_fma_f32 v[144:145], v[20:21], v[168:169], v[144:145]
	v_pk_fma_f32 v[146:147], v[18:19], v[168:169], v[146:147]
	v_pk_fma_f32 v[148:149], v[16:17], v[168:169], v[148:149]
	v_pk_fma_f32 v[150:151], v[14:15], v[168:169], v[150:151]
	v_pk_fma_f32 v[152:153], v[12:13], v[168:169], v[152:153]
	v_pk_fma_f32 v[154:155], v[10:11], v[168:169], v[154:155]
	v_pk_fma_f32 v[156:157], v[8:9], v[168:169], v[156:157]
	v_pk_fma_f32 v[158:159], v[6:7], v[168:169], v[158:159]
	v_pk_fma_f32 v[160:161], v[4:5], v[168:169], v[160:161]
	v_pk_fma_f32 v[162:163], v[2:3], v[168:169], v[162:163]
	v_pk_fma_f32 v[164:165], v[0:1], v[168:169], v[90:91]
	global_load_dword v188, v200, s[50:51] offset:1024
	s_waitcnt vmcnt(25)
	v_and_b32_e32 v189, s99, v189
	v_lshlrev_b32_e32 v166, 16, v189
	v_and_b32_e32 v167, 0xffff0000, v189
	v_pk_fma_f32 v[92:93], v[60:61], v[166:167], v[92:93]
	v_pk_fma_f32 v[94:95], v[30:31], v[166:167], v[94:95]
	v_pk_fma_f32 v[138:139], v[28:29], v[166:167], v[138:139]
	v_pk_fma_f32 v[140:141], v[26:27], v[166:167], v[140:141]
	v_pk_fma_f32 v[142:143], v[24:25], v[166:167], v[142:143]
	v_pk_fma_f32 v[144:145], v[22:23], v[166:167], v[144:145]
	v_pk_fma_f32 v[146:147], v[20:21], v[166:167], v[146:147]
	v_pk_fma_f32 v[148:149], v[18:19], v[166:167], v[148:149]
	v_pk_fma_f32 v[150:151], v[16:17], v[166:167], v[150:151]
	v_pk_fma_f32 v[152:153], v[14:15], v[166:167], v[152:153]
	v_pk_fma_f32 v[154:155], v[12:13], v[166:167], v[154:155]
	v_pk_fma_f32 v[156:157], v[10:11], v[166:167], v[156:157]
	v_pk_fma_f32 v[158:159], v[8:9], v[166:167], v[158:159]
	v_pk_fma_f32 v[160:161], v[6:7], v[166:167], v[160:161]
	v_pk_fma_f32 v[162:163], v[4:5], v[166:167], v[162:163]
	v_pk_fma_f32 v[164:165], v[2:3], v[166:167], v[164:165]
	global_load_dword v189, v200, s[50:51] offset:2048
	s_waitcnt vmcnt(25)
; template <int TT>
; __device__ __forceinline__ void conv_pair(const Params& p, unsigned char* lds, bool sample, int tile) {
;     ...
;             else { const int i = t0 + r - (CW - 1); unsigned raw = 0u; if (sample || i >= 0) raw = *(const unsigned*)(U + (size_t)(sample ? row0 + r - (CW - 1) : sq * SEQ + i) * MIXB + 2 * cp);
;                 val[0] = __uint_as_float(raw << 16); val[1] = __uint_as_float(raw & 0xffff0000u); }
; #pragma unroll
;             for (int t = 0; t < TT; ++t) { const int j = r - t; if (j >= 0 && j < CW) acc[t] += w[j] * val; }
	v_and_b32_e32 v190, s99, v190
	v_lshlrev_b32_e32 v168, 16, v190
	v_and_b32_e32 v169, 0xffff0000, v190
	v_pk_fma_f32 v[92:93], v[62:63], v[168:169], v[92:93]
	v_pk_fma_f32 v[94:95], v[60:61], v[168:169], v[94:95]
	v_pk_fma_f32 v[138:139], v[30:31], v[168:169], v[138:139]
	v_pk_fma_f32 v[140:141], v[28:29], v[168:169], v[140:141]
	v_pk_fma_f32 v[142:143], v[26:27], v[168:169], v[142:143]
	v_pk_fma_f32 v[144:145], v[24:25], v[168:169], v[144:145]
	v_pk_fma_f32 v[146:147], v[22:23], v[168:169], v[146:147]
	v_pk_fma_f32 v[148:149], v[20:21], v[168:169], v[148:149]
	v_pk_fma_f32 v[150:151], v[18:19], v[168:169], v[150:151]
	v_pk_fma_f32 v[152:153], v[16:17], v[168:169], v[152:153]
	v_pk_fma_f32 v[154:155], v[14:15], v[168:169], v[154:155]
	v_pk_fma_f32 v[156:157], v[12:13], v[168:169], v[156:157]
	v_pk_fma_f32 v[158:159], v[10:11], v[168:169], v[158:159]
	v_pk_fma_f32 v[160:161], v[8:9], v[168:169], v[160:161]
	v_pk_fma_f32 v[162:163], v[6:7], v[168:169], v[162:163]
	v_pk_fma_f32 v[164:165], v[4:5], v[168:169], v[164:165]
	global_load_dword v190, v200, s[50:51] offset:3072
	s_waitcnt vmcnt(25)
	v_and_b32_e32 v191, s99, v191
	v_lshlrev_b32_e32 v166, 16, v191
	v_and_b32_e32 v167, 0xffff0000, v191
	v_pk_fma_f32 v[92:93], v[64:65], v[166:167], v[92:93]
	v_pk_fma_f32 v[94:95], v[62:63], v[166:167], v[94:95]
	v_pk_fma_f32 v[138:139], v[60:61], v[166:167], v[138:139]
	v_pk_fma_f32 v[140:141], v[30:31], v[166:167], v[140:141]
	v_pk_fma_f32 v[142:143], v[28:29], v[166:167], v[142:143]
	v_pk_fma_f32 v[144:145], v[26:27], v[166:167], v[144:145]
	v_pk_fma_f32 v[146:147], v[24:25], v[166:167], v[146:147]
	v_pk_fma_f32 v[148:149], v[22:23], v[166:167], v[148:149]
	v_pk_fma_f32 v[150:151], v[20:21], v[166:167], v[150:151]
	v_pk_fma_f32 v[152:153], v[18:19], v[166:167], v[152:153]
	v_pk_fma_f32 v[154:155], v[16:17], v[166:167], v[154:155]
	v_pk_fma_f32 v[156:157], v[14:15], v[166:167], v[156:157]
	v_pk_fma_f32 v[158:159], v[12:13], v[166:167], v[158:159]
	v_pk_fma_f32 v[160:161], v[10:11], v[166:167], v[160:161]
	v_pk_fma_f32 v[162:163], v[8:9], v[166:167], v[162:163]
	v_pk_fma_f32 v[164:165], v[6:7], v[166:167], v[164:165]
	s_add_u32 s50, s50, 0x1000
	s_addc_u32 s51, s51, 0
	global_load_dword v191, v200, s[50:51]
	s_waitcnt vmcnt(25)
	v_and_b32_e32 v192, s99, v192
	v_lshlrev_b32_e32 v168, 16, v192
	v_and_b32_e32 v169, 0xffff0000, v192
	v_pk_fma_f32 v[92:93], v[66:67], v[168:169], v[92:93]
	v_pk_fma_f32 v[94:95], v[64:65], v[168:169], v[94:95]
	v_pk_fma_f32 v[138:139], v[62:63], v[168:169], v[138:139]
	v_pk_fma_f32 v[140:141], v[60:61], v[168:169], v[140:141]
	v_pk_fma_f32 v[142:143], v[30:31], v[168:169], v[142:143]
	v_pk_fma_f32 v[144:145], v[28:29], v[168:169], v[144:145]
	v_pk_fma_f32 v[146:147], v[26:27], v[168:169], v[146:147]
	v_pk_fma_f32 v[148:149], v[24:25], v[168:169], v[148:149]
	v_pk_fma_f32 v[150:151], v[22:23], v[168:169], v[150:151]
	v_pk_fma_f32 v[152:153], v[20:21], v[168:169], v[152:153]
	v_pk_fma_f32 v[154:155], v[18:19], v[168:169], v[154:155]
	v_pk_fma_f32 v[156:157], v[16:17], v[168:169], v[156:157]
	v_pk_fma_f32 v[158:159], v[14:15], v[168:169], v[158:159]
	v_pk_fma_f32 v[160:161], v[12:13], v[168:169], v[160:161]
	v_pk_fma_f32 v[162:163], v[10:11], v[168:169], v[162:163]
	v_pk_fma_f32 v[164:165], v[8:9], v[168:169], v[164:165]
	global_load_dword v192, v200, s[50:51] offset:1024
	s_waitcnt vmcnt(25)
	v_and_b32_e32 v193, s99, v193
	v_lshlrev_b32_e32 v166, 16, v193
	v_and_b32_e32 v167, 0xffff0000, v193
	v_pk_fma_f32 v[92:93], v[68:69], v[166:167], v[92:93]
	v_pk_fma_f32 v[94:95], v[66:67], v[166:167], v[94:95]
	v_pk_fma_f32 v[138:139], v[64:65], v[166:167], v[138:139]
	v_pk_fma_f32 v[140:141], v[62:63], v[166:167], v[140:141]
	v_pk_fma_f32 v[142:143], v[60:61], v[166:167], v[142:143]
	v_pk_fma_f32 v[144:145], v[30:31], v[166:167], v[144:145]
	v_pk_fma_f32 v[146:147], v[28:29], v[166:167], v[146:147]
	v_pk_fma_f32 v[148:149], v[26:27], v[166:167], v[148:149]
	v_pk_fma_f32 v[150:151], v[24:25], v[166:167], v[150:151]
	v_pk_fma_f32 v[152:153], v[22:23], v[166:167], v[152:153]
	v_pk_fma_f32 v[154:155], v[20:21], v[166:167], v[154:155]
	v_pk_fma_f32 v[156:157], v[18:19], v[166:167], v[156:157]
	v_pk_fma_f32 v[158:159], v[16:17], v[166:167], v[158:159]
	v_pk_fma_f32 v[160:161], v[14:15], v[166:167], v[160:161]
	v_pk_fma_f32 v[162:163], v[12:13], v[166:167], v[162:163]
	v_pk_fma_f32 v[164:165], v[10:11], v[166:167], v[164:165]
	s_waitcnt vmcnt(24)
	v_and_b32_e32 v194, s99, v194
	v_lshlrev_b32_e32 v168, 16, v194
	v_and_b32_e32 v169, 0xffff0000, v194
	v_pk_fma_f32 v[92:93], v[70:71], v[168:169], v[92:93]
	v_pk_fma_f32 v[94:95], v[68:69], v[168:169], v[94:95]
	v_pk_fma_f32 v[138:139], v[66:67], v[168:169], v[138:139]
	v_pk_fma_f32 v[140:141], v[64:65], v[168:169], v[140:141]
	v_pk_fma_f32 v[142:143], v[62:63], v[168:169], v[142:143]
	v_pk_fma_f32 v[144:145], v[60:61], v[168:169], v[144:145]
	v_pk_fma_f32 v[146:147], v[30:31], v[168:169], v[146:147]
	v_pk_fma_f32 v[148:149], v[28:29], v[168:169], v[148:149]
	v_pk_fma_f32 v[150:151], v[26:27], v[168:169], v[150:151]
	v_pk_fma_f32 v[152:153], v[24:25], v[168:169], v[152:153]
	v_pk_fma_f32 v[154:155], v[22:23], v[168:169], v[154:155]
	v_pk_fma_f32 v[156:157], v[20:21], v[168:169], v[156:157]
	v_pk_fma_f32 v[158:159], v[18:19], v[168:169], v[158:159]
	v_pk_fma_f32 v[160:161], v[16:17], v[168:169], v[160:161]
	v_pk_fma_f32 v[162:163], v[14:15], v[168:169], v[162:163]
	v_pk_fma_f32 v[164:165], v[12:13], v[168:169], v[164:165]
	s_waitcnt vmcnt(23)
; template <int TT>
; __device__ __forceinline__ void conv_pair(const Params& p, unsigned char* lds, bool sample, int tile) {
;     ...
;             else { const int i = t0 + r - (CW - 1); unsigned raw = 0u; if (sample || i >= 0) raw = *(const unsigned*)(U + (size_t)(sample ? row0 + r - (CW - 1) : sq * SEQ + i) * MIXB + 2 * cp);
;                 val[0] = __uint_as_float(raw << 16); val[1] = __uint_as_float(raw & 0xffff0000u); }
; #pragma unroll
;             for (int t = 0; t < TT; ++t) { const int j = r - t; if (j >= 0 && j < CW) acc[t] += w[j] * val; }
	v_and_b32_e32 v195, s99, v195
	v_lshlrev_b32_e32 v166, 16, v195
	v_and_b32_e32 v167, 0xffff0000, v195
	v_pk_fma_f32 v[92:93], v[72:73], v[166:167], v[92:93]
	v_pk_fma_f32 v[94:95], v[70:71], v[166:167], v[94:95]
	v_pk_fma_f32 v[138:139], v[68:69], v[166:167], v[138:139]
	v_pk_fma_f32 v[140:141], v[66:67], v[166:167], v[140:141]
	v_pk_fma_f32 v[142:143], v[64:65], v[166:167], v[142:143]
	v_pk_fma_f32 v[144:145], v[62:63], v[166:167], v[144:145]
	v_pk_fma_f32 v[146:147], v[60:61], v[166:167], v[146:147]
	v_pk_fma_f32 v[148:149], v[30:31], v[166:167], v[148:149]
	v_pk_fma_f32 v[150:151], v[28:29], v[166:167], v[150:151]
	v_pk_fma_f32 v[152:153], v[26:27], v[166:167], v[152:153]
	v_pk_fma_f32 v[154:155], v[24:25], v[166:167], v[154:155]
	v_pk_fma_f32 v[156:157], v[22:23], v[166:167], v[156:157]
	v_pk_fma_f32 v[158:159], v[20:21], v[166:167], v[158:159]
	v_pk_fma_f32 v[160:161], v[18:19], v[166:167], v[160:161]
	v_pk_fma_f32 v[162:163], v[16:17], v[166:167], v[162:163]
	v_pk_fma_f32 v[164:165], v[14:15], v[166:167], v[164:165]
	s_waitcnt vmcnt(22)
	v_and_b32_e32 v196, s99, v196
	v_lshlrev_b32_e32 v168, 16, v196
	v_and_b32_e32 v169, 0xffff0000, v196
	v_pk_fma_f32 v[92:93], v[74:75], v[168:169], v[92:93]
	v_pk_fma_f32 v[94:95], v[72:73], v[168:169], v[94:95]
	v_pk_fma_f32 v[138:139], v[70:71], v[168:169], v[138:139]
	v_pk_fma_f32 v[140:141], v[68:69], v[168:169], v[140:141]
	v_pk_fma_f32 v[142:143], v[66:67], v[168:169], v[142:143]
	v_pk_fma_f32 v[144:145], v[64:65], v[168:169], v[144:145]
	v_pk_fma_f32 v[146:147], v[62:63], v[168:169], v[146:147]
	v_pk_fma_f32 v[148:149], v[60:61], v[168:169], v[148:149]
	v_pk_fma_f32 v[150:151], v[30:31], v[168:169], v[150:151]
	v_pk_fma_f32 v[152:153], v[28:29], v[168:169], v[152:153]
	v_pk_fma_f32 v[154:155], v[26:27], v[168:169], v[154:155]
	v_pk_fma_f32 v[156:157], v[24:25], v[168:169], v[156:157]
	v_pk_fma_f32 v[158:159], v[22:23], v[168:169], v[158:159]
	v_pk_fma_f32 v[160:161], v[20:21], v[168:169], v[160:161]
	v_pk_fma_f32 v[162:163], v[18:19], v[168:169], v[162:163]
	v_pk_fma_f32 v[164:165], v[16:17], v[168:169], v[164:165]
	s_waitcnt vmcnt(21)
	v_and_b32_e32 v197, s99, v197
	v_lshlrev_b32_e32 v166, 16, v197
	v_and_b32_e32 v167, 0xffff0000, v197
	v_pk_fma_f32 v[92:93], v[76:77], v[166:167], v[92:93]
	v_pk_fma_f32 v[94:95], v[74:75], v[166:167], v[94:95]
	v_pk_fma_f32 v[138:139], v[72:73], v[166:167], v[138:139]
	v_pk_fma_f32 v[140:141], v[70:71], v[166:167], v[140:141]
	v_pk_fma_f32 v[142:143], v[68:69], v[166:167], v[142:143]
	v_pk_fma_f32 v[144:145], v[66:67], v[166:167], v[144:145]
	v_pk_fma_f32 v[146:147], v[64:65], v[166:167], v[146:147]
	v_pk_fma_f32 v[148:149], v[62:63], v[166:167], v[148:149]
	v_pk_fma_f32 v[150:151], v[60:61], v[166:167], v[150:151]
	v_pk_fma_f32 v[152:153], v[30:31], v[166:167], v[152:153]
	v_pk_fma_f32 v[154:155], v[28:29], v[166:167], v[154:155]
	v_pk_fma_f32 v[156:157], v[26:27], v[166:167], v[156:157]
	v_pk_fma_f32 v[158:159], v[24:25], v[166:167], v[158:159]
	v_pk_fma_f32 v[160:161], v[22:23], v[166:167], v[160:161]
	v_pk_fma_f32 v[162:163], v[20:21], v[166:167], v[162:163]
	v_pk_fma_f32 v[164:165], v[18:19], v[166:167], v[164:165]
	s_waitcnt vmcnt(20)
	v_and_b32_e32 v198, s99, v198
	v_lshlrev_b32_e32 v168, 16, v198
	v_and_b32_e32 v169, 0xffff0000, v198
	v_pk_fma_f32 v[92:93], v[78:79], v[168:169], v[92:93]
	v_pk_fma_f32 v[94:95], v[76:77], v[168:169], v[94:95]
	v_pk_fma_f32 v[138:139], v[74:75], v[168:169], v[138:139]
	v_pk_fma_f32 v[140:141], v[72:73], v[168:169], v[140:141]
	v_pk_fma_f32 v[142:143], v[70:71], v[168:169], v[142:143]
	v_pk_fma_f32 v[144:145], v[68:69], v[168:169], v[144:145]
	v_pk_fma_f32 v[146:147], v[66:67], v[168:169], v[146:147]
	v_pk_fma_f32 v[148:149], v[64:65], v[168:169], v[148:149]
	v_pk_fma_f32 v[150:151], v[62:63], v[168:169], v[150:151]
	v_pk_fma_f32 v[152:153], v[60:61], v[168:169], v[152:153]
	v_pk_fma_f32 v[154:155], v[30:31], v[168:169], v[154:155]
	v_pk_fma_f32 v[156:157], v[28:29], v[168:169], v[156:157]
	v_pk_fma_f32 v[158:159], v[26:27], v[168:169], v[158:159]
	v_pk_fma_f32 v[160:161], v[24:25], v[168:169], v[160:161]
	v_pk_fma_f32 v[162:163], v[22:23], v[168:169], v[162:163]
	v_pk_fma_f32 v[164:165], v[20:21], v[168:169], v[164:165]
	s_waitcnt vmcnt(19)
	v_and_b32_e32 v50, s99, v50
	v_lshlrev_b32_e32 v166, 16, v50
	v_and_b32_e32 v167, 0xffff0000, v50
	v_pk_fma_f32 v[92:93], v[80:81], v[166:167], v[92:93]
	v_pk_fma_f32 v[94:95], v[78:79], v[166:167], v[94:95]
	v_pk_fma_f32 v[138:139], v[76:77], v[166:167], v[138:139]
	v_pk_fma_f32 v[140:141], v[74:75], v[166:167], v[140:141]
	v_pk_fma_f32 v[142:143], v[72:73], v[166:167], v[142:143]
	v_pk_fma_f32 v[144:145], v[70:71], v[166:167], v[144:145]
	v_pk_fma_f32 v[146:147], v[68:69], v[166:167], v[146:147]
	v_pk_fma_f32 v[148:149], v[66:67], v[166:167], v[148:149]
	v_pk_fma_f32 v[150:151], v[64:65], v[166:167], v[150:151]
	v_pk_fma_f32 v[152:153], v[62:63], v[166:167], v[152:153]
	v_pk_fma_f32 v[154:155], v[60:61], v[166:167], v[154:155]
	v_pk_fma_f32 v[156:157], v[30:31], v[166:167], v[156:157]
	v_pk_fma_f32 v[158:159], v[28:29], v[166:167], v[158:159]
	v_pk_fma_f32 v[160:161], v[26:27], v[166:167], v[160:161]
	v_pk_fma_f32 v[162:163], v[24:25], v[166:167], v[162:163]
	v_pk_fma_f32 v[164:165], v[22:23], v[166:167], v[164:165]
	s_waitcnt vmcnt(18)
; template <int TT>
; __device__ __forceinline__ void conv_pair(const Params& p, unsigned char* lds, bool sample, int tile) {
;     ...
;             else { const int i = t0 + r - (CW - 1); unsigned raw = 0u; if (sample || i >= 0) raw = *(const unsigned*)(U + (size_t)(sample ? row0 + r - (CW - 1) : sq * SEQ + i) * MIXB + 2 * cp);
;                 val[0] = __uint_as_float(raw << 16); val[1] = __uint_as_float(raw & 0xffff0000u); }
; #pragma unroll
;             for (int t = 0; t < TT; ++t) { const int j = r - t; if (j >= 0 && j < CW) acc[t] += w[j] * val; }
	v_and_b32_e32 v170, s99, v170
	v_lshlrev_b32_e32 v168, 16, v170
	v_and_b32_e32 v169, 0xffff0000, v170
	v_pk_fma_f32 v[92:93], v[82:83], v[168:169], v[92:93]
	v_pk_fma_f32 v[94:95], v[80:81], v[168:169], v[94:95]
	v_pk_fma_f32 v[138:139], v[78:79], v[168:169], v[138:139]
	v_pk_fma_f32 v[140:141], v[76:77], v[168:169], v[140:141]
	v_pk_fma_f32 v[142:143], v[74:75], v[168:169], v[142:143]
	v_pk_fma_f32 v[144:145], v[72:73], v[168:169], v[144:145]
	v_pk_fma_f32 v[146:147], v[70:71], v[168:169], v[146:147]
	v_pk_fma_f32 v[148:149], v[68:69], v[168:169], v[148:149]
	v_pk_fma_f32 v[150:151], v[66:67], v[168:169], v[150:151]
	v_pk_fma_f32 v[152:153], v[64:65], v[168:169], v[152:153]
	v_pk_fma_f32 v[154:155], v[62:63], v[168:169], v[154:155]
	v_pk_fma_f32 v[156:157], v[60:61], v[168:169], v[156:157]
	v_pk_fma_f32 v[158:159], v[30:31], v[168:169], v[158:159]
	v_pk_fma_f32 v[160:161], v[28:29], v[168:169], v[160:161]
	v_pk_fma_f32 v[162:163], v[26:27], v[168:169], v[162:163]
	v_pk_fma_f32 v[164:165], v[24:25], v[168:169], v[164:165]
	s_waitcnt vmcnt(17)
	v_and_b32_e32 v171, s99, v171
	v_lshlrev_b32_e32 v166, 16, v171
	v_and_b32_e32 v167, 0xffff0000, v171
	v_pk_fma_f32 v[92:93], v[84:85], v[166:167], v[92:93]
	v_pk_fma_f32 v[94:95], v[82:83], v[166:167], v[94:95]
	v_pk_fma_f32 v[138:139], v[80:81], v[166:167], v[138:139]
	v_pk_fma_f32 v[140:141], v[78:79], v[166:167], v[140:141]
	v_pk_fma_f32 v[142:143], v[76:77], v[166:167], v[142:143]
	v_pk_fma_f32 v[144:145], v[74:75], v[166:167], v[144:145]
	v_pk_fma_f32 v[146:147], v[72:73], v[166:167], v[146:147]
	v_pk_fma_f32 v[148:149], v[70:71], v[166:167], v[148:149]
	v_pk_fma_f32 v[150:151], v[68:69], v[166:167], v[150:151]
	v_pk_fma_f32 v[152:153], v[66:67], v[166:167], v[152:153]
	v_pk_fma_f32 v[154:155], v[64:65], v[166:167], v[154:155]
	v_pk_fma_f32 v[156:157], v[62:63], v[166:167], v[156:157]
	v_pk_fma_f32 v[158:159], v[60:61], v[166:167], v[158:159]
	v_pk_fma_f32 v[160:161], v[30:31], v[166:167], v[160:161]
	v_pk_fma_f32 v[162:163], v[28:29], v[166:167], v[162:163]
	v_pk_fma_f32 v[164:165], v[26:27], v[166:167], v[164:165]
	s_waitcnt vmcnt(16)
	v_and_b32_e32 v172, s99, v172
	v_lshlrev_b32_e32 v168, 16, v172
	v_and_b32_e32 v169, 0xffff0000, v172
	v_pk_fma_f32 v[92:93], v[86:87], v[168:169], v[92:93]
	v_pk_fma_f32 v[94:95], v[84:85], v[168:169], v[94:95]
	v_pk_fma_f32 v[138:139], v[82:83], v[168:169], v[138:139]
	v_pk_fma_f32 v[140:141], v[80:81], v[168:169], v[140:141]
	v_pk_fma_f32 v[142:143], v[78:79], v[168:169], v[142:143]
	v_pk_fma_f32 v[144:145], v[76:77], v[168:169], v[144:145]
	v_pk_fma_f32 v[146:147], v[74:75], v[168:169], v[146:147]
	v_pk_fma_f32 v[148:149], v[72:73], v[168:169], v[148:149]
	v_pk_fma_f32 v[150:151], v[70:71], v[168:169], v[150:151]
	v_pk_fma_f32 v[152:153], v[68:69], v[168:169], v[152:153]
	v_pk_fma_f32 v[154:155], v[66:67], v[168:169], v[154:155]
	v_pk_fma_f32 v[156:157], v[64:65], v[168:169], v[156:157]
	v_pk_fma_f32 v[158:159], v[62:63], v[168:169], v[158:159]
	v_pk_fma_f32 v[160:161], v[60:61], v[168:169], v[160:161]
	v_pk_fma_f32 v[162:163], v[30:31], v[168:169], v[162:163]
	v_pk_fma_f32 v[164:165], v[28:29], v[168:169], v[164:165]
	s_waitcnt vmcnt(15)
	v_lshlrev_b32_e32 v166, 16, v173
	v_and_b32_e32 v167, 0xffff0000, v173
	v_pk_fma_f32 v[92:93], v[88:89], v[166:167], v[92:93]
	v_pk_fma_f32 v[94:95], v[86:87], v[166:167], v[94:95]
	v_pk_fma_f32 v[138:139], v[84:85], v[166:167], v[138:139]
	v_pk_fma_f32 v[140:141], v[82:83], v[166:167], v[140:141]
	v_pk_fma_f32 v[142:143], v[80:81], v[166:167], v[142:143]
	v_pk_fma_f32 v[144:145], v[78:79], v[166:167], v[144:145]
	v_pk_fma_f32 v[146:147], v[76:77], v[166:167], v[146:147]
	v_pk_fma_f32 v[148:149], v[74:75], v[166:167], v[148:149]
	v_pk_fma_f32 v[150:151], v[72:73], v[166:167], v[150:151]
	v_pk_fma_f32 v[152:153], v[70:71], v[166:167], v[152:153]
	v_pk_fma_f32 v[154:155], v[68:69], v[166:167], v[154:155]
	v_pk_fma_f32 v[156:157], v[66:67], v[166:167], v[156:157]
	v_pk_fma_f32 v[158:159], v[64:65], v[166:167], v[158:159]
	v_pk_fma_f32 v[160:161], v[62:63], v[166:167], v[160:161]
	v_pk_fma_f32 v[162:163], v[60:61], v[166:167], v[162:163]
	v_pk_fma_f32 v[164:165], v[30:31], v[166:167], v[164:165]
	s_waitcnt vmcnt(14)
	v_lshlrev_b32_e32 v168, 16, v174
	v_and_b32_e32 v169, 0xffff0000, v174
	v_pk_fma_f32 v[94:95], v[88:89], v[168:169], v[94:95]
	v_pk_fma_f32 v[138:139], v[86:87], v[168:169], v[138:139]
	v_pk_fma_f32 v[140:141], v[84:85], v[168:169], v[140:141]
	v_pk_fma_f32 v[142:143], v[82:83], v[168:169], v[142:143]
	v_pk_fma_f32 v[144:145], v[80:81], v[168:169], v[144:145]
	v_pk_fma_f32 v[146:147], v[78:79], v[168:169], v[146:147]
	v_pk_fma_f32 v[148:149], v[76:77], v[168:169], v[148:149]
	v_pk_fma_f32 v[150:151], v[74:75], v[168:169], v[150:151]
	v_pk_fma_f32 v[152:153], v[72:73], v[168:169], v[152:153]
	v_pk_fma_f32 v[154:155], v[70:71], v[168:169], v[154:155]
	v_pk_fma_f32 v[156:157], v[68:69], v[168:169], v[156:157]
	v_pk_fma_f32 v[158:159], v[66:67], v[168:169], v[158:159]
	v_pk_fma_f32 v[160:161], v[64:65], v[168:169], v[160:161]
	v_pk_fma_f32 v[162:163], v[62:63], v[168:169], v[162:163]
	v_pk_fma_f32 v[164:165], v[60:61], v[168:169], v[164:165]
	s_waitcnt vmcnt(13)
; template <int TT>
; __device__ __forceinline__ void conv_pair(const Params& p, unsigned char* lds, bool sample, int tile) {
;     ...
;             else { const int i = t0 + r - (CW - 1); unsigned raw = 0u; if (sample || i >= 0) raw = *(const unsigned*)(U + (size_t)(sample ? row0 + r - (CW - 1) : sq * SEQ + i) * MIXB + 2 * cp);
;                 val[0] = __uint_as_float(raw << 16); val[1] = __uint_as_float(raw & 0xffff0000u); }
; #pragma unroll
;             for (int t = 0; t < TT; ++t) { const int j = r - t; if (j >= 0 && j < CW) acc[t] += w[j] * val; }
	v_lshlrev_b32_e32 v166, 16, v175
	v_and_b32_e32 v167, 0xffff0000, v175
	v_pk_fma_f32 v[138:139], v[88:89], v[166:167], v[138:139]
	v_pk_fma_f32 v[140:141], v[86:87], v[166:167], v[140:141]
	v_pk_fma_f32 v[142:143], v[84:85], v[166:167], v[142:143]
	v_pk_fma_f32 v[144:145], v[82:83], v[166:167], v[144:145]
	v_pk_fma_f32 v[146:147], v[80:81], v[166:167], v[146:147]
	v_pk_fma_f32 v[148:149], v[78:79], v[166:167], v[148:149]
	v_pk_fma_f32 v[150:151], v[76:77], v[166:167], v[150:151]
	v_pk_fma_f32 v[152:153], v[74:75], v[166:167], v[152:153]
	v_pk_fma_f32 v[154:155], v[72:73], v[166:167], v[154:155]
	v_pk_fma_f32 v[156:157], v[70:71], v[166:167], v[156:157]
	v_pk_fma_f32 v[158:159], v[68:69], v[166:167], v[158:159]
	v_pk_fma_f32 v[160:161], v[66:67], v[166:167], v[160:161]
	v_pk_fma_f32 v[162:163], v[64:65], v[166:167], v[162:163]
	v_pk_fma_f32 v[164:165], v[62:63], v[166:167], v[164:165]
	s_waitcnt vmcnt(12)
	v_lshlrev_b32_e32 v168, 16, v180
	v_and_b32_e32 v169, 0xffff0000, v180
	v_pk_fma_f32 v[140:141], v[88:89], v[168:169], v[140:141]
	v_pk_fma_f32 v[142:143], v[86:87], v[168:169], v[142:143]
	v_pk_fma_f32 v[144:145], v[84:85], v[168:169], v[144:145]
	v_pk_fma_f32 v[146:147], v[82:83], v[168:169], v[146:147]
	v_pk_fma_f32 v[148:149], v[80:81], v[168:169], v[148:149]
	v_pk_fma_f32 v[150:151], v[78:79], v[168:169], v[150:151]
	v_pk_fma_f32 v[152:153], v[76:77], v[168:169], v[152:153]
	v_pk_fma_f32 v[154:155], v[74:75], v[168:169], v[154:155]
	v_pk_fma_f32 v[156:157], v[72:73], v[168:169], v[156:157]
	v_pk_fma_f32 v[158:159], v[70:71], v[168:169], v[158:159]
	v_pk_fma_f32 v[160:161], v[68:69], v[168:169], v[160:161]
	v_pk_fma_f32 v[162:163], v[66:67], v[168:169], v[162:163]
	v_pk_fma_f32 v[164:165], v[64:65], v[168:169], v[164:165]
	s_waitcnt vmcnt(11)
	v_lshlrev_b32_e32 v166, 16, v181
	v_and_b32_e32 v167, 0xffff0000, v181
	v_pk_fma_f32 v[142:143], v[88:89], v[166:167], v[142:143]
	v_pk_fma_f32 v[144:145], v[86:87], v[166:167], v[144:145]
	v_pk_fma_f32 v[146:147], v[84:85], v[166:167], v[146:147]
	v_pk_fma_f32 v[148:149], v[82:83], v[166:167], v[148:149]
	v_pk_fma_f32 v[150:151], v[80:81], v[166:167], v[150:151]
	v_pk_fma_f32 v[152:153], v[78:79], v[166:167], v[152:153]
	v_pk_fma_f32 v[154:155], v[76:77], v[166:167], v[154:155]
	v_pk_fma_f32 v[156:157], v[74:75], v[166:167], v[156:157]
	v_pk_fma_f32 v[158:159], v[72:73], v[166:167], v[158:159]
	v_pk_fma_f32 v[160:161], v[70:71], v[166:167], v[160:161]
	v_pk_fma_f32 v[162:163], v[68:69], v[166:167], v[162:163]
	v_pk_fma_f32 v[164:165], v[66:67], v[166:167], v[164:165]
	s_waitcnt vmcnt(10)
	v_lshlrev_b32_e32 v168, 16, v182
	v_and_b32_e32 v169, 0xffff0000, v182
	v_pk_fma_f32 v[144:145], v[88:89], v[168:169], v[144:145]
	v_pk_fma_f32 v[146:147], v[86:87], v[168:169], v[146:147]
	v_pk_fma_f32 v[148:149], v[84:85], v[168:169], v[148:149]
	v_pk_fma_f32 v[150:151], v[82:83], v[168:169], v[150:151]
	v_pk_fma_f32 v[152:153], v[80:81], v[168:169], v[152:153]
	v_pk_fma_f32 v[154:155], v[78:79], v[168:169], v[154:155]
	v_pk_fma_f32 v[156:157], v[76:77], v[168:169], v[156:157]
	v_pk_fma_f32 v[158:159], v[74:75], v[168:169], v[158:159]
	v_pk_fma_f32 v[160:161], v[72:73], v[168:169], v[160:161]
	v_pk_fma_f32 v[162:163], v[70:71], v[168:169], v[162:163]
	v_pk_fma_f32 v[164:165], v[68:69], v[168:169], v[164:165]
	s_waitcnt vmcnt(9)
	v_lshlrev_b32_e32 v166, 16, v183
	v_and_b32_e32 v167, 0xffff0000, v183
	v_pk_fma_f32 v[146:147], v[88:89], v[166:167], v[146:147]
	v_pk_fma_f32 v[148:149], v[86:87], v[166:167], v[148:149]
	v_pk_fma_f32 v[150:151], v[84:85], v[166:167], v[150:151]
	v_pk_fma_f32 v[152:153], v[82:83], v[166:167], v[152:153]
	v_pk_fma_f32 v[154:155], v[80:81], v[166:167], v[154:155]
	v_pk_fma_f32 v[156:157], v[78:79], v[166:167], v[156:157]
	v_pk_fma_f32 v[158:159], v[76:77], v[166:167], v[158:159]
	v_pk_fma_f32 v[160:161], v[74:75], v[166:167], v[160:161]
	v_pk_fma_f32 v[162:163], v[72:73], v[166:167], v[162:163]
	v_pk_fma_f32 v[164:165], v[70:71], v[166:167], v[164:165]
	s_waitcnt vmcnt(8)
	v_lshlrev_b32_e32 v168, 16, v184
	v_and_b32_e32 v169, 0xffff0000, v184
	v_pk_fma_f32 v[148:149], v[88:89], v[168:169], v[148:149]
	v_pk_fma_f32 v[150:151], v[86:87], v[168:169], v[150:151]
	v_pk_fma_f32 v[152:153], v[84:85], v[168:169], v[152:153]
	v_pk_fma_f32 v[154:155], v[82:83], v[168:169], v[154:155]
	v_pk_fma_f32 v[156:157], v[80:81], v[168:169], v[156:157]
	v_pk_fma_f32 v[158:159], v[78:79], v[168:169], v[158:159]
	v_pk_fma_f32 v[160:161], v[76:77], v[168:169], v[160:161]
	v_pk_fma_f32 v[162:163], v[74:75], v[168:169], v[162:163]
	v_pk_fma_f32 v[164:165], v[72:73], v[168:169], v[164:165]
	s_waitcnt vmcnt(7)
	v_lshlrev_b32_e32 v166, 16, v185
	v_and_b32_e32 v167, 0xffff0000, v185
	v_pk_fma_f32 v[150:151], v[88:89], v[166:167], v[150:151]
	v_pk_fma_f32 v[152:153], v[86:87], v[166:167], v[152:153]
	v_pk_fma_f32 v[154:155], v[84:85], v[166:167], v[154:155]
	v_pk_fma_f32 v[156:157], v[82:83], v[166:167], v[156:157]
	v_pk_fma_f32 v[158:159], v[80:81], v[166:167], v[158:159]
	v_pk_fma_f32 v[160:161], v[78:79], v[166:167], v[160:161]
	v_pk_fma_f32 v[162:163], v[76:77], v[166:167], v[162:163]
	v_pk_fma_f32 v[164:165], v[74:75], v[166:167], v[164:165]
	s_waitcnt vmcnt(6)
	v_lshlrev_b32_e32 v168, 16, v186
	v_and_b32_e32 v169, 0xffff0000, v186
	v_pk_fma_f32 v[152:153], v[88:89], v[168:169], v[152:153]
	v_pk_fma_f32 v[154:155], v[86:87], v[168:169], v[154:155]
	v_pk_fma_f32 v[156:157], v[84:85], v[168:169], v[156:157]
	v_pk_fma_f32 v[158:159], v[82:83], v[168:169], v[158:159]
	v_pk_fma_f32 v[160:161], v[80:81], v[168:169], v[160:161]
	v_pk_fma_f32 v[162:163], v[78:79], v[168:169], v[162:163]
	v_pk_fma_f32 v[164:165], v[76:77], v[168:169], v[164:165]
	s_waitcnt vmcnt(5)
; #define LDS_BARRIER() do { asm volatile("s_waitcnt lgkmcnt(0)" ::: "memory"); __builtin_amdgcn_s_barrier(); asm volatile("" ::: "memory"); } while (0)
; template <int TT>
; __device__ __forceinline__ void conv_pair(const Params& p, unsigned char* lds, bool sample, int tile) {
;     ...
;             for (int t = 0; t < TT; ++t) { const int j = r - t; if (j >= 0 && j < CW) acc[t] += w[j] * val; }
;         }
; #pragma unroll
;         for (int t = 0; t < TT; ++t) *(f32x2v*)(zb + t * MIXB + 2 * cp) = acc[t];
;     }
;     LDS_BARRIER();
;     if (tile >= 0) {
; #pragma unroll
;         for (int tt = 0; tt < TT / 4; ++tt) { const int t = wq * (TT / 4) + tt;
;             const f32x4 z0 = *(const f32x4*)(zb + t * MIXB + 8 * lane), z1 = *(const f32x4*)(zb + t * MIXB + 8 * lane + 4);
;             const float s1 = wave_sum((z0[0] + z0[1]) + (z0[2] + z0[3]) + (z1[0] + z1[1]) + (z1[2] + z1[3]));
	v_lshlrev_b32_e32 v166, 16, v187
	v_and_b32_e32 v167, 0xffff0000, v187
	v_pk_fma_f32 v[154:155], v[88:89], v[166:167], v[154:155]
	v_pk_fma_f32 v[156:157], v[86:87], v[166:167], v[156:157]
	v_pk_fma_f32 v[158:159], v[84:85], v[166:167], v[158:159]
	v_pk_fma_f32 v[160:161], v[82:83], v[166:167], v[160:161]
	v_pk_fma_f32 v[162:163], v[80:81], v[166:167], v[162:163]
	v_pk_fma_f32 v[164:165], v[78:79], v[166:167], v[164:165]
	s_waitcnt vmcnt(4)
	v_lshlrev_b32_e32 v168, 16, v188
	v_and_b32_e32 v169, 0xffff0000, v188
	v_pk_fma_f32 v[156:157], v[88:89], v[168:169], v[156:157]
	v_pk_fma_f32 v[158:159], v[86:87], v[168:169], v[158:159]
	v_pk_fma_f32 v[160:161], v[84:85], v[168:169], v[160:161]
	v_pk_fma_f32 v[162:163], v[82:83], v[168:169], v[162:163]
	v_pk_fma_f32 v[164:165], v[80:81], v[168:169], v[164:165]
	s_waitcnt vmcnt(3)
	v_lshlrev_b32_e32 v166, 16, v189
	v_and_b32_e32 v167, 0xffff0000, v189
	v_pk_fma_f32 v[158:159], v[88:89], v[166:167], v[158:159]
	v_pk_fma_f32 v[160:161], v[86:87], v[166:167], v[160:161]
	v_pk_fma_f32 v[162:163], v[84:85], v[166:167], v[162:163]
	v_pk_fma_f32 v[164:165], v[82:83], v[166:167], v[164:165]
	s_waitcnt vmcnt(2)
	v_lshlrev_b32_e32 v168, 16, v190
	v_and_b32_e32 v169, 0xffff0000, v190
	v_pk_fma_f32 v[160:161], v[88:89], v[168:169], v[160:161]
	v_pk_fma_f32 v[162:163], v[86:87], v[168:169], v[162:163]
	v_pk_fma_f32 v[164:165], v[84:85], v[168:169], v[164:165]
	s_waitcnt vmcnt(1)
	v_lshlrev_b32_e32 v166, 16, v191
	v_and_b32_e32 v167, 0xffff0000, v191
	v_pk_fma_f32 v[162:163], v[88:89], v[166:167], v[162:163]
	v_pk_fma_f32 v[164:165], v[86:87], v[166:167], v[164:165]
	s_waitcnt vmcnt(0)
	v_lshlrev_b32_e32 v168, 16, v192
	v_and_b32_e32 v169, 0xffff0000, v192
	v_pk_fma_f32 v[164:165], v[88:89], v[168:169], v[164:165]
	v_lshlrev_b32_e32 v202, 5, v206
	global_load_dwordx4 v[32:35], v202, s[76:77]
	global_load_dwordx4 v[36:39], v202, s[76:77] offset:16
	global_load_dwordx4 v[40:43], v202, s[78:79]
	global_load_dwordx4 v[44:47], v202, s[78:79] offset:16
	ds_write_b64 v201, v[92:93]
	ds_write_b64 v201, v[94:95] offset:2048
	ds_write_b64 v201, v[138:139] offset:4096
	ds_write_b64 v201, v[140:141] offset:6144
	ds_write_b64 v201, v[142:143] offset:8192
	ds_write_b64 v201, v[144:145] offset:10240
	ds_write_b64 v201, v[146:147] offset:12288
	ds_write_b64 v201, v[148:149] offset:14336
	ds_write_b64 v201, v[150:151] offset:16384
	ds_write_b64 v201, v[152:153] offset:18432
	ds_write_b64 v201, v[154:155] offset:20480
	ds_write_b64 v201, v[156:157] offset:22528
	ds_write_b64 v201, v[158:159] offset:24576
	ds_write_b64 v201, v[160:161] offset:26624
	ds_write_b64 v201, v[162:163] offset:28672
	ds_write_b64 v201, v[164:165] offset:30720
	s_waitcnt lgkmcnt(0)
	s_barrier
	v_lshrrev_b32_e32 v91, 6, v176
	v_readfirstlane_b32 s46, v176
	v_lshlrev_b32_e32 v91, 13, v91
	v_lshl_add_u32 v91, v206, 5, v91
	v_readlane_b32 s56, v247, 38
	v_readlane_b32 s57, v247, 39
	ds_read_b128 v[0:3], v91
	ds_read_b128 v[4:7], v91 offset:16
	ds_read_b128 v[8:11], v91 offset:2048
	ds_read_b128 v[12:15], v91 offset:2064
	ds_read_b128 v[16:19], v91 offset:4096
	ds_read_b128 v[20:23], v91 offset:4112
	ds_read_b128 v[24:27], v91 offset:6144
	ds_read_b128 v[28:31], v91 offset:6160
	s_lshr_b32 s46, s46, 6
	s_and_b32 s46, s46, 3
	s_lshl_b32 s46, s46, 2
	s_add_u32 s46, s46, s47
	s_lshl_b32 s46, s46, 11
	s_add_u32 s56, s56, s46
	s_addc_u32 s57, s57, 0
	s_add_u32 s56, s56, 0x96f6200
	s_addc_u32 s57, s57, 0
	v_mov_b32_e32 v92, 0x358637bd
	v_lshlrev_b32_e32 v93, 4, v206
	s_waitcnt lgkmcnt(6)
	v_add_f32_e32 v50, v0, v1
	v_add_f32_e32 v83, v2, v3
	v_add_f32_e32 v84, v4, v5
	v_add_f32_e32 v50, v50, v83
	v_add_f32_e32 v83, v6, v7
	v_add_f32_e32 v50, v50, v84
	v_add_f32_e32 v50, v50, v83
	s_waitcnt lgkmcnt(4)
	v_add_f32_e32 v80, v8, v9
	v_add_f32_e32 v85, v10, v11
	v_add_f32_e32 v86, v12, v13
	v_add_f32_e32 v80, v80, v85
	v_add_f32_e32 v85, v14, v15
	v_add_f32_e32 v80, v80, v86
	v_add_f32_e32 v80, v80, v85
	s_waitcnt lgkmcnt(2)
	v_add_f32_e32 v81, v16, v17
	v_add_f32_e32 v87, v18, v19
	v_add_f32_e32 v88, v20, v21
	v_add_f32_e32 v81, v81, v87
	v_add_f32_e32 v87, v22, v23
	v_add_f32_e32 v81, v81, v88
	v_add_f32_e32 v81, v81, v87
	s_waitcnt lgkmcnt(0)
	v_add_f32_e32 v82, v24, v25
	v_add_f32_e32 v89, v26, v27
	v_add_f32_e32 v90, v28, v29
	v_add_f32_e32 v82, v82, v89
	v_add_f32_e32 v89, v30, v31
	v_add_f32_e32 v82, v82, v90
	v_add_f32_e32 v82, v82, v89
	v_add_f32_dpp v50, v50, v50 quad_perm:[1,0,3,2] row_mask:0xf bank_mask:0xf bound_ctrl:1
	v_add_f32_dpp v80, v80, v80 quad_perm:[1,0,3,2] row_mask:0xf bank_mask:0xf bound_ctrl:1
	v_add_f32_dpp v81, v81, v81 quad_perm:[1,0,3,2] row_mask:0xf bank_mask:0xf bound_ctrl:1
	v_add_f32_dpp v82, v82, v82 quad_perm:[1,0,3,2] row_mask:0xf bank_mask:0xf bound_ctrl:1
	v_add_f32_dpp v50, v50, v50 quad_perm:[2,3,0,1] row_mask:0xf bank_mask:0xf bound_ctrl:1
	v_add_f32_dpp v80, v80, v80 quad_perm:[2,3,0,1] row_mask:0xf bank_mask:0xf bound_ctrl:1
	v_add_f32_dpp v81, v81, v81 quad_perm:[2,3,0,1] row_mask:0xf bank_mask:0xf bound_ctrl:1
	v_add_f32_dpp v82, v82, v82 quad_perm:[2,3,0,1] row_mask:0xf bank_mask:0xf bound_ctrl:1
	v_add_f32_dpp v50, v50, v50 row_half_mirror row_mask:0xf bank_mask:0xf bound_ctrl:1
	v_add_f32_dpp v80, v80, v80 row_half_mirror row_mask:0xf bank_mask:0xf bound_ctrl:1
	v_add_f32_dpp v81, v81, v81 row_half_mirror row_mask:0xf bank_mask:0xf bound_ctrl:1
	v_add_f32_dpp v82, v82, v82 row_half_mirror row_mask:0xf bank_mask:0xf bound_ctrl:1
	v_add_f32_dpp v50, v50, v50 row_mirror row_mask:0xf bank_mask:0xf bound_ctrl:1
	v_add_f32_dpp v80, v80, v80 row_mirror row_mask:0xf bank_mask:0xf bound_ctrl:1
; template <int CTRL> __device__ __forceinline__ float dpp_step(float t) { return t + __builtin_bit_cast(float, __builtin_amdgcn_update_dpp(0, __builtin_bit_cast(int, t), CTRL, 0xF, 0xF, true)); }
; __device__ __forceinline__ float wave_sum(float v) {
;     float t = dpp_step<0xB1>(v);
;     t = dpp_step<0x4E>(t);
;     t = dpp_step<0x141>(t);
;     t = dpp_step<0x140>(t);
;     const int ti = __builtin_bit_cast(int, t);
;     return (__builtin_bit_cast(float, __builtin_amdgcn_readlane(ti, 0)) + __builtin_bit_cast(float, __builtin_amdgcn_readlane(ti, 16)))
;          + (__builtin_bit_cast(float, __builtin_amdgcn_readlane(ti, 32)) + __builtin_bit_cast(float, __builtin_amdgcn_readlane(ti, 48)));
; template <int TT>
; __device__ __forceinline__ void conv_pair(const Params& p, unsigned char* lds, bool sample, int tile) {
;     ...
;             const float s1 = wave_sum((z0[0] + z0[1]) + (z0[2] + z0[3]) + (z1[0] + z1[1]) + (z1[2] + z1[3]));
;             const float mu = s1 * (1.0f / MIXB); const f32x4 d0 = z0 - mu, d1 = z1 - mu;
;             const float s2 = wave_sum((d0[0] * d0[0] + d0[1] * d0[1]) + (d0[2] * d0[2] + d0[3] * d0[3]) + (d1[0] * d1[0] + d1[1] * d1[1]) + (d1[2] * d1[2] + d1[3] * d1[3]));
;             const float rstd = rsqrtf(s2 * (1.0f / MIXB) + EPS);
	v_add_f32_dpp v81, v81, v81 row_mirror row_mask:0xf bank_mask:0xf bound_ctrl:1
	v_add_f32_dpp v82, v82, v82 row_mirror row_mask:0xf bank_mask:0xf bound_ctrl:1
	s_nop 0
	v_readlane_b32 s46, v50, 0
	v_readlane_b32 s50, v50, 16
	v_readlane_b32 s51, v50, 32
	v_readlane_b32 s54, v50, 48
	v_readlane_b32 s55, v80, 0
	v_readlane_b32 s60, v80, 16
	v_readlane_b32 s61, v80, 32
	v_readlane_b32 s32, v80, 48
	v_mov_b32_e32 v83, s50
	v_mov_b32_e32 v84, s54
	v_add_f32_e32 v83, s46, v83
	v_add_f32_e32 v84, s51, v84
	v_add_f32_e32 v50, v83, v84
	v_mov_b32_e32 v85, s60
	v_mov_b32_e32 v86, s32
	v_add_f32_e32 v85, s55, v85
	v_add_f32_e32 v86, s61, v86
	v_add_f32_e32 v80, v85, v86
	s_nop 0
	v_readlane_b32 s46, v81, 0
	v_readlane_b32 s50, v81, 16
	v_readlane_b32 s51, v81, 32
	v_readlane_b32 s54, v81, 48
	v_readlane_b32 s55, v82, 0
	v_readlane_b32 s60, v82, 16
	v_readlane_b32 s61, v82, 32
	v_readlane_b32 s32, v82, 48
	v_mov_b32_e32 v87, s50
	v_mov_b32_e32 v88, s54
	v_add_f32_e32 v87, s46, v87
	v_add_f32_e32 v88, s51, v88
	v_add_f32_e32 v81, v87, v88
	v_mov_b32_e32 v89, s60
	v_mov_b32_e32 v90, s32
	v_add_f32_e32 v89, s55, v89
	v_add_f32_e32 v90, s61, v90
	v_add_f32_e32 v82, v89, v90
	v_fmamk_f32 v0, v50, 0xbb000000, v0
	v_fmamk_f32 v1, v50, 0xbb000000, v1
	v_fmamk_f32 v2, v50, 0xbb000000, v2
	v_fmamk_f32 v3, v50, 0xbb000000, v3
	v_fmamk_f32 v4, v50, 0xbb000000, v4
	v_fmamk_f32 v5, v50, 0xbb000000, v5
	v_fmamk_f32 v6, v50, 0xbb000000, v6
	v_fmamk_f32 v7, v50, 0xbb000000, v7
	v_fmamk_f32 v8, v80, 0xbb000000, v8
	v_fmamk_f32 v9, v80, 0xbb000000, v9
	v_fmamk_f32 v10, v80, 0xbb000000, v10
	v_fmamk_f32 v11, v80, 0xbb000000, v11
	v_fmamk_f32 v12, v80, 0xbb000000, v12
	v_fmamk_f32 v13, v80, 0xbb000000, v13
	v_fmamk_f32 v14, v80, 0xbb000000, v14
	v_fmamk_f32 v15, v80, 0xbb000000, v15
	v_fmamk_f32 v16, v81, 0xbb000000, v16
	v_fmamk_f32 v17, v81, 0xbb000000, v17
	v_fmamk_f32 v18, v81, 0xbb000000, v18
	v_fmamk_f32 v19, v81, 0xbb000000, v19
	v_fmamk_f32 v20, v81, 0xbb000000, v20
	v_fmamk_f32 v21, v81, 0xbb000000, v21
	v_fmamk_f32 v22, v81, 0xbb000000, v22
	v_fmamk_f32 v23, v81, 0xbb000000, v23
	v_fmamk_f32 v24, v82, 0xbb000000, v24
	v_fmamk_f32 v25, v82, 0xbb000000, v25
	v_fmamk_f32 v26, v82, 0xbb000000, v26
	v_fmamk_f32 v27, v82, 0xbb000000, v27
	v_fmamk_f32 v28, v82, 0xbb000000, v28
	v_fmamk_f32 v29, v82, 0xbb000000, v29
	v_fmamk_f32 v30, v82, 0xbb000000, v30
	v_fmamk_f32 v31, v82, 0xbb000000, v31
	v_pk_mul_f32 v[60:61], v[0:1], v[0:1]
	v_pk_mul_f32 v[62:63], v[2:3], v[2:3]
	v_pk_mul_f32 v[76:77], v[4:5], v[4:5]
	v_pk_mul_f32 v[78:79], v[6:7], v[6:7]
	v_add_f32_e32 v50, v60, v61
	v_add_f32_e32 v83, v62, v63
	v_add_f32_e32 v84, v76, v77
	v_add_f32_e32 v50, v50, v83
	v_add_f32_e32 v83, v78, v79
	v_add_f32_e32 v50, v50, v84
	v_add_f32_e32 v50, v50, v83
	v_pk_mul_f32 v[64:65], v[8:9], v[8:9]
	v_pk_mul_f32 v[66:67], v[10:11], v[10:11]
	v_pk_mul_f32 v[76:77], v[12:13], v[12:13]
	v_pk_mul_f32 v[78:79], v[14:15], v[14:15]
	v_add_f32_e32 v80, v64, v65
	v_add_f32_e32 v85, v66, v67
	v_add_f32_e32 v86, v76, v77
	v_add_f32_e32 v80, v80, v85
	v_add_f32_e32 v85, v78, v79
	v_add_f32_e32 v80, v80, v86
	v_add_f32_e32 v80, v80, v85
	v_pk_mul_f32 v[68:69], v[16:17], v[16:17]
	v_pk_mul_f32 v[70:71], v[18:19], v[18:19]
	v_pk_mul_f32 v[76:77], v[20:21], v[20:21]
	v_pk_mul_f32 v[78:79], v[22:23], v[22:23]
	v_add_f32_e32 v81, v68, v69
	v_add_f32_e32 v87, v70, v71
	v_add_f32_e32 v88, v76, v77
	v_add_f32_e32 v81, v81, v87
	v_add_f32_e32 v87, v78, v79
	v_add_f32_e32 v81, v81, v88
	v_add_f32_e32 v81, v81, v87
	v_pk_mul_f32 v[72:73], v[24:25], v[24:25]
	v_pk_mul_f32 v[74:75], v[26:27], v[26:27]
	v_pk_mul_f32 v[76:77], v[28:29], v[28:29]
	v_pk_mul_f32 v[78:79], v[30:31], v[30:31]
	v_add_f32_e32 v82, v72, v73
	v_add_f32_e32 v89, v74, v75
	v_add_f32_e32 v90, v76, v77
	v_add_f32_e32 v82, v82, v89
	v_add_f32_e32 v89, v78, v79
	v_add_f32_e32 v82, v82, v90
	v_add_f32_e32 v82, v82, v89
	v_add_f32_dpp v50, v50, v50 quad_perm:[1,0,3,2] row_mask:0xf bank_mask:0xf bound_ctrl:1
	v_add_f32_dpp v80, v80, v80 quad_perm:[1,0,3,2] row_mask:0xf bank_mask:0xf bound_ctrl:1
	v_add_f32_dpp v81, v81, v81 quad_perm:[1,0,3,2] row_mask:0xf bank_mask:0xf bound_ctrl:1
	v_add_f32_dpp v82, v82, v82 quad_perm:[1,0,3,2] row_mask:0xf bank_mask:0xf bound_ctrl:1
	v_add_f32_dpp v50, v50, v50 quad_perm:[2,3,0,1] row_mask:0xf bank_mask:0xf bound_ctrl:1
	v_add_f32_dpp v80, v80, v80 quad_perm:[2,3,0,1] row_mask:0xf bank_mask:0xf bound_ctrl:1
	v_add_f32_dpp v81, v81, v81 quad_perm:[2,3,0,1] row_mask:0xf bank_mask:0xf bound_ctrl:1
	v_add_f32_dpp v82, v82, v82 quad_perm:[2,3,0,1] row_mask:0xf bank_mask:0xf bound_ctrl:1
	v_add_f32_dpp v50, v50, v50 row_half_mirror row_mask:0xf bank_mask:0xf bound_ctrl:1
	v_add_f32_dpp v80, v80, v80 row_half_mirror row_mask:0xf bank_mask:0xf bound_ctrl:1
	v_add_f32_dpp v81, v81, v81 row_half_mirror row_mask:0xf bank_mask:0xf bound_ctrl:1
	v_add_f32_dpp v82, v82, v82 row_half_mirror row_mask:0xf bank_mask:0xf bound_ctrl:1
	v_add_f32_dpp v50, v50, v50 row_mirror row_mask:0xf bank_mask:0xf bound_ctrl:1
	v_add_f32_dpp v80, v80, v80 row_mirror row_mask:0xf bank_mask:0xf bound_ctrl:1
	v_add_f32_dpp v81, v81, v81 row_mirror row_mask:0xf bank_mask:0xf bound_ctrl:1
	v_add_f32_dpp v82, v82, v82 row_mirror row_mask:0xf bank_mask:0xf bound_ctrl:1
	s_nop 0
	v_readlane_b32 s46, v50, 0
	v_readlane_b32 s50, v50, 16
	v_readlane_b32 s51, v50, 32
	v_readlane_b32 s54, v50, 48
	v_readlane_b32 s55, v80, 0
	v_readlane_b32 s60, v80, 16
	v_readlane_b32 s61, v80, 32
	v_readlane_b32 s32, v80, 48
	v_mov_b32_e32 v83, s50
	v_mov_b32_e32 v84, s54
	v_add_f32_e32 v83, s46, v83
	v_add_f32_e32 v84, s51, v84
	v_add_f32_e32 v50, v83, v84
	v_mov_b32_e32 v85, s60
	v_mov_b32_e32 v86, s32
	v_add_f32_e32 v85, s55, v85
	v_add_f32_e32 v86, s61, v86
	v_add_f32_e32 v80, v85, v86
	s_nop 0
	v_readlane_b32 s46, v81, 0
	v_readlane_b32 s50, v81, 16
	v_readlane_b32 s51, v81, 32
	v_readlane_b32 s54, v81, 48
	v_readlane_b32 s55, v82, 0
	v_readlane_b32 s60, v82, 16
	v_readlane_b32 s61, v82, 32
	v_readlane_b32 s32, v82, 48
	v_mov_b32_e32 v87, s50
	v_mov_b32_e32 v88, s54
	v_add_f32_e32 v87, s46, v87
	v_add_f32_e32 v88, s51, v88
	v_add_f32_e32 v81, v87, v88
	v_mov_b32_e32 v89, s60
	v_mov_b32_e32 v90, s32
	v_add_f32_e32 v89, s55, v89
	v_add_f32_e32 v90, s61, v90
	v_add_f32_e32 v82, v89, v90
	v_fmamk_f32 v50, v50, 0x3b000000, v92
	v_fmamk_f32 v80, v80, 0x3b000000, v92
	v_fmamk_f32 v81, v81, 0x3b000000, v92
	v_fmamk_f32 v82, v82, 0x3b000000, v92
	v_rsq_f32_e32 v50, v50
	v_rsq_f32_e32 v80, v80
	v_rsq_f32_e32 v81, v81
	v_rsq_f32_e32 v82, v82
	s_waitcnt vmcnt(0)
; __device__ __forceinline__ unsigned cvt_pk_bf16(float lo, float hi) { unsigned r; asm volatile("v_cvt_pk_bf16_f32 %0, %1, %2" : "=v"(r) : "v"(lo), "v"(hi)); return r; }
; __device__ __forceinline__ float siluf_(float x) { return x * frcp(1.0f + __expf(-x)); }
; template <int TT>
; __device__ __forceinline__ void conv_pair(const Params& p, unsigned char* lds, bool sample, int tile) {
;     ...
;             f32x4 y0 = d0 * rstd * g0 + b0, y1 = d1 * rstd * g1 + b1;
; #pragma unroll
;             for (int j = 0; j < 4; ++j) { y0[j] = siluf_(y0[j]); y1[j] = siluf_(y1[j]); }
;             u32x4 o; o.x = cvt_pk_bf16(y0[0], y0[1]); o.y = cvt_pk_bf16(y0[2], y0[3]); o.z = cvt_pk_bf16(y1[0], y1[1]); o.w = cvt_pk_bf16(y1[2], y1[3]);
;             *(u32x4*)(CAT + (size_t)(row0 + t) * DM + MIXA + 8 * lane) = o; }
	v_mul_f32_e32 v0, v0, v50
	v_mul_f32_e32 v1, v1, v50
	v_mul_f32_e32 v2, v2, v50
	v_mul_f32_e32 v3, v3, v50
	v_mul_f32_e32 v4, v4, v50
	v_mul_f32_e32 v5, v5, v50
	v_mul_f32_e32 v6, v6, v50
	v_mul_f32_e32 v7, v7, v50
	v_mul_f32_e32 v8, v8, v80
	v_mul_f32_e32 v9, v9, v80
	v_mul_f32_e32 v10, v10, v80
	v_mul_f32_e32 v11, v11, v80
	v_mul_f32_e32 v12, v12, v80
	v_mul_f32_e32 v13, v13, v80
	v_mul_f32_e32 v14, v14, v80
	v_mul_f32_e32 v15, v15, v80
	v_mul_f32_e32 v16, v16, v81
	v_mul_f32_e32 v17, v17, v81
	v_mul_f32_e32 v18, v18, v81
	v_mul_f32_e32 v19, v19, v81
	v_mul_f32_e32 v20, v20, v81
	v_mul_f32_e32 v21, v21, v81
	v_mul_f32_e32 v22, v22, v81
	v_mul_f32_e32 v23, v23, v81
	v_mul_f32_e32 v24, v24, v82
	v_mul_f32_e32 v25, v25, v82
	v_mul_f32_e32 v26, v26, v82
	v_mul_f32_e32 v27, v27, v82
	v_mul_f32_e32 v28, v28, v82
	v_mul_f32_e32 v29, v29, v82
	v_mul_f32_e32 v30, v30, v82
	v_mul_f32_e32 v31, v31, v82
	v_pk_fma_f32 v[0:1], v[32:33], v[0:1], v[40:41]
	v_pk_fma_f32 v[2:3], v[34:35], v[2:3], v[42:43]
	v_pk_fma_f32 v[4:5], v[36:37], v[4:5], v[44:45]
	v_pk_fma_f32 v[6:7], v[38:39], v[6:7], v[46:47]
	v_pk_fma_f32 v[8:9], v[32:33], v[8:9], v[40:41]
	v_pk_fma_f32 v[10:11], v[34:35], v[10:11], v[42:43]
	v_pk_fma_f32 v[12:13], v[36:37], v[12:13], v[44:45]
	v_pk_fma_f32 v[14:15], v[38:39], v[14:15], v[46:47]
	v_pk_fma_f32 v[16:17], v[32:33], v[16:17], v[40:41]
	v_pk_fma_f32 v[18:19], v[34:35], v[18:19], v[42:43]
	v_pk_fma_f32 v[20:21], v[36:37], v[20:21], v[44:45]
	v_pk_fma_f32 v[22:23], v[38:39], v[22:23], v[46:47]
	v_pk_fma_f32 v[24:25], v[32:33], v[24:25], v[40:41]
	v_pk_fma_f32 v[26:27], v[34:35], v[26:27], v[42:43]
	v_pk_fma_f32 v[28:29], v[36:37], v[28:29], v[44:45]
	v_pk_fma_f32 v[30:31], v[38:39], v[30:31], v[46:47]
	v_mul_f32_e32 v60, 0xbfb8aa3b, v0
	v_mul_f32_e32 v61, 0xbfb8aa3b, v1
	v_mul_f32_e32 v62, 0xbfb8aa3b, v2
	v_mul_f32_e32 v63, 0xbfb8aa3b, v3
	v_mul_f32_e32 v76, 0xbfb8aa3b, v4
	v_mul_f32_e32 v77, 0xbfb8aa3b, v5
	v_mul_f32_e32 v78, 0xbfb8aa3b, v6
	v_mul_f32_e32 v79, 0xbfb8aa3b, v7
	v_exp_f32_e32 v60, v60
	v_exp_f32_e32 v61, v61
	v_exp_f32_e32 v62, v62
	v_exp_f32_e32 v63, v63
	v_exp_f32_e32 v76, v76
	v_exp_f32_e32 v77, v77
	v_exp_f32_e32 v78, v78
	v_exp_f32_e32 v79, v79
	v_add_f32_e32 v60, 1.0, v60
	v_add_f32_e32 v61, 1.0, v61
	v_add_f32_e32 v62, 1.0, v62
	v_add_f32_e32 v63, 1.0, v63
	v_add_f32_e32 v76, 1.0, v76
	v_add_f32_e32 v77, 1.0, v77
	v_add_f32_e32 v78, 1.0, v78
	v_add_f32_e32 v79, 1.0, v79
	v_rcp_f32_e32 v60, v60
	v_rcp_f32_e32 v61, v61
	v_rcp_f32_e32 v62, v62
	v_rcp_f32_e32 v63, v63
	v_rcp_f32_e32 v76, v76
	v_rcp_f32_e32 v77, v77
	v_rcp_f32_e32 v78, v78
	v_rcp_f32_e32 v79, v79
	v_mul_f32_e32 v0, v0, v60
	v_mul_f32_e32 v1, v1, v61
	v_mul_f32_e32 v2, v2, v62
	v_mul_f32_e32 v3, v3, v63
	v_mul_f32_e32 v4, v4, v76
	v_mul_f32_e32 v5, v5, v77
	v_mul_f32_e32 v6, v6, v78
	v_mul_f32_e32 v7, v7, v79
	v_cvt_pk_bf16_f32 v60, v0, v1
	v_cvt_pk_bf16_f32 v61, v2, v3
	v_cvt_pk_bf16_f32 v62, v4, v5
	v_cvt_pk_bf16_f32 v63, v6, v7
	global_store_dwordx4 v93, v[60:63], s[56:57]
	v_mul_f32_e32 v64, 0xbfb8aa3b, v8
	v_mul_f32_e32 v65, 0xbfb8aa3b, v9
	v_mul_f32_e32 v66, 0xbfb8aa3b, v10
	v_mul_f32_e32 v67, 0xbfb8aa3b, v11
	v_mul_f32_e32 v76, 0xbfb8aa3b, v12
	v_mul_f32_e32 v77, 0xbfb8aa3b, v13
	v_mul_f32_e32 v78, 0xbfb8aa3b, v14
	v_mul_f32_e32 v79, 0xbfb8aa3b, v15
	v_exp_f32_e32 v64, v64
	v_exp_f32_e32 v65, v65
	v_exp_f32_e32 v66, v66
	v_exp_f32_e32 v67, v67
	v_exp_f32_e32 v76, v76
	v_exp_f32_e32 v77, v77
	v_exp_f32_e32 v78, v78
	v_exp_f32_e32 v79, v79
	v_add_f32_e32 v64, 1.0, v64
	v_add_f32_e32 v65, 1.0, v65
	v_add_f32_e32 v66, 1.0, v66
	v_add_f32_e32 v67, 1.0, v67
	v_add_f32_e32 v76, 1.0, v76
	v_add_f32_e32 v77, 1.0, v77
	v_add_f32_e32 v78, 1.0, v78
	v_add_f32_e32 v79, 1.0, v79
	v_rcp_f32_e32 v64, v64
	v_rcp_f32_e32 v65, v65
	v_rcp_f32_e32 v66, v66
	v_rcp_f32_e32 v67, v67
	v_rcp_f32_e32 v76, v76
	v_rcp_f32_e32 v77, v77
	v_rcp_f32_e32 v78, v78
	v_rcp_f32_e32 v79, v79
	v_mul_f32_e32 v8, v8, v64
	v_mul_f32_e32 v9, v9, v65
	v_mul_f32_e32 v10, v10, v66
	v_mul_f32_e32 v11, v11, v67
	v_mul_f32_e32 v12, v12, v76
	v_mul_f32_e32 v13, v13, v77
	v_mul_f32_e32 v14, v14, v78
	v_mul_f32_e32 v15, v15, v79
	v_cvt_pk_bf16_f32 v64, v8, v9
	v_cvt_pk_bf16_f32 v65, v10, v11
	v_cvt_pk_bf16_f32 v66, v12, v13
	v_cvt_pk_bf16_f32 v67, v14, v15
	global_store_dwordx4 v93, v[64:67], s[56:57] offset:2048
	v_mul_f32_e32 v68, 0xbfb8aa3b, v16
	v_mul_f32_e32 v69, 0xbfb8aa3b, v17
	v_mul_f32_e32 v70, 0xbfb8aa3b, v18
	v_mul_f32_e32 v71, 0xbfb8aa3b, v19
	v_mul_f32_e32 v76, 0xbfb8aa3b, v20
	v_mul_f32_e32 v77, 0xbfb8aa3b, v21
	v_mul_f32_e32 v78, 0xbfb8aa3b, v22
	v_mul_f32_e32 v79, 0xbfb8aa3b, v23
	v_exp_f32_e32 v68, v68
	v_exp_f32_e32 v69, v69
	v_exp_f32_e32 v70, v70
	v_exp_f32_e32 v71, v71
	v_exp_f32_e32 v76, v76
	v_exp_f32_e32 v77, v77
	v_exp_f32_e32 v78, v78
	v_exp_f32_e32 v79, v79
	v_add_f32_e32 v68, 1.0, v68
	v_add_f32_e32 v69, 1.0, v69
	v_add_f32_e32 v70, 1.0, v70
	v_add_f32_e32 v71, 1.0, v71
	v_add_f32_e32 v76, 1.0, v76
	v_add_f32_e32 v77, 1.0, v77
	v_add_f32_e32 v78, 1.0, v78
	v_add_f32_e32 v79, 1.0, v79
	v_rcp_f32_e32 v68, v68
	v_rcp_f32_e32 v69, v69
	v_rcp_f32_e32 v70, v70
	v_rcp_f32_e32 v71, v71
	v_rcp_f32_e32 v76, v76
	v_rcp_f32_e32 v77, v77
	v_rcp_f32_e32 v78, v78
	v_rcp_f32_e32 v79, v79
	v_mul_f32_e32 v16, v16, v68
	v_mul_f32_e32 v17, v17, v69
	v_mul_f32_e32 v18, v18, v70
	v_mul_f32_e32 v19, v19, v71
	v_mul_f32_e32 v20, v20, v76
	v_mul_f32_e32 v21, v21, v77
	v_mul_f32_e32 v22, v22, v78
	v_mul_f32_e32 v23, v23, v79
	v_cvt_pk_bf16_f32 v68, v16, v17
	v_cvt_pk_bf16_f32 v69, v18, v19
	v_cvt_pk_bf16_f32 v70, v20, v21
	v_cvt_pk_bf16_f32 v71, v22, v23
	s_add_u32 s56, s56, 0x1000
	s_addc_u32 s57, s57, 0
	global_store_dwordx4 v93, v[68:71], s[56:57]
	v_mul_f32_e32 v72, 0xbfb8aa3b, v24
	v_mul_f32_e32 v73, 0xbfb8aa3b, v25
	v_mul_f32_e32 v74, 0xbfb8aa3b, v26
	v_mul_f32_e32 v75, 0xbfb8aa3b, v27
	v_mul_f32_e32 v76, 0xbfb8aa3b, v28
	v_mul_f32_e32 v77, 0xbfb8aa3b, v29
	v_mul_f32_e32 v78, 0xbfb8aa3b, v30
	v_mul_f32_e32 v79, 0xbfb8aa3b, v31
	v_exp_f32_e32 v72, v72
	v_exp_f32_e32 v73, v73
	v_exp_f32_e32 v74, v74
	v_exp_f32_e32 v75, v75
	v_exp_f32_e32 v76, v76
	v_exp_f32_e32 v77, v77
	v_exp_f32_e32 v78, v78
	v_exp_f32_e32 v79, v79
	v_add_f32_e32 v72, 1.0, v72
	v_add_f32_e32 v73, 1.0, v73
	v_add_f32_e32 v74, 1.0, v74
	v_add_f32_e32 v75, 1.0, v75
	v_add_f32_e32 v76, 1.0, v76
	v_add_f32_e32 v77, 1.0, v77
	v_add_f32_e32 v78, 1.0, v78
	v_add_f32_e32 v79, 1.0, v79
	v_rcp_f32_e32 v72, v72
	v_rcp_f32_e32 v73, v73
	v_rcp_f32_e32 v74, v74
	v_rcp_f32_e32 v75, v75
	v_rcp_f32_e32 v76, v76
	v_rcp_f32_e32 v77, v77
	v_rcp_f32_e32 v78, v78
	v_rcp_f32_e32 v79, v79
	v_mul_f32_e32 v24, v24, v72
	v_mul_f32_e32 v25, v25, v73
	v_mul_f32_e32 v26, v26, v74
	v_mul_f32_e32 v27, v27, v75
	v_mul_f32_e32 v28, v28, v76
	v_mul_f32_e32 v29, v29, v77
	v_mul_f32_e32 v30, v30, v78
	v_mul_f32_e32 v31, v31, v79
	v_cvt_pk_bf16_f32 v72, v24, v25
	v_cvt_pk_bf16_f32 v73, v26, v27
	v_cvt_pk_bf16_f32 v74, v28, v29
	v_cvt_pk_bf16_f32 v75, v30, v31
	global_store_dwordx4 v93, v[72:75], s[56:57] offset:2048
	s_branch .LBB0_484
